# combo14: combo12 + GEMM K-loop load phases issue the LDS-DMA loads before the fragment ds_reads
# speedup vs baseline: 1.0066x; 1.0066x over previous
; #define PG8_STAGE(bufoff, gbase, voff) do { _Pragma("unroll") for (int _i = 0; _i < 2; ++_i) \
;         __builtin_amdgcn_global_load_lds((const unsigned*)((const char*)(gbase) + (voff)[_i]), (PG8_LAS unsigned*)(lds + (bufoff) + ldsw + _i * 8192), 16, 0, 0); } while (0)
; #define PG8_LDA(dst, b, h) do { _Pragma("unroll") for (int m = 0; m < 4; ++m) _Pragma("unroll") for (int k = 0; k < 2; ++k) dst[m][k] = *(const PG8_LAS bf16x8*)(lds + PG8_SA(b, h) + aoff + m * 2048 + k * 1024); } while (0)
; #define PG8_LDB(dst, b, h) do { _Pragma("unroll") for (int n = 0; n < 2; ++n) _Pragma("unroll") for (int k = 0; k < 2; ++k) dst[n][k] = *(const PG8_LAS bf16x8*)(lds + PG8_SB(b, h) + boff + n * 2048 + k * 1024); } while (0)
; #define PG8_MMA(ai, bj, At, Bt) do { __builtin_amdgcn_s_setprio(1); _Pragma("unroll") for (int m = 0; m < 4; ++m) _Pragma("unroll") for (int n = 0; n < 2; ++n) _Pragma("unroll") for (int k = 0; k < 2; ++k) \
;         acc[ai][bj][m][n] = __builtin_amdgcn_mfma_f32_16x16x32_bf16(Bt[n][k], At[m][k], acc[ai][bj][m][n], 0, 0, 0); __builtin_amdgcn_s_setprio(0); } while (0)
; #define PG8_WAIT_V(n) asm volatile("s_waitcnt vmcnt(" #n ")" ::: "memory")
; #define PG8_WAIT_L(n) asm volatile("s_waitcnt lgkmcnt(" #n ")" ::: "memory")
; template <class Epi, class Sched, bool ALIGN_EPI = false, bool SP2 = false>
; __device__ __forceinline__ void gemm_phase(PG8_LAS unsigned char* lds, const Gemm g, const Sched& S, const Epi& E, const int tid_arg) {
;     ...
;             const bool last = (t == nt - 2);
;             const char* a1 = cA + (size_t)(t + 1) * kstep;
;             const char* a2 = last ? nA : cA + (size_t)(t + 2) * kstep; const char* b2 = last ? nB : cB + (size_t)(t + 2) * kstep;
;             const char* a3 = a2 + kstep; const char* b3 = b2 + kstep;
;             if (last && has_next) S.a_ready(nxt);
;             if constexpr (SP2) {
;             PG8_LDB(B0, 0, 0); PG8_LDB(B1, 0, 1); PG8_SCHED; PG8_LDA(At, 0, 0); PG8_STAGE(PG8_SA(1, 1), a1 + hstep, voffA);
;             PG8_WAIT_V(8); PG8_WAIT_L(0); PG8_BAR; PG8_MMA(0, 0, At, B0); PG8_MMA(0, 1, At, B1); PG8_BAR; PG8_SCHED;
;             PG8_LDA(At, 0, 1); PG8_STAGE(PG8_SB(0, 0), b2, voffB); PG8_STAGE(PG8_SB(0, 1), b2 + hstep, voffB); PG8_STAGE(PG8_SA(0, 0), a2, voffA);
;             PG8_WAIT_V(8); PG8_WAIT_L(0); PG8_BAR; PG8_MMA(1, 0, At, B0); PG8_MMA(1, 1, At, B1); PG8_BAR; PG8_SCHED;
.LBB0_253:
	s_add_u32 s0, s8, 0xfffc0080
	s_addc_u32 s1, s9, -1
	s_cmp_eq_u32 s70, 12
	s_cselect_b32 s35, s23, s1
	s_cselect_b32 s34, s36, s0
	s_cselect_b32 s1, s21, s69
	s_cselect_b32 s0, s37, s68
	s_mov_b32 m0, s57
	s_nop 0
	global_load_lds_dwordx4 v138, s[8:9]
	s_mov_b32 m0, s58
	s_nop 0
	global_load_lds_dwordx4 v136, s[8:9]
	ds_read_b128 v[144:147], v166
	ds_read_b128 v[148:151], v167
	ds_read_b128 v[152:155], v168
	ds_read_b128 v[156:159], v169
	ds_read_b128 v[184:187], v170
	ds_read_b128 v[188:191], v171
	ds_read_b128 v[192:195], v172
	ds_read_b128 v[196:199], v173
	ds_read_b128 v[200:203], v165
	ds_read_b128 v[204:207], v165 offset:1024
	ds_read_b128 v[208:211], v165 offset:2048
	ds_read_b128 v[212:215], v165 offset:3072
	ds_read_b128 v[216:219], v165 offset:4096
	ds_read_b128 v[220:223], v165 offset:5120
	ds_read_b128 v[224:227], v165 offset:6144
	ds_read_b128 v[228:231], v165 offset:7168
	s_waitcnt vmcnt(8)
	s_waitcnt lgkmcnt(0)
	s_setprio 1
	s_barrier
	v_mfma_f32_16x16x32_bf16 v[124:127], v[144:147], v[200:203], v[124:127]
	v_mfma_f32_16x16x32_bf16 v[120:123], v[152:155], v[200:203], v[120:123]
	v_mfma_f32_16x16x32_bf16 v[108:111], v[144:147], v[208:211], v[108:111]
	v_mfma_f32_16x16x32_bf16 v[104:107], v[152:155], v[208:211], v[104:107]
	v_mfma_f32_16x16x32_bf16 v[92:95], v[144:147], v[216:219], v[92:95]
	v_mfma_f32_16x16x32_bf16 v[88:91], v[152:155], v[216:219], v[88:91]
	v_mfma_f32_16x16x32_bf16 v[76:79], v[144:147], v[224:227], v[76:79]
	v_mfma_f32_16x16x32_bf16 v[72:75], v[152:155], v[224:227], v[72:75]
	v_mfma_f32_16x16x32_bf16 v[124:127], v[148:151], v[204:207], v[124:127]
	v_mfma_f32_16x16x32_bf16 v[120:123], v[156:159], v[204:207], v[120:123]
	v_mfma_f32_16x16x32_bf16 v[108:111], v[148:151], v[212:215], v[108:111]
	v_mfma_f32_16x16x32_bf16 v[104:107], v[156:159], v[212:215], v[104:107]
	v_mfma_f32_16x16x32_bf16 v[92:95], v[148:151], v[220:223], v[92:95]
	v_mfma_f32_16x16x32_bf16 v[88:91], v[156:159], v[220:223], v[88:91]
	v_mfma_f32_16x16x32_bf16 v[76:79], v[148:151], v[228:231], v[76:79]
	v_mfma_f32_16x16x32_bf16 v[72:75], v[156:159], v[228:231], v[72:75]
	s_setprio 0
	s_setprio 1
	v_mfma_f32_16x16x32_bf16 v[116:119], v[184:187], v[200:203], v[116:119]
	v_mfma_f32_16x16x32_bf16 v[112:115], v[192:195], v[200:203], v[112:115]
	v_mfma_f32_16x16x32_bf16 v[100:103], v[184:187], v[208:211], v[100:103]
	v_mfma_f32_16x16x32_bf16 v[96:99], v[192:195], v[208:211], v[96:99]
	v_mfma_f32_16x16x32_bf16 v[84:87], v[184:187], v[216:219], v[84:87]
	v_mfma_f32_16x16x32_bf16 v[80:83], v[192:195], v[216:219], v[80:83]
	v_mfma_f32_16x16x32_bf16 v[68:71], v[184:187], v[224:227], v[68:71]
	v_mfma_f32_16x16x32_bf16 v[64:67], v[192:195], v[224:227], v[64:67]
	v_mfma_f32_16x16x32_bf16 v[116:119], v[188:191], v[204:207], v[116:119]
	v_mfma_f32_16x16x32_bf16 v[112:115], v[196:199], v[204:207], v[112:115]
	v_mfma_f32_16x16x32_bf16 v[100:103], v[188:191], v[212:215], v[100:103]
	v_mfma_f32_16x16x32_bf16 v[96:99], v[196:199], v[212:215], v[96:99]
	v_mfma_f32_16x16x32_bf16 v[84:87], v[188:191], v[220:223], v[84:87]
	v_mfma_f32_16x16x32_bf16 v[80:83], v[196:199], v[220:223], v[80:83]
	v_mfma_f32_16x16x32_bf16 v[68:71], v[188:191], v[228:231], v[68:71]
	v_mfma_f32_16x16x32_bf16 v[64:67], v[196:199], v[228:231], v[64:67]
	s_barrier
	s_setprio 0
	s_mov_b32 m0, s29
	s_add_u32 s98, s0, s14
	s_addc_u32 s99, s1, s15
	s_add_u32 s72, s0, 0x40000
	global_load_lds_dwordx4 v130, s[0:1]
	s_mov_b32 m0, s31
	s_addc_u32 s73, s1, 0
	global_load_lds_dwordx4 v134, s[0:1]
	s_mov_b32 m0, s40
	s_nop 0
	global_load_lds_dwordx4 v130, s[72:73]
	s_mov_b32 m0, s41
	s_nop 0
	global_load_lds_dwordx4 v134, s[72:73]
	s_add_u32 s100, s34, s14
	s_addc_u32 s101, s35, s15
	s_mov_b32 m0, s39
	s_nop 0
	global_load_lds_dwordx4 v128, s[34:35]
	s_mov_b32 m0, s42
	s_nop 0
	global_load_lds_dwordx4 v132, s[34:35]
	ds_read_b128 v[200:203], v165 offset:16384
	ds_read_b128 v[204:207], v165 offset:17408
	ds_read_b128 v[208:211], v165 offset:18432
	ds_read_b128 v[212:215], v165 offset:19456
	ds_read_b128 v[216:219], v165 offset:20480
	ds_read_b128 v[220:223], v165 offset:21504
	ds_read_b128 v[224:227], v165 offset:22528
	ds_read_b128 v[228:231], v165 offset:23552
	s_waitcnt vmcnt(8)
	s_waitcnt lgkmcnt(0)
	s_setprio 1
	s_barrier
	v_mfma_f32_16x16x32_bf16 v[60:63], v[144:147], v[200:203], v[60:63]
	v_mfma_f32_16x16x32_bf16 v[56:59], v[152:155], v[200:203], v[56:59]
	v_mfma_f32_16x16x32_bf16 v[44:47], v[144:147], v[208:211], v[44:47]
	v_mfma_f32_16x16x32_bf16 v[40:43], v[152:155], v[208:211], v[40:43]
	v_mfma_f32_16x16x32_bf16 v[28:31], v[144:147], v[216:219], v[28:31]
	v_mfma_f32_16x16x32_bf16 v[24:27], v[152:155], v[216:219], v[24:27]
	v_mfma_f32_16x16x32_bf16 v[12:15], v[144:147], v[224:227], v[12:15]
	v_mfma_f32_16x16x32_bf16 v[8:11], v[152:155], v[224:227], v[8:11]
	v_mfma_f32_16x16x32_bf16 v[60:63], v[148:151], v[204:207], v[60:63]
	v_mfma_f32_16x16x32_bf16 v[56:59], v[156:159], v[204:207], v[56:59]
	v_mfma_f32_16x16x32_bf16 v[44:47], v[148:151], v[212:215], v[44:47]
	v_mfma_f32_16x16x32_bf16 v[40:43], v[156:159], v[212:215], v[40:43]
	v_mfma_f32_16x16x32_bf16 v[28:31], v[148:151], v[220:223], v[28:31]
	v_mfma_f32_16x16x32_bf16 v[24:27], v[156:159], v[220:223], v[24:27]
	v_mfma_f32_16x16x32_bf16 v[12:15], v[148:151], v[228:231], v[12:15]
	v_mfma_f32_16x16x32_bf16 v[8:11], v[156:159], v[228:231], v[8:11]
	s_setprio 0
	s_setprio 1
	v_mfma_f32_16x16x32_bf16 v[52:55], v[184:187], v[200:203], v[52:55]
	v_mfma_f32_16x16x32_bf16 v[48:51], v[192:195], v[200:203], v[48:51]
	v_mfma_f32_16x16x32_bf16 v[36:39], v[184:187], v[208:211], v[36:39]
	v_mfma_f32_16x16x32_bf16 v[32:35], v[192:195], v[208:211], v[32:35]
	v_mfma_f32_16x16x32_bf16 v[20:23], v[184:187], v[216:219], v[20:23]
	v_mfma_f32_16x16x32_bf16 v[16:19], v[192:195], v[216:219], v[16:19]
	v_mfma_f32_16x16x32_bf16 v[4:7], v[184:187], v[224:227], v[4:7]
	v_mfma_f32_16x16x32_bf16 v[0:3], v[192:195], v[224:227], v[0:3]
	v_mfma_f32_16x16x32_bf16 v[52:55], v[188:191], v[204:207], v[52:55]
	v_mfma_f32_16x16x32_bf16 v[48:51], v[196:199], v[204:207], v[48:51]
	v_mfma_f32_16x16x32_bf16 v[36:39], v[188:191], v[212:215], v[36:39]
	v_mfma_f32_16x16x32_bf16 v[32:35], v[196:199], v[212:215], v[32:35]
	v_mfma_f32_16x16x32_bf16 v[20:23], v[188:191], v[220:223], v[20:23]
	v_mfma_f32_16x16x32_bf16 v[16:19], v[196:199], v[220:223], v[16:19]
	v_mfma_f32_16x16x32_bf16 v[4:7], v[188:191], v[228:231], v[4:7]
	v_mfma_f32_16x16x32_bf16 v[0:3], v[196:199], v[228:231], v[0:3]
	s_barrier
; #define PG8_STAGE(bufoff, gbase, voff) do { _Pragma("unroll") for (int _i = 0; _i < 2; ++_i) \
;         __builtin_amdgcn_global_load_lds((const unsigned*)((const char*)(gbase) + (voff)[_i]), (PG8_LAS unsigned*)(lds + (bufoff) + ldsw + _i * 8192), 16, 0, 0); } while (0)
; #define PG8_LDA(dst, b, h) do { _Pragma("unroll") for (int m = 0; m < 4; ++m) _Pragma("unroll") for (int k = 0; k < 2; ++k) dst[m][k] = *(const PG8_LAS bf16x8*)(lds + PG8_SA(b, h) + aoff + m * 2048 + k * 1024); } while (0)
; #define PG8_LDB(dst, b, h) do { _Pragma("unroll") for (int n = 0; n < 2; ++n) _Pragma("unroll") for (int k = 0; k < 2; ++k) dst[n][k] = *(const PG8_LAS bf16x8*)(lds + PG8_SB(b, h) + boff + n * 2048 + k * 1024); } while (0)
; #define PG8_MMA(ai, bj, At, Bt) do { __builtin_amdgcn_s_setprio(1); _Pragma("unroll") for (int m = 0; m < 4; ++m) _Pragma("unroll") for (int n = 0; n < 2; ++n) _Pragma("unroll") for (int k = 0; k < 2; ++k) \
;         acc[ai][bj][m][n] = __builtin_amdgcn_mfma_f32_16x16x32_bf16(Bt[n][k], At[m][k], acc[ai][bj][m][n], 0, 0, 0); __builtin_amdgcn_s_setprio(0); } while (0)
; #define PG8_WAIT_V(n) asm volatile("s_waitcnt vmcnt(" #n ")" ::: "memory")
; #define PG8_WAIT_L(n) asm volatile("s_waitcnt lgkmcnt(" #n ")" ::: "memory")
; #define PG8_BAR __builtin_amdgcn_s_barrier()
; #define PG8_SCHED __builtin_amdgcn_sched_barrier(0)
; template <class Epi, class Sched, bool ALIGN_EPI = false, bool SP2 = false>
; __device__ __forceinline__ void gemm_phase(PG8_LAS unsigned char* lds, const Gemm g, const Sched& S, const Epi& E, const int tid_arg) {
;     ...
;         for (int t = 0; t < nt; t += 2) {
;     ...
;             PG8_LDB(B0, 1, 0); PG8_LDB(B1, 1, 1); PG8_SCHED; PG8_LDA(At, 1, 0); PG8_STAGE(PG8_SA(0, 1), a2 + hstep, voffA);
;             PG8_WAIT_V(8); PG8_WAIT_L(0); PG8_BAR; PG8_MMA(0, 0, At, B0); PG8_MMA(0, 1, At, B1); PG8_BAR; PG8_SCHED;
;             PG8_LDA(At, 1, 1); PG8_STAGE(PG8_SB(1, 0), b3, voffB); PG8_STAGE(PG8_SB(1, 1), b3 + hstep, voffB); PG8_STAGE(PG8_SA(1, 0), a3, voffA);
;             PG8_WAIT_V(8); PG8_WAIT_L(0); PG8_BAR; PG8_MMA(1, 0, At, B0); PG8_MMA(1, 1, At, B1); PG8_BAR; PG8_SCHED;
	s_setprio 0
	s_add_u32 s34, s34, 0x40000
	s_addc_u32 s35, s35, 0
	s_mov_b32 m0, s43
	s_nop 0
	global_load_lds_dwordx4 v128, s[34:35]
	s_mov_b32 m0, s44
	s_nop 0
	global_load_lds_dwordx4 v132, s[34:35]
	ds_read_b128 v[144:147], v174
	ds_read_b128 v[148:151], v175
	ds_read_b128 v[152:155], v176
	ds_read_b128 v[156:159], v177
	ds_read_b128 v[184:187], v178
	ds_read_b128 v[188:191], v179
	ds_read_b128 v[192:195], v180
	ds_read_b128 v[196:199], v181
	ds_read_b128 v[200:203], v165 offset:32768
	ds_read_b128 v[204:207], v165 offset:33792
	ds_read_b128 v[208:211], v165 offset:34816
	ds_read_b128 v[212:215], v165 offset:35840
	ds_read_b128 v[216:219], v165 offset:36864
	ds_read_b128 v[220:223], v165 offset:37888
	ds_read_b128 v[224:227], v165 offset:38912
	ds_read_b128 v[228:231], v165 offset:39936
	s_waitcnt vmcnt(8)
	s_waitcnt lgkmcnt(0)
	s_setprio 1
	s_barrier
	v_mfma_f32_16x16x32_bf16 v[124:127], v[144:147], v[200:203], v[124:127]
	v_mfma_f32_16x16x32_bf16 v[120:123], v[152:155], v[200:203], v[120:123]
	v_mfma_f32_16x16x32_bf16 v[108:111], v[144:147], v[208:211], v[108:111]
	v_mfma_f32_16x16x32_bf16 v[104:107], v[152:155], v[208:211], v[104:107]
	v_mfma_f32_16x16x32_bf16 v[92:95], v[144:147], v[216:219], v[92:95]
	v_mfma_f32_16x16x32_bf16 v[88:91], v[152:155], v[216:219], v[88:91]
	v_mfma_f32_16x16x32_bf16 v[76:79], v[144:147], v[224:227], v[76:79]
	v_mfma_f32_16x16x32_bf16 v[72:75], v[152:155], v[224:227], v[72:75]
	v_mfma_f32_16x16x32_bf16 v[124:127], v[148:151], v[204:207], v[124:127]
	v_mfma_f32_16x16x32_bf16 v[120:123], v[156:159], v[204:207], v[120:123]
	v_mfma_f32_16x16x32_bf16 v[108:111], v[148:151], v[212:215], v[108:111]
	v_mfma_f32_16x16x32_bf16 v[104:107], v[156:159], v[212:215], v[104:107]
	v_mfma_f32_16x16x32_bf16 v[92:95], v[148:151], v[220:223], v[92:95]
	v_mfma_f32_16x16x32_bf16 v[88:91], v[156:159], v[220:223], v[88:91]
	v_mfma_f32_16x16x32_bf16 v[76:79], v[148:151], v[228:231], v[76:79]
	v_mfma_f32_16x16x32_bf16 v[72:75], v[156:159], v[228:231], v[72:75]
	s_setprio 0
	s_setprio 1
	v_mfma_f32_16x16x32_bf16 v[116:119], v[184:187], v[200:203], v[116:119]
	v_mfma_f32_16x16x32_bf16 v[112:115], v[192:195], v[200:203], v[112:115]
	v_mfma_f32_16x16x32_bf16 v[100:103], v[184:187], v[208:211], v[100:103]
	v_mfma_f32_16x16x32_bf16 v[96:99], v[192:195], v[208:211], v[96:99]
	v_mfma_f32_16x16x32_bf16 v[84:87], v[184:187], v[216:219], v[84:87]
	v_mfma_f32_16x16x32_bf16 v[80:83], v[192:195], v[216:219], v[80:83]
	v_mfma_f32_16x16x32_bf16 v[68:71], v[184:187], v[224:227], v[68:71]
	v_mfma_f32_16x16x32_bf16 v[64:67], v[192:195], v[224:227], v[64:67]
	v_mfma_f32_16x16x32_bf16 v[116:119], v[188:191], v[204:207], v[116:119]
	v_mfma_f32_16x16x32_bf16 v[112:115], v[196:199], v[204:207], v[112:115]
	v_mfma_f32_16x16x32_bf16 v[100:103], v[188:191], v[212:215], v[100:103]
	v_mfma_f32_16x16x32_bf16 v[96:99], v[196:199], v[212:215], v[96:99]
	v_mfma_f32_16x16x32_bf16 v[84:87], v[188:191], v[220:223], v[84:87]
	v_mfma_f32_16x16x32_bf16 v[80:83], v[196:199], v[220:223], v[80:83]
	v_mfma_f32_16x16x32_bf16 v[68:71], v[188:191], v[228:231], v[68:71]
	v_mfma_f32_16x16x32_bf16 v[64:67], v[196:199], v[228:231], v[64:67]
	s_barrier
	s_setprio 0
	s_mov_b32 m0, s47
	s_add_u32 s0, s0, 0x40080
	global_load_lds_dwordx4 v130, s[98:99]
	s_mov_b32 m0, s48
	s_addc_u32 s1, s1, 0
	global_load_lds_dwordx4 v134, s[98:99]
	s_mov_b32 m0, s51
	s_nop 0
	global_load_lds_dwordx4 v130, s[0:1]
	s_mov_b32 m0, s52
	s_nop 0
	global_load_lds_dwordx4 v134, s[0:1]
	s_mov_b32 m0, s49
	s_nop 0
	global_load_lds_dwordx4 v128, s[100:101]
	s_mov_b32 m0, s50
	s_nop 0
	global_load_lds_dwordx4 v132, s[100:101]
	ds_read_b128 v[200:203], v165 offset:49152
	ds_read_b128 v[204:207], v165 offset:50176
	ds_read_b128 v[208:211], v165 offset:51200
	ds_read_b128 v[212:215], v165 offset:52224
	ds_read_b128 v[216:219], v165 offset:53248
	ds_read_b128 v[220:223], v165 offset:54272
	ds_read_b128 v[224:227], v165 offset:55296
	ds_read_b128 v[228:231], v165 offset:56320
	s_waitcnt vmcnt(8)
	s_waitcnt lgkmcnt(0)
	s_setprio 1
	s_barrier
	v_mfma_f32_16x16x32_bf16 v[60:63], v[144:147], v[200:203], v[60:63]
	v_mfma_f32_16x16x32_bf16 v[56:59], v[152:155], v[200:203], v[56:59]
	v_mfma_f32_16x16x32_bf16 v[44:47], v[144:147], v[208:211], v[44:47]
	v_mfma_f32_16x16x32_bf16 v[40:43], v[152:155], v[208:211], v[40:43]
	v_mfma_f32_16x16x32_bf16 v[28:31], v[144:147], v[216:219], v[28:31]
	v_mfma_f32_16x16x32_bf16 v[24:27], v[152:155], v[216:219], v[24:27]
	v_mfma_f32_16x16x32_bf16 v[12:15], v[144:147], v[224:227], v[12:15]
	v_mfma_f32_16x16x32_bf16 v[8:11], v[152:155], v[224:227], v[8:11]
	v_mfma_f32_16x16x32_bf16 v[60:63], v[148:151], v[204:207], v[60:63]
	v_mfma_f32_16x16x32_bf16 v[56:59], v[156:159], v[204:207], v[56:59]
	v_mfma_f32_16x16x32_bf16 v[44:47], v[148:151], v[212:215], v[44:47]
	v_mfma_f32_16x16x32_bf16 v[40:43], v[156:159], v[212:215], v[40:43]
	v_mfma_f32_16x16x32_bf16 v[28:31], v[148:151], v[220:223], v[28:31]
	v_mfma_f32_16x16x32_bf16 v[24:27], v[156:159], v[220:223], v[24:27]
	v_mfma_f32_16x16x32_bf16 v[12:15], v[148:151], v[228:231], v[12:15]
	v_mfma_f32_16x16x32_bf16 v[8:11], v[156:159], v[228:231], v[8:11]
	s_setprio 0
	s_setprio 1
	v_mfma_f32_16x16x32_bf16 v[52:55], v[184:187], v[200:203], v[52:55]
	v_mfma_f32_16x16x32_bf16 v[48:51], v[192:195], v[200:203], v[48:51]
	v_mfma_f32_16x16x32_bf16 v[36:39], v[184:187], v[208:211], v[36:39]
	v_mfma_f32_16x16x32_bf16 v[32:35], v[192:195], v[208:211], v[32:35]
	v_mfma_f32_16x16x32_bf16 v[20:23], v[184:187], v[216:219], v[20:23]
	v_mfma_f32_16x16x32_bf16 v[16:19], v[192:195], v[216:219], v[16:19]
	v_mfma_f32_16x16x32_bf16 v[4:7], v[184:187], v[224:227], v[4:7]
	v_mfma_f32_16x16x32_bf16 v[0:3], v[192:195], v[224:227], v[0:3]
	v_mfma_f32_16x16x32_bf16 v[52:55], v[188:191], v[204:207], v[52:55]
	v_mfma_f32_16x16x32_bf16 v[48:51], v[196:199], v[204:207], v[48:51]
	v_mfma_f32_16x16x32_bf16 v[36:39], v[188:191], v[212:215], v[36:39]
	v_mfma_f32_16x16x32_bf16 v[32:35], v[196:199], v[212:215], v[32:35]
	v_mfma_f32_16x16x32_bf16 v[20:23], v[188:191], v[220:223], v[20:23]
	v_mfma_f32_16x16x32_bf16 v[16:19], v[196:199], v[220:223], v[16:19]
	v_mfma_f32_16x16x32_bf16 v[4:7], v[188:191], v[228:231], v[4:7]
	v_mfma_f32_16x16x32_bf16 v[0:3], v[196:199], v[228:231], v[0:3]
	s_barrier
	s_setprio 0
	s_add_i32 s70, s70, 2
	s_add_u32 s68, s68, 0x100
	s_addc_u32 s69, s69, 0
	s_add_u32 s8, s8, 0x100
	s_addc_u32 s9, s9, 0
	s_cmp_gt_u32 s70, 13
	s_cbranch_scc0 .LBB0_253
	s_and_b64 vcc, exec, s[16:17]
	s_cbranch_vccz .LBB0_256
	s_barrier

; #define PG8_STAGE(bufoff, gbase, voff) do { _Pragma("unroll") for (int _i = 0; _i < 2; ++_i) \
;         __builtin_amdgcn_global_load_lds((const unsigned*)((const char*)(gbase) + (voff)[_i]), (PG8_LAS unsigned*)(lds + (bufoff) + ldsw + _i * 8192), 16, 0, 0); } while (0)
; #define PG8_LDA(dst, b, h) do { _Pragma("unroll") for (int m = 0; m < 4; ++m) _Pragma("unroll") for (int k = 0; k < 2; ++k) dst[m][k] = *(const PG8_LAS bf16x8*)(lds + PG8_SA(b, h) + aoff + m * 2048 + k * 1024); } while (0)
; #define PG8_LDB(dst, b, h) do { _Pragma("unroll") for (int n = 0; n < 2; ++n) _Pragma("unroll") for (int k = 0; k < 2; ++k) dst[n][k] = *(const PG8_LAS bf16x8*)(lds + PG8_SB(b, h) + boff + n * 2048 + k * 1024); } while (0)
; #define PG8_MMA(ai, bj, At, Bt) do { __builtin_amdgcn_s_setprio(1); _Pragma("unroll") for (int m = 0; m < 4; ++m) _Pragma("unroll") for (int n = 0; n < 2; ++n) _Pragma("unroll") for (int k = 0; k < 2; ++k) \
;         acc[ai][bj][m][n] = __builtin_amdgcn_mfma_f32_16x16x32_bf16(Bt[n][k], At[m][k], acc[ai][bj][m][n], 0, 0, 0); __builtin_amdgcn_s_setprio(0); } while (0)
; #define PG8_WAIT_V(n) asm volatile("s_waitcnt vmcnt(" #n ")" ::: "memory")
; #define PG8_WAIT_L(n) asm volatile("s_waitcnt lgkmcnt(" #n ")" ::: "memory")
; template <class Epi, class Sched, bool ALIGN_EPI = false, bool SP2 = false>
; __device__ __forceinline__ void gemm_phase(PG8_LAS unsigned char* lds, const Gemm g, const Sched& S, const Epi& E, const int tid_arg) {
;     ...
;             const bool last = (t == nt - 2);
;             const char* a1 = cA + (size_t)(t + 1) * kstep;
;             const char* a2 = last ? nA : cA + (size_t)(t + 2) * kstep; const char* b2 = last ? nB : cB + (size_t)(t + 2) * kstep;
;             const char* a3 = a2 + kstep; const char* b3 = b2 + kstep;
;             if (last && has_next) S.a_ready(nxt);
;             if constexpr (SP2) {
;             PG8_LDB(B0, 0, 0); PG8_LDB(B1, 0, 1); PG8_SCHED; PG8_LDA(At, 0, 0); PG8_STAGE(PG8_SA(1, 1), a1 + hstep, voffA);
;             PG8_WAIT_V(8); PG8_WAIT_L(0); PG8_BAR; PG8_MMA(0, 0, At, B0); PG8_MMA(0, 1, At, B1); PG8_BAR; PG8_SCHED;
;             PG8_LDA(At, 0, 1); PG8_STAGE(PG8_SB(0, 0), b2, voffB); PG8_STAGE(PG8_SB(0, 1), b2 + hstep, voffB); PG8_STAGE(PG8_SA(0, 0), a2, voffA);
;             PG8_WAIT_V(8); PG8_WAIT_L(0); PG8_BAR; PG8_MMA(1, 0, At, B0); PG8_MMA(1, 1, At, B1); PG8_BAR; PG8_SCHED;
.LBB0_533:
	s_add_u32 s0, s12, 0xfffc0080
	s_addc_u32 s1, s13, -1
	s_cmp_eq_u32 s65, 12
	s_cselect_b32 s37, s11, s1
	s_cselect_b32 s36, s29, s0
	s_cselect_b32 s1, s27, s64
	s_cselect_b32 s0, s62, s63
	s_mov_b32 m0, s59
	s_nop 0
	global_load_lds_dwordx4 v146, s[12:13]
	s_mov_b32 m0, s60
	s_nop 0
	global_load_lds_dwordx4 v144, s[12:13]
	ds_read_b128 v[128:131], v165
	ds_read_b128 v[132:135], v166
	ds_read_b128 v[152:155], v167
	ds_read_b128 v[156:159], v168
	ds_read_b128 v[182:185], v169
	ds_read_b128 v[186:189], v170
	ds_read_b128 v[190:193], v171
	ds_read_b128 v[194:197], v172
	ds_read_b128 v[198:201], v164
	ds_read_b128 v[202:205], v164 offset:1024
	ds_read_b128 v[206:209], v164 offset:2048
	ds_read_b128 v[210:213], v164 offset:3072
	ds_read_b128 v[214:217], v164 offset:4096
	ds_read_b128 v[218:221], v164 offset:5120
	ds_read_b128 v[222:225], v164 offset:6144
	ds_read_b128 v[226:229], v164 offset:7168
	s_waitcnt vmcnt(8)
	s_waitcnt lgkmcnt(0)
	s_setprio 1
	s_barrier
	v_mfma_f32_16x16x32_bf16 v[124:127], v[128:131], v[198:201], v[124:127]
	v_mfma_f32_16x16x32_bf16 v[120:123], v[152:155], v[198:201], v[120:123]
	v_mfma_f32_16x16x32_bf16 v[108:111], v[128:131], v[206:209], v[108:111]
	v_mfma_f32_16x16x32_bf16 v[104:107], v[152:155], v[206:209], v[104:107]
	v_mfma_f32_16x16x32_bf16 v[92:95], v[128:131], v[214:217], v[92:95]
	v_mfma_f32_16x16x32_bf16 v[88:91], v[152:155], v[214:217], v[88:91]
	v_mfma_f32_16x16x32_bf16 v[76:79], v[128:131], v[222:225], v[76:79]
	v_mfma_f32_16x16x32_bf16 v[72:75], v[152:155], v[222:225], v[72:75]
	v_mfma_f32_16x16x32_bf16 v[124:127], v[132:135], v[202:205], v[124:127]
	v_mfma_f32_16x16x32_bf16 v[120:123], v[156:159], v[202:205], v[120:123]
	v_mfma_f32_16x16x32_bf16 v[108:111], v[132:135], v[210:213], v[108:111]
	v_mfma_f32_16x16x32_bf16 v[104:107], v[156:159], v[210:213], v[104:107]
	v_mfma_f32_16x16x32_bf16 v[92:95], v[132:135], v[218:221], v[92:95]
	v_mfma_f32_16x16x32_bf16 v[88:91], v[156:159], v[218:221], v[88:91]
	v_mfma_f32_16x16x32_bf16 v[76:79], v[132:135], v[226:229], v[76:79]
	v_mfma_f32_16x16x32_bf16 v[72:75], v[156:159], v[226:229], v[72:75]
	s_setprio 0
	s_setprio 1
	v_mfma_f32_16x16x32_bf16 v[116:119], v[182:185], v[198:201], v[116:119]
	v_mfma_f32_16x16x32_bf16 v[112:115], v[190:193], v[198:201], v[112:115]
	v_mfma_f32_16x16x32_bf16 v[100:103], v[182:185], v[206:209], v[100:103]
	v_mfma_f32_16x16x32_bf16 v[96:99], v[190:193], v[206:209], v[96:99]
	v_mfma_f32_16x16x32_bf16 v[84:87], v[182:185], v[214:217], v[84:87]
	v_mfma_f32_16x16x32_bf16 v[80:83], v[190:193], v[214:217], v[80:83]
	v_mfma_f32_16x16x32_bf16 v[68:71], v[182:185], v[222:225], v[68:71]
	v_mfma_f32_16x16x32_bf16 v[64:67], v[190:193], v[222:225], v[64:67]
	v_mfma_f32_16x16x32_bf16 v[116:119], v[186:189], v[202:205], v[116:119]
	v_mfma_f32_16x16x32_bf16 v[112:115], v[194:197], v[202:205], v[112:115]
	v_mfma_f32_16x16x32_bf16 v[100:103], v[186:189], v[210:213], v[100:103]
	v_mfma_f32_16x16x32_bf16 v[96:99], v[194:197], v[210:213], v[96:99]
	v_mfma_f32_16x16x32_bf16 v[84:87], v[186:189], v[218:221], v[84:87]
	v_mfma_f32_16x16x32_bf16 v[80:83], v[194:197], v[218:221], v[80:83]
	v_mfma_f32_16x16x32_bf16 v[68:71], v[186:189], v[226:229], v[68:71]
	v_mfma_f32_16x16x32_bf16 v[64:67], v[194:197], v[226:229], v[64:67]
	s_barrier
	s_setprio 0
	s_mov_b32 m0, s5
	s_add_u32 s98, s0, s20
	s_addc_u32 s99, s1, s21
	s_add_u32 s66, s0, 0x40000
	global_load_lds_dwordx4 v138, s[0:1]
	s_mov_b32 m0, s40
	s_addc_u32 s67, s1, 0
	global_load_lds_dwordx4 v142, s[0:1]
	s_mov_b32 m0, s41
	s_nop 0
	global_load_lds_dwordx4 v138, s[66:67]
	s_mov_b32 m0, s42
	s_nop 0
	global_load_lds_dwordx4 v142, s[66:67]
	s_add_u32 s100, s36, s20
	s_addc_u32 s101, s37, s21
	s_mov_b32 m0, s39
	s_nop 0
	global_load_lds_dwordx4 v136, s[36:37]
	s_mov_b32 m0, s43
	s_nop 0
	global_load_lds_dwordx4 v140, s[36:37]
	ds_read_b128 v[198:201], v164 offset:16384
	ds_read_b128 v[202:205], v164 offset:17408
	ds_read_b128 v[206:209], v164 offset:18432
	ds_read_b128 v[210:213], v164 offset:19456
	ds_read_b128 v[214:217], v164 offset:20480
	ds_read_b128 v[218:221], v164 offset:21504
	ds_read_b128 v[222:225], v164 offset:22528
	ds_read_b128 v[226:229], v164 offset:23552
	s_waitcnt vmcnt(8)
	s_waitcnt lgkmcnt(0)
	s_setprio 1
	s_barrier
	v_mfma_f32_16x16x32_bf16 v[60:63], v[128:131], v[198:201], v[60:63]
	v_mfma_f32_16x16x32_bf16 v[56:59], v[152:155], v[198:201], v[56:59]
	v_mfma_f32_16x16x32_bf16 v[44:47], v[128:131], v[206:209], v[44:47]
	v_mfma_f32_16x16x32_bf16 v[40:43], v[152:155], v[206:209], v[40:43]
	v_mfma_f32_16x16x32_bf16 v[28:31], v[128:131], v[214:217], v[28:31]
	v_mfma_f32_16x16x32_bf16 v[24:27], v[152:155], v[214:217], v[24:27]
	v_mfma_f32_16x16x32_bf16 v[12:15], v[128:131], v[222:225], v[12:15]
	v_mfma_f32_16x16x32_bf16 v[8:11], v[152:155], v[222:225], v[8:11]
	v_mfma_f32_16x16x32_bf16 v[60:63], v[132:135], v[202:205], v[60:63]
	v_mfma_f32_16x16x32_bf16 v[56:59], v[156:159], v[202:205], v[56:59]
	v_mfma_f32_16x16x32_bf16 v[44:47], v[132:135], v[210:213], v[44:47]
	v_mfma_f32_16x16x32_bf16 v[40:43], v[156:159], v[210:213], v[40:43]
	v_mfma_f32_16x16x32_bf16 v[28:31], v[132:135], v[218:221], v[28:31]
	v_mfma_f32_16x16x32_bf16 v[24:27], v[156:159], v[218:221], v[24:27]
	v_mfma_f32_16x16x32_bf16 v[12:15], v[132:135], v[226:229], v[12:15]
	v_mfma_f32_16x16x32_bf16 v[8:11], v[156:159], v[226:229], v[8:11]
	s_setprio 0
	s_setprio 1
	v_mfma_f32_16x16x32_bf16 v[52:55], v[182:185], v[198:201], v[52:55]
	v_mfma_f32_16x16x32_bf16 v[48:51], v[190:193], v[198:201], v[48:51]
	v_mfma_f32_16x16x32_bf16 v[36:39], v[182:185], v[206:209], v[36:39]
	v_mfma_f32_16x16x32_bf16 v[32:35], v[190:193], v[206:209], v[32:35]
	v_mfma_f32_16x16x32_bf16 v[20:23], v[182:185], v[214:217], v[20:23]
	v_mfma_f32_16x16x32_bf16 v[16:19], v[190:193], v[214:217], v[16:19]
	v_mfma_f32_16x16x32_bf16 v[4:7], v[182:185], v[222:225], v[4:7]
	v_mfma_f32_16x16x32_bf16 v[0:3], v[190:193], v[222:225], v[0:3]
	v_mfma_f32_16x16x32_bf16 v[52:55], v[186:189], v[202:205], v[52:55]
	v_mfma_f32_16x16x32_bf16 v[48:51], v[194:197], v[202:205], v[48:51]
	v_mfma_f32_16x16x32_bf16 v[36:39], v[186:189], v[210:213], v[36:39]
	v_mfma_f32_16x16x32_bf16 v[32:35], v[194:197], v[210:213], v[32:35]
	v_mfma_f32_16x16x32_bf16 v[20:23], v[186:189], v[218:221], v[20:23]
	v_mfma_f32_16x16x32_bf16 v[16:19], v[194:197], v[218:221], v[16:19]
	v_mfma_f32_16x16x32_bf16 v[4:7], v[186:189], v[226:229], v[4:7]
	v_mfma_f32_16x16x32_bf16 v[0:3], v[194:197], v[226:229], v[0:3]
	s_barrier
; #define PG8_STAGE(bufoff, gbase, voff) do { _Pragma("unroll") for (int _i = 0; _i < 2; ++_i) \
;         __builtin_amdgcn_global_load_lds((const unsigned*)((const char*)(gbase) + (voff)[_i]), (PG8_LAS unsigned*)(lds + (bufoff) + ldsw + _i * 8192), 16, 0, 0); } while (0)
; #define PG8_LDA(dst, b, h) do { _Pragma("unroll") for (int m = 0; m < 4; ++m) _Pragma("unroll") for (int k = 0; k < 2; ++k) dst[m][k] = *(const PG8_LAS bf16x8*)(lds + PG8_SA(b, h) + aoff + m * 2048 + k * 1024); } while (0)
; #define PG8_LDB(dst, b, h) do { _Pragma("unroll") for (int n = 0; n < 2; ++n) _Pragma("unroll") for (int k = 0; k < 2; ++k) dst[n][k] = *(const PG8_LAS bf16x8*)(lds + PG8_SB(b, h) + boff + n * 2048 + k * 1024); } while (0)
; #define PG8_MMA(ai, bj, At, Bt) do { __builtin_amdgcn_s_setprio(1); _Pragma("unroll") for (int m = 0; m < 4; ++m) _Pragma("unroll") for (int n = 0; n < 2; ++n) _Pragma("unroll") for (int k = 0; k < 2; ++k) \
;         acc[ai][bj][m][n] = __builtin_amdgcn_mfma_f32_16x16x32_bf16(Bt[n][k], At[m][k], acc[ai][bj][m][n], 0, 0, 0); __builtin_amdgcn_s_setprio(0); } while (0)
; #define PG8_WAIT_V(n) asm volatile("s_waitcnt vmcnt(" #n ")" ::: "memory")
; #define PG8_WAIT_L(n) asm volatile("s_waitcnt lgkmcnt(" #n ")" ::: "memory")
; #define PG8_BAR __builtin_amdgcn_s_barrier()
; #define PG8_SCHED __builtin_amdgcn_sched_barrier(0)
; template <class Epi, class Sched, bool ALIGN_EPI = false, bool SP2 = false>
; __device__ __forceinline__ void gemm_phase(PG8_LAS unsigned char* lds, const Gemm g, const Sched& S, const Epi& E, const int tid_arg) {
;     ...
;         for (int t = 0; t < nt; t += 2) {
;     ...
;             PG8_LDB(B0, 1, 0); PG8_LDB(B1, 1, 1); PG8_SCHED; PG8_LDA(At, 1, 0); PG8_STAGE(PG8_SA(0, 1), a2 + hstep, voffA);
;             PG8_WAIT_V(8); PG8_WAIT_L(0); PG8_BAR; PG8_MMA(0, 0, At, B0); PG8_MMA(0, 1, At, B1); PG8_BAR; PG8_SCHED;
;             PG8_LDA(At, 1, 1); PG8_STAGE(PG8_SB(1, 0), b3, voffB); PG8_STAGE(PG8_SB(1, 1), b3 + hstep, voffB); PG8_STAGE(PG8_SA(1, 0), a3, voffA);
;             PG8_WAIT_V(8); PG8_WAIT_L(0); PG8_BAR; PG8_MMA(1, 0, At, B0); PG8_MMA(1, 1, At, B1); PG8_BAR; PG8_SCHED;
	s_setprio 0
	s_add_u32 s36, s36, 0x40000
	s_addc_u32 s37, s37, 0
	s_mov_b32 m0, s44
	s_nop 0
	global_load_lds_dwordx4 v136, s[36:37]
	s_mov_b32 m0, s45
	s_nop 0
	global_load_lds_dwordx4 v140, s[36:37]
	ds_read_b128 v[128:131], v173
	ds_read_b128 v[132:135], v174
	ds_read_b128 v[152:155], v175
	ds_read_b128 v[156:159], v176
	ds_read_b128 v[182:185], v177
	ds_read_b128 v[186:189], v178
	ds_read_b128 v[190:193], v179
	ds_read_b128 v[194:197], v180
	ds_read_b128 v[198:201], v164 offset:32768
	ds_read_b128 v[202:205], v164 offset:33792
	ds_read_b128 v[206:209], v164 offset:34816
	ds_read_b128 v[210:213], v164 offset:35840
	ds_read_b128 v[214:217], v164 offset:36864
	ds_read_b128 v[218:221], v164 offset:37888
	ds_read_b128 v[222:225], v164 offset:38912
	ds_read_b128 v[226:229], v164 offset:39936
	s_waitcnt vmcnt(8)
	s_waitcnt lgkmcnt(0)
	s_setprio 1
	s_barrier
	v_mfma_f32_16x16x32_bf16 v[124:127], v[128:131], v[198:201], v[124:127]
	v_mfma_f32_16x16x32_bf16 v[120:123], v[152:155], v[198:201], v[120:123]
	v_mfma_f32_16x16x32_bf16 v[108:111], v[128:131], v[206:209], v[108:111]
	v_mfma_f32_16x16x32_bf16 v[104:107], v[152:155], v[206:209], v[104:107]
	v_mfma_f32_16x16x32_bf16 v[92:95], v[128:131], v[214:217], v[92:95]
	v_mfma_f32_16x16x32_bf16 v[88:91], v[152:155], v[214:217], v[88:91]
	v_mfma_f32_16x16x32_bf16 v[76:79], v[128:131], v[222:225], v[76:79]
	v_mfma_f32_16x16x32_bf16 v[72:75], v[152:155], v[222:225], v[72:75]
	v_mfma_f32_16x16x32_bf16 v[124:127], v[132:135], v[202:205], v[124:127]
	v_mfma_f32_16x16x32_bf16 v[120:123], v[156:159], v[202:205], v[120:123]
	v_mfma_f32_16x16x32_bf16 v[108:111], v[132:135], v[210:213], v[108:111]
	v_mfma_f32_16x16x32_bf16 v[104:107], v[156:159], v[210:213], v[104:107]
	v_mfma_f32_16x16x32_bf16 v[92:95], v[132:135], v[218:221], v[92:95]
	v_mfma_f32_16x16x32_bf16 v[88:91], v[156:159], v[218:221], v[88:91]
	v_mfma_f32_16x16x32_bf16 v[76:79], v[132:135], v[226:229], v[76:79]
	v_mfma_f32_16x16x32_bf16 v[72:75], v[156:159], v[226:229], v[72:75]
	s_setprio 0
	s_setprio 1
	v_mfma_f32_16x16x32_bf16 v[116:119], v[182:185], v[198:201], v[116:119]
	v_mfma_f32_16x16x32_bf16 v[112:115], v[190:193], v[198:201], v[112:115]
	v_mfma_f32_16x16x32_bf16 v[100:103], v[182:185], v[206:209], v[100:103]
	v_mfma_f32_16x16x32_bf16 v[96:99], v[190:193], v[206:209], v[96:99]
	v_mfma_f32_16x16x32_bf16 v[84:87], v[182:185], v[214:217], v[84:87]
	v_mfma_f32_16x16x32_bf16 v[80:83], v[190:193], v[214:217], v[80:83]
	v_mfma_f32_16x16x32_bf16 v[68:71], v[182:185], v[222:225], v[68:71]
	v_mfma_f32_16x16x32_bf16 v[64:67], v[190:193], v[222:225], v[64:67]
	v_mfma_f32_16x16x32_bf16 v[116:119], v[186:189], v[202:205], v[116:119]
	v_mfma_f32_16x16x32_bf16 v[112:115], v[194:197], v[202:205], v[112:115]
	v_mfma_f32_16x16x32_bf16 v[100:103], v[186:189], v[210:213], v[100:103]
	v_mfma_f32_16x16x32_bf16 v[96:99], v[194:197], v[210:213], v[96:99]
	v_mfma_f32_16x16x32_bf16 v[84:87], v[186:189], v[218:221], v[84:87]
	v_mfma_f32_16x16x32_bf16 v[80:83], v[194:197], v[218:221], v[80:83]
	v_mfma_f32_16x16x32_bf16 v[68:71], v[186:189], v[226:229], v[68:71]
	v_mfma_f32_16x16x32_bf16 v[64:67], v[194:197], v[226:229], v[64:67]
	s_barrier
	s_setprio 0
	s_mov_b32 m0, s49
	s_add_u32 s0, s0, 0x40080
	global_load_lds_dwordx4 v138, s[98:99]
	s_mov_b32 m0, s50
	s_addc_u32 s1, s1, 0
	global_load_lds_dwordx4 v142, s[98:99]
	s_mov_b32 m0, s53
	s_nop 0
	global_load_lds_dwordx4 v138, s[0:1]
	s_mov_b32 m0, s54
	s_nop 0
	global_load_lds_dwordx4 v142, s[0:1]
	s_mov_b32 m0, s51
	s_nop 0
	global_load_lds_dwordx4 v136, s[100:101]
	s_mov_b32 m0, s52
	s_nop 0
	global_load_lds_dwordx4 v140, s[100:101]
	ds_read_b128 v[198:201], v164 offset:49152
	ds_read_b128 v[202:205], v164 offset:50176
	ds_read_b128 v[206:209], v164 offset:51200
	ds_read_b128 v[210:213], v164 offset:52224
	ds_read_b128 v[214:217], v164 offset:53248
	ds_read_b128 v[218:221], v164 offset:54272
	ds_read_b128 v[222:225], v164 offset:55296
	ds_read_b128 v[226:229], v164 offset:56320
	s_waitcnt vmcnt(8)
	s_waitcnt lgkmcnt(0)
	s_setprio 1
	s_barrier
	v_mfma_f32_16x16x32_bf16 v[60:63], v[128:131], v[198:201], v[60:63]
	v_mfma_f32_16x16x32_bf16 v[56:59], v[152:155], v[198:201], v[56:59]
	v_mfma_f32_16x16x32_bf16 v[44:47], v[128:131], v[206:209], v[44:47]
	v_mfma_f32_16x16x32_bf16 v[40:43], v[152:155], v[206:209], v[40:43]
	v_mfma_f32_16x16x32_bf16 v[28:31], v[128:131], v[214:217], v[28:31]
	v_mfma_f32_16x16x32_bf16 v[24:27], v[152:155], v[214:217], v[24:27]
	v_mfma_f32_16x16x32_bf16 v[12:15], v[128:131], v[222:225], v[12:15]
	v_mfma_f32_16x16x32_bf16 v[8:11], v[152:155], v[222:225], v[8:11]
	v_mfma_f32_16x16x32_bf16 v[60:63], v[132:135], v[202:205], v[60:63]
	v_mfma_f32_16x16x32_bf16 v[56:59], v[156:159], v[202:205], v[56:59]
	v_mfma_f32_16x16x32_bf16 v[44:47], v[132:135], v[210:213], v[44:47]
	v_mfma_f32_16x16x32_bf16 v[40:43], v[156:159], v[210:213], v[40:43]
	v_mfma_f32_16x16x32_bf16 v[28:31], v[132:135], v[218:221], v[28:31]
	v_mfma_f32_16x16x32_bf16 v[24:27], v[156:159], v[218:221], v[24:27]
	v_mfma_f32_16x16x32_bf16 v[12:15], v[132:135], v[226:229], v[12:15]
	v_mfma_f32_16x16x32_bf16 v[8:11], v[156:159], v[226:229], v[8:11]
	s_setprio 0
	s_setprio 1
	v_mfma_f32_16x16x32_bf16 v[52:55], v[182:185], v[198:201], v[52:55]
	v_mfma_f32_16x16x32_bf16 v[48:51], v[190:193], v[198:201], v[48:51]
	v_mfma_f32_16x16x32_bf16 v[36:39], v[182:185], v[206:209], v[36:39]
	v_mfma_f32_16x16x32_bf16 v[32:35], v[190:193], v[206:209], v[32:35]
	v_mfma_f32_16x16x32_bf16 v[20:23], v[182:185], v[214:217], v[20:23]
	v_mfma_f32_16x16x32_bf16 v[16:19], v[190:193], v[214:217], v[16:19]
	v_mfma_f32_16x16x32_bf16 v[4:7], v[182:185], v[222:225], v[4:7]
	v_mfma_f32_16x16x32_bf16 v[0:3], v[190:193], v[222:225], v[0:3]
	v_mfma_f32_16x16x32_bf16 v[52:55], v[186:189], v[202:205], v[52:55]
	v_mfma_f32_16x16x32_bf16 v[48:51], v[194:197], v[202:205], v[48:51]
	v_mfma_f32_16x16x32_bf16 v[36:39], v[186:189], v[210:213], v[36:39]
	v_mfma_f32_16x16x32_bf16 v[32:35], v[194:197], v[210:213], v[32:35]
	v_mfma_f32_16x16x32_bf16 v[20:23], v[186:189], v[218:221], v[20:23]
	v_mfma_f32_16x16x32_bf16 v[16:19], v[194:197], v[218:221], v[16:19]
	v_mfma_f32_16x16x32_bf16 v[4:7], v[186:189], v[226:229], v[4:7]
	v_mfma_f32_16x16x32_bf16 v[0:3], v[194:197], v[226:229], v[0:3]
	s_barrier
	s_setprio 0
	s_add_i32 s65, s65, 2
	s_add_u32 s63, s63, 0x100
	s_addc_u32 s64, s64, 0
	s_add_u32 s12, s12, 0x100
	s_addc_u32 s13, s13, 0
	s_cmp_gt_u32 s65, 13
	s_cbranch_scc0 .LBB0_533
	s_and_b64 vcc, exec, s[22:23]
	s_cbranch_vccz .LBB0_536
	s_barrier

; #define PG8_STAGE(bufoff, gbase, voff) do { _Pragma("unroll") for (int _i = 0; _i < 2; ++_i) \
;         __builtin_amdgcn_global_load_lds((const unsigned*)((const char*)(gbase) + (voff)[_i]), (PG8_LAS unsigned*)(lds + (bufoff) + ldsw + _i * 8192), 16, 0, 0); } while (0)
; #define PG8_LDA(dst, b, h) do { _Pragma("unroll") for (int m = 0; m < 4; ++m) _Pragma("unroll") for (int k = 0; k < 2; ++k) dst[m][k] = *(const PG8_LAS bf16x8*)(lds + PG8_SA(b, h) + aoff + m * 2048 + k * 1024); } while (0)
; #define PG8_LDB(dst, b, h) do { _Pragma("unroll") for (int n = 0; n < 2; ++n) _Pragma("unroll") for (int k = 0; k < 2; ++k) dst[n][k] = *(const PG8_LAS bf16x8*)(lds + PG8_SB(b, h) + boff + n * 2048 + k * 1024); } while (0)
; #define PG8_MMA(ai, bj, At, Bt) do { __builtin_amdgcn_s_setprio(1); _Pragma("unroll") for (int m = 0; m < 4; ++m) _Pragma("unroll") for (int n = 0; n < 2; ++n) _Pragma("unroll") for (int k = 0; k < 2; ++k) \
;         acc[ai][bj][m][n] = __builtin_amdgcn_mfma_f32_16x16x32_bf16(Bt[n][k], At[m][k], acc[ai][bj][m][n], 0, 0, 0); __builtin_amdgcn_s_setprio(0); } while (0)
; #define PG8_WAIT_V(n) asm volatile("s_waitcnt vmcnt(" #n ")" ::: "memory")
; #define PG8_WAIT_L(n) asm volatile("s_waitcnt lgkmcnt(" #n ")" ::: "memory")
; template <class Epi, class Sched, bool ALIGN_EPI = false, bool SP2 = false>
; __device__ __forceinline__ void gemm_phase(PG8_LAS unsigned char* lds, const Gemm g, const Sched& S, const Epi& E, const int tid_arg) {
;     ...
;             const bool last = (t == nt - 2);
;             const char* a1 = cA + (size_t)(t + 1) * kstep;
;             const char* a2 = last ? nA : cA + (size_t)(t + 2) * kstep; const char* b2 = last ? nB : cB + (size_t)(t + 2) * kstep;
;             const char* a3 = a2 + kstep; const char* b3 = b2 + kstep;
;             if (last && has_next) S.a_ready(nxt);
;             if constexpr (SP2) {
;             PG8_LDB(B0, 0, 0); PG8_LDB(B1, 0, 1); PG8_SCHED; PG8_LDA(At, 0, 0); PG8_STAGE(PG8_SA(1, 1), a1 + hstep, voffA);
;             PG8_WAIT_V(8); PG8_WAIT_L(0); PG8_BAR; PG8_MMA(0, 0, At, B0); PG8_MMA(0, 1, At, B1); PG8_BAR; PG8_SCHED;
;             PG8_LDA(At, 0, 1); PG8_STAGE(PG8_SB(0, 0), b2, voffB); PG8_STAGE(PG8_SB(0, 1), b2 + hstep, voffB); PG8_STAGE(PG8_SA(0, 0), a2, voffA);
;             PG8_WAIT_V(8); PG8_WAIT_L(0); PG8_BAR; PG8_MMA(1, 0, At, B0); PG8_MMA(1, 1, At, B1); PG8_BAR; PG8_SCHED;
.LBB0_685:
	s_add_u32 s10, s4, 0x100
	s_addc_u32 s11, s5, 0
	s_cmp_eq_u32 s79, 12
	s_cselect_b32 s15, s17, s11
	s_cselect_b32 s14, s37, s10
	s_cselect_b32 s1, s35, s78
	s_cselect_b32 s0, s46, s47
	s_mov_b32 m0, s72
	s_nop 0
	global_load_lds_dwordx4 v196, s[4:5]
	s_mov_b32 m0, s73
	s_nop 0
	global_load_lds_dwordx4 v194, s[4:5]
	ds_read_b128 v[72:75], v207
	ds_read_b128 v[100:103], v208
	ds_read_b128 v[136:139], v209
	ds_read_b128 v[140:143], v210
	ds_read_b128 v[144:147], v211
	ds_read_b128 v[148:151], v212
	ds_read_b128 v[152:155], v213
	ds_read_b128 v[156:159], v214
	ds_read_b128 v[160:163], v206
	ds_read_b128 v[164:167], v206 offset:1024
	ds_read_b128 v[168:171], v206 offset:2048
	ds_read_b128 v[172:175], v206 offset:3072
	ds_read_b128 v[176:179], v206 offset:4096
	ds_read_b128 v[180:183], v206 offset:5120
	ds_read_b128 v[226:229], v206 offset:6144
	ds_read_b128 v[230:233], v206 offset:7168
	s_waitcnt vmcnt(8)
	s_waitcnt lgkmcnt(0)
	s_setprio 1
	s_barrier
	v_mfma_f32_16x16x32_bf16 v[132:135], v[72:75], v[160:163], v[132:135]
	v_mfma_f32_16x16x32_bf16 v[60:63], v[136:139], v[160:163], v[60:63]
	v_mfma_f32_16x16x32_bf16 v[124:127], v[72:75], v[168:171], v[124:127]
	v_mfma_f32_16x16x32_bf16 v[52:55], v[136:139], v[168:171], v[52:55]
	v_mfma_f32_16x16x32_bf16 v[116:119], v[72:75], v[176:179], v[116:119]
	v_mfma_f32_16x16x32_bf16 v[44:47], v[136:139], v[176:179], v[44:47]
	v_mfma_f32_16x16x32_bf16 v[108:111], v[72:75], v[226:229], v[108:111]
	v_mfma_f32_16x16x32_bf16 v[36:39], v[136:139], v[226:229], v[36:39]
	v_mfma_f32_16x16x32_bf16 v[132:135], v[100:103], v[164:167], v[132:135]
	v_mfma_f32_16x16x32_bf16 v[60:63], v[140:143], v[164:167], v[60:63]
	v_mfma_f32_16x16x32_bf16 v[124:127], v[100:103], v[172:175], v[124:127]
	v_mfma_f32_16x16x32_bf16 v[52:55], v[140:143], v[172:175], v[52:55]
	v_mfma_f32_16x16x32_bf16 v[116:119], v[100:103], v[180:183], v[116:119]
	v_mfma_f32_16x16x32_bf16 v[44:47], v[140:143], v[180:183], v[44:47]
	v_mfma_f32_16x16x32_bf16 v[108:111], v[100:103], v[230:233], v[108:111]
	v_mfma_f32_16x16x32_bf16 v[36:39], v[140:143], v[230:233], v[36:39]
	s_setprio 0
	s_setprio 1
	v_mfma_f32_16x16x32_bf16 v[128:131], v[144:147], v[160:163], v[128:131]
	v_mfma_f32_16x16x32_bf16 v[56:59], v[152:155], v[160:163], v[56:59]
	v_mfma_f32_16x16x32_bf16 v[120:123], v[144:147], v[168:171], v[120:123]
	v_mfma_f32_16x16x32_bf16 v[48:51], v[152:155], v[168:171], v[48:51]
	v_mfma_f32_16x16x32_bf16 v[112:115], v[144:147], v[176:179], v[112:115]
	v_mfma_f32_16x16x32_bf16 v[40:43], v[152:155], v[176:179], v[40:43]
	v_mfma_f32_16x16x32_bf16 v[104:107], v[144:147], v[226:229], v[104:107]
	v_mfma_f32_16x16x32_bf16 v[32:35], v[152:155], v[226:229], v[32:35]
	v_mfma_f32_16x16x32_bf16 v[128:131], v[148:151], v[164:167], v[128:131]
	v_mfma_f32_16x16x32_bf16 v[56:59], v[156:159], v[164:167], v[56:59]
	v_mfma_f32_16x16x32_bf16 v[120:123], v[148:151], v[172:175], v[120:123]
	v_mfma_f32_16x16x32_bf16 v[48:51], v[156:159], v[172:175], v[48:51]
	v_mfma_f32_16x16x32_bf16 v[112:115], v[148:151], v[180:183], v[112:115]
	v_mfma_f32_16x16x32_bf16 v[40:43], v[156:159], v[180:183], v[40:43]
	v_mfma_f32_16x16x32_bf16 v[104:107], v[148:151], v[230:233], v[104:107]
	v_mfma_f32_16x16x32_bf16 v[32:35], v[156:159], v[230:233], v[32:35]
	s_barrier
	s_setprio 0
	s_mov_b32 m0, s43
	s_add_u32 s98, s0, s24
	s_addc_u32 s99, s1, s25
	s_add_u32 s4, s0, 0x40000
	global_load_lds_dwordx4 v188, s[0:1]
	s_mov_b32 m0, s45
	s_addc_u32 s5, s1, 0
	global_load_lds_dwordx4 v192, s[0:1]
	s_mov_b32 m0, s50
	s_nop 0
	global_load_lds_dwordx4 v188, s[4:5]
	s_mov_b32 m0, s51
	s_nop 0
	global_load_lds_dwordx4 v192, s[4:5]
	s_add_u32 s100, s14, s24
	s_addc_u32 s101, s15, s25
	s_mov_b32 m0, s49
	s_nop 0
	global_load_lds_dwordx4 v186, s[14:15]
	s_mov_b32 m0, s52
	s_nop 0
	global_load_lds_dwordx4 v190, s[14:15]
	ds_read_b128 v[160:163], v206 offset:16384
	ds_read_b128 v[164:167], v206 offset:17408
	ds_read_b128 v[168:171], v206 offset:18432
	ds_read_b128 v[172:175], v206 offset:19456
	ds_read_b128 v[176:179], v206 offset:20480
	ds_read_b128 v[180:183], v206 offset:21504
	ds_read_b128 v[226:229], v206 offset:22528
	ds_read_b128 v[230:233], v206 offset:23552
	s_waitcnt vmcnt(8)
	s_waitcnt lgkmcnt(0)
	s_setprio 1
	s_barrier
	v_mfma_f32_16x16x32_bf16 v[96:99], v[72:75], v[160:163], v[96:99]
	v_mfma_f32_16x16x32_bf16 v[28:31], v[136:139], v[160:163], v[28:31]
	v_mfma_f32_16x16x32_bf16 v[88:91], v[72:75], v[168:171], v[88:91]
	v_mfma_f32_16x16x32_bf16 v[20:23], v[136:139], v[168:171], v[20:23]
	v_mfma_f32_16x16x32_bf16 v[80:83], v[72:75], v[176:179], v[80:83]
	v_mfma_f32_16x16x32_bf16 v[12:15], v[136:139], v[176:179], v[12:15]
	v_mfma_f32_16x16x32_bf16 v[68:71], v[72:75], v[226:229], v[68:71]
	v_mfma_f32_16x16x32_bf16 v[4:7], v[136:139], v[226:229], v[4:7]
	v_mfma_f32_16x16x32_bf16 v[96:99], v[100:103], v[164:167], v[96:99]
	v_mfma_f32_16x16x32_bf16 v[28:31], v[140:143], v[164:167], v[28:31]
	v_mfma_f32_16x16x32_bf16 v[88:91], v[100:103], v[172:175], v[88:91]
	v_mfma_f32_16x16x32_bf16 v[20:23], v[140:143], v[172:175], v[20:23]
	v_mfma_f32_16x16x32_bf16 v[80:83], v[100:103], v[180:183], v[80:83]
	v_mfma_f32_16x16x32_bf16 v[12:15], v[140:143], v[180:183], v[12:15]
	v_mfma_f32_16x16x32_bf16 v[68:71], v[100:103], v[230:233], v[68:71]
	v_mfma_f32_16x16x32_bf16 v[4:7], v[140:143], v[230:233], v[4:7]
	s_setprio 0
	s_setprio 1
	v_mfma_f32_16x16x32_bf16 v[24:27], v[152:155], v[160:163], v[24:27]
	v_mfma_f32_16x16x32_bf16 v[84:87], v[144:147], v[168:171], v[84:87]
	v_mfma_f32_16x16x32_bf16 v[16:19], v[152:155], v[168:171], v[16:19]
	v_mfma_f32_16x16x32_bf16 v[76:79], v[144:147], v[176:179], v[76:79]
	v_mfma_f32_16x16x32_bf16 v[8:11], v[152:155], v[176:179], v[8:11]
	v_mfma_f32_16x16x32_bf16 v[64:67], v[144:147], v[226:229], v[64:67]
	v_mfma_f32_16x16x32_bf16 v[0:3], v[152:155], v[226:229], v[0:3]
	v_mfma_f32_16x16x32_bf16 v[72:75], v[144:147], v[160:163], v[92:95]
	v_mfma_f32_16x16x32_bf16 v[24:27], v[156:159], v[164:167], v[24:27]
	v_mfma_f32_16x16x32_bf16 v[84:87], v[148:151], v[172:175], v[84:87]
	v_mfma_f32_16x16x32_bf16 v[16:19], v[156:159], v[172:175], v[16:19]
	v_mfma_f32_16x16x32_bf16 v[76:79], v[148:151], v[180:183], v[76:79]
	v_mfma_f32_16x16x32_bf16 v[8:11], v[156:159], v[180:183], v[8:11]
	v_mfma_f32_16x16x32_bf16 v[64:67], v[148:151], v[230:233], v[64:67]
	v_mfma_f32_16x16x32_bf16 v[0:3], v[156:159], v[230:233], v[0:3]
	v_mfma_f32_16x16x32_bf16 v[72:75], v[148:151], v[164:167], v[72:75]
	s_barrier
; #define PG8_STAGE(bufoff, gbase, voff) do { _Pragma("unroll") for (int _i = 0; _i < 2; ++_i) \
;         __builtin_amdgcn_global_load_lds((const unsigned*)((const char*)(gbase) + (voff)[_i]), (PG8_LAS unsigned*)(lds + (bufoff) + ldsw + _i * 8192), 16, 0, 0); } while (0)
; #define PG8_LDA(dst, b, h) do { _Pragma("unroll") for (int m = 0; m < 4; ++m) _Pragma("unroll") for (int k = 0; k < 2; ++k) dst[m][k] = *(const PG8_LAS bf16x8*)(lds + PG8_SA(b, h) + aoff + m * 2048 + k * 1024); } while (0)
; #define PG8_LDB(dst, b, h) do { _Pragma("unroll") for (int n = 0; n < 2; ++n) _Pragma("unroll") for (int k = 0; k < 2; ++k) dst[n][k] = *(const PG8_LAS bf16x8*)(lds + PG8_SB(b, h) + boff + n * 2048 + k * 1024); } while (0)
; #define PG8_MMA(ai, bj, At, Bt) do { __builtin_amdgcn_s_setprio(1); _Pragma("unroll") for (int m = 0; m < 4; ++m) _Pragma("unroll") for (int n = 0; n < 2; ++n) _Pragma("unroll") for (int k = 0; k < 2; ++k) \
;         acc[ai][bj][m][n] = __builtin_amdgcn_mfma_f32_16x16x32_bf16(Bt[n][k], At[m][k], acc[ai][bj][m][n], 0, 0, 0); __builtin_amdgcn_s_setprio(0); } while (0)
; #define PG8_WAIT_V(n) asm volatile("s_waitcnt vmcnt(" #n ")" ::: "memory")
; #define PG8_WAIT_L(n) asm volatile("s_waitcnt lgkmcnt(" #n ")" ::: "memory")
; #define PG8_BAR __builtin_amdgcn_s_barrier()
; #define PG8_SCHED __builtin_amdgcn_sched_barrier(0)
; template <class Epi, class Sched, bool ALIGN_EPI = false, bool SP2 = false>
; __device__ __forceinline__ void gemm_phase(PG8_LAS unsigned char* lds, const Gemm g, const Sched& S, const Epi& E, const int tid_arg) {
;     ...
;         for (int t = 0; t < nt; t += 2) {
;     ...
;             PG8_LDB(B0, 1, 0); PG8_LDB(B1, 1, 1); PG8_SCHED; PG8_LDA(At, 1, 0); PG8_STAGE(PG8_SA(0, 1), a2 + hstep, voffA);
;             PG8_WAIT_V(8); PG8_WAIT_L(0); PG8_BAR; PG8_MMA(0, 0, At, B0); PG8_MMA(0, 1, At, B1); PG8_BAR; PG8_SCHED;
;             PG8_LDA(At, 1, 1); PG8_STAGE(PG8_SB(1, 0), b3, voffB); PG8_STAGE(PG8_SB(1, 1), b3 + hstep, voffB); PG8_STAGE(PG8_SA(1, 0), a3, voffA);
;             PG8_WAIT_V(8); PG8_WAIT_L(0); PG8_BAR; PG8_MMA(1, 0, At, B0); PG8_MMA(1, 1, At, B1); PG8_BAR; PG8_SCHED;
	s_setprio 0
	s_add_u32 s4, s14, 0x40000
	s_addc_u32 s5, s15, 0
	s_mov_b32 m0, s53
	s_nop 0
	global_load_lds_dwordx4 v186, s[4:5]
	s_mov_b32 m0, s54
	s_nop 0
	global_load_lds_dwordx4 v190, s[4:5]
	ds_read_b128 v[92:95], v215
	ds_read_b128 v[100:103], v216
	ds_read_b128 v[136:139], v217
	ds_read_b128 v[140:143], v218
	ds_read_b128 v[144:147], v219
	ds_read_b128 v[148:151], v220
	ds_read_b128 v[152:155], v221
	ds_read_b128 v[156:159], v222
	ds_read_b128 v[160:163], v206 offset:32768
	ds_read_b128 v[164:167], v206 offset:33792
	ds_read_b128 v[168:171], v206 offset:34816
	ds_read_b128 v[172:175], v206 offset:35840
	ds_read_b128 v[176:179], v206 offset:36864
	ds_read_b128 v[180:183], v206 offset:37888
	ds_read_b128 v[226:229], v206 offset:38912
	ds_read_b128 v[230:233], v206 offset:39936
	s_waitcnt vmcnt(8)
	s_waitcnt lgkmcnt(0)
	s_setprio 1
	s_barrier
	v_mfma_f32_16x16x32_bf16 v[132:135], v[92:95], v[160:163], v[132:135]
	v_mfma_f32_16x16x32_bf16 v[60:63], v[136:139], v[160:163], v[60:63]
	v_mfma_f32_16x16x32_bf16 v[124:127], v[92:95], v[168:171], v[124:127]
	v_mfma_f32_16x16x32_bf16 v[52:55], v[136:139], v[168:171], v[52:55]
	v_mfma_f32_16x16x32_bf16 v[116:119], v[92:95], v[176:179], v[116:119]
	v_mfma_f32_16x16x32_bf16 v[44:47], v[136:139], v[176:179], v[44:47]
	v_mfma_f32_16x16x32_bf16 v[108:111], v[92:95], v[226:229], v[108:111]
	v_mfma_f32_16x16x32_bf16 v[36:39], v[136:139], v[226:229], v[36:39]
	v_mfma_f32_16x16x32_bf16 v[132:135], v[100:103], v[164:167], v[132:135]
	v_mfma_f32_16x16x32_bf16 v[60:63], v[140:143], v[164:167], v[60:63]
	v_mfma_f32_16x16x32_bf16 v[124:127], v[100:103], v[172:175], v[124:127]
	v_mfma_f32_16x16x32_bf16 v[52:55], v[140:143], v[172:175], v[52:55]
	v_mfma_f32_16x16x32_bf16 v[116:119], v[100:103], v[180:183], v[116:119]
	v_mfma_f32_16x16x32_bf16 v[44:47], v[140:143], v[180:183], v[44:47]
	v_mfma_f32_16x16x32_bf16 v[108:111], v[100:103], v[230:233], v[108:111]
	v_mfma_f32_16x16x32_bf16 v[36:39], v[140:143], v[230:233], v[36:39]
	s_setprio 0
	s_setprio 1
	v_mfma_f32_16x16x32_bf16 v[128:131], v[144:147], v[160:163], v[128:131]
	v_mfma_f32_16x16x32_bf16 v[56:59], v[152:155], v[160:163], v[56:59]
	v_mfma_f32_16x16x32_bf16 v[120:123], v[144:147], v[168:171], v[120:123]
	v_mfma_f32_16x16x32_bf16 v[48:51], v[152:155], v[168:171], v[48:51]
	v_mfma_f32_16x16x32_bf16 v[112:115], v[144:147], v[176:179], v[112:115]
	v_mfma_f32_16x16x32_bf16 v[40:43], v[152:155], v[176:179], v[40:43]
	v_mfma_f32_16x16x32_bf16 v[104:107], v[144:147], v[226:229], v[104:107]
	v_mfma_f32_16x16x32_bf16 v[32:35], v[152:155], v[226:229], v[32:35]
	v_mfma_f32_16x16x32_bf16 v[128:131], v[148:151], v[164:167], v[128:131]
	v_mfma_f32_16x16x32_bf16 v[56:59], v[156:159], v[164:167], v[56:59]
	v_mfma_f32_16x16x32_bf16 v[120:123], v[148:151], v[172:175], v[120:123]
	v_mfma_f32_16x16x32_bf16 v[48:51], v[156:159], v[172:175], v[48:51]
	v_mfma_f32_16x16x32_bf16 v[112:115], v[148:151], v[180:183], v[112:115]
	v_mfma_f32_16x16x32_bf16 v[40:43], v[156:159], v[180:183], v[40:43]
	v_mfma_f32_16x16x32_bf16 v[104:107], v[148:151], v[230:233], v[104:107]
	v_mfma_f32_16x16x32_bf16 v[32:35], v[156:159], v[230:233], v[32:35]
	s_barrier
	s_setprio 0
	s_mov_b32 m0, s59
	s_add_u32 s0, s0, 0x40080
	global_load_lds_dwordx4 v188, s[98:99]
	s_mov_b32 m0, s60
	s_addc_u32 s1, s1, 0
	global_load_lds_dwordx4 v192, s[98:99]
	s_mov_b32 m0, s63
	s_nop 0
	global_load_lds_dwordx4 v188, s[0:1]
	s_mov_b32 m0, s64
	s_nop 0
	global_load_lds_dwordx4 v192, s[0:1]
	s_mov_b32 m0, s61
	s_nop 0
	global_load_lds_dwordx4 v186, s[100:101]
	s_mov_b32 m0, s62
	s_nop 0
	global_load_lds_dwordx4 v190, s[100:101]
	ds_read_b128 v[160:163], v206 offset:49152
	ds_read_b128 v[164:167], v206 offset:50176
	ds_read_b128 v[168:171], v206 offset:51200
	ds_read_b128 v[172:175], v206 offset:52224
	ds_read_b128 v[176:179], v206 offset:53248
	ds_read_b128 v[180:183], v206 offset:54272
	ds_read_b128 v[226:229], v206 offset:55296
	ds_read_b128 v[230:233], v206 offset:56320
	s_waitcnt vmcnt(8)
	s_waitcnt lgkmcnt(0)
	s_setprio 1
	s_barrier
	v_mfma_f32_16x16x32_bf16 v[96:99], v[92:95], v[160:163], v[96:99]
	v_mfma_f32_16x16x32_bf16 v[28:31], v[136:139], v[160:163], v[28:31]
	v_mfma_f32_16x16x32_bf16 v[88:91], v[92:95], v[168:171], v[88:91]
	v_mfma_f32_16x16x32_bf16 v[20:23], v[136:139], v[168:171], v[20:23]
	v_mfma_f32_16x16x32_bf16 v[80:83], v[92:95], v[176:179], v[80:83]
	v_mfma_f32_16x16x32_bf16 v[12:15], v[136:139], v[176:179], v[12:15]
	v_mfma_f32_16x16x32_bf16 v[68:71], v[92:95], v[226:229], v[68:71]
	v_mfma_f32_16x16x32_bf16 v[4:7], v[136:139], v[226:229], v[4:7]
	v_mfma_f32_16x16x32_bf16 v[96:99], v[100:103], v[164:167], v[96:99]
	v_mfma_f32_16x16x32_bf16 v[28:31], v[140:143], v[164:167], v[28:31]
	v_mfma_f32_16x16x32_bf16 v[88:91], v[100:103], v[172:175], v[88:91]
	v_mfma_f32_16x16x32_bf16 v[20:23], v[140:143], v[172:175], v[20:23]
	v_mfma_f32_16x16x32_bf16 v[80:83], v[100:103], v[180:183], v[80:83]
	v_mfma_f32_16x16x32_bf16 v[12:15], v[140:143], v[180:183], v[12:15]
	v_mfma_f32_16x16x32_bf16 v[68:71], v[100:103], v[230:233], v[68:71]
	v_mfma_f32_16x16x32_bf16 v[4:7], v[140:143], v[230:233], v[4:7]
	s_setprio 0
	s_setprio 1
	v_mfma_f32_16x16x32_bf16 v[72:75], v[144:147], v[160:163], v[72:75]
	v_mfma_f32_16x16x32_bf16 v[92:95], v[148:151], v[164:167], v[72:75]
	v_mfma_f32_16x16x32_bf16 v[72:75], v[144:147], v[168:171], v[84:87]
	v_mfma_f32_16x16x32_bf16 v[24:27], v[152:155], v[160:163], v[24:27]
	v_mfma_f32_16x16x32_bf16 v[84:87], v[148:151], v[172:175], v[72:75]
	v_mfma_f32_16x16x32_bf16 v[16:19], v[152:155], v[168:171], v[16:19]
	v_mfma_f32_16x16x32_bf16 v[72:75], v[144:147], v[176:179], v[76:79]
	v_mfma_f32_16x16x32_bf16 v[8:11], v[152:155], v[176:179], v[8:11]
	v_mfma_f32_16x16x32_bf16 v[64:67], v[144:147], v[226:229], v[64:67]
	v_mfma_f32_16x16x32_bf16 v[0:3], v[152:155], v[226:229], v[0:3]
	v_mfma_f32_16x16x32_bf16 v[24:27], v[156:159], v[164:167], v[24:27]
	v_mfma_f32_16x16x32_bf16 v[16:19], v[156:159], v[172:175], v[16:19]
	v_mfma_f32_16x16x32_bf16 v[76:79], v[148:151], v[180:183], v[72:75]
	v_mfma_f32_16x16x32_bf16 v[8:11], v[156:159], v[180:183], v[8:11]
	v_mfma_f32_16x16x32_bf16 v[64:67], v[148:151], v[230:233], v[64:67]
	v_mfma_f32_16x16x32_bf16 v[0:3], v[156:159], v[230:233], v[0:3]
	s_barrier
	s_setprio 0
	s_add_i32 s79, s79, 2
	s_add_u32 s47, s47, 0x100
	s_addc_u32 s78, s78, 0
	s_cmp_gt_u32 s79, 13
	s_mov_b64 s[4:5], s[10:11]
	s_cbranch_scc0 .LBB0_685
	s_and_b64 vcc, exec, s[26:27]
	s_cbranch_vccz .LBB0_688
	s_barrier

; #define PG8_STAGE(bufoff, gbase, voff) do { _Pragma("unroll") for (int _i = 0; _i < 2; ++_i) \
;         __builtin_amdgcn_global_load_lds((const unsigned*)((const char*)(gbase) + (voff)[_i]), (PG8_LAS unsigned*)(lds + (bufoff) + ldsw + _i * 8192), 16, 0, 0); } while (0)
; #define PG8_LDA(dst, b, h) do { _Pragma("unroll") for (int m = 0; m < 4; ++m) _Pragma("unroll") for (int k = 0; k < 2; ++k) dst[m][k] = *(const PG8_LAS bf16x8*)(lds + PG8_SA(b, h) + aoff + m * 2048 + k * 1024); } while (0)
; #define PG8_LDB(dst, b, h) do { _Pragma("unroll") for (int n = 0; n < 2; ++n) _Pragma("unroll") for (int k = 0; k < 2; ++k) dst[n][k] = *(const PG8_LAS bf16x8*)(lds + PG8_SB(b, h) + boff + n * 2048 + k * 1024); } while (0)
; #define PG8_MMA(ai, bj, At, Bt) do { __builtin_amdgcn_s_setprio(1); _Pragma("unroll") for (int m = 0; m < 4; ++m) _Pragma("unroll") for (int n = 0; n < 2; ++n) _Pragma("unroll") for (int k = 0; k < 2; ++k) \
;         acc[ai][bj][m][n] = __builtin_amdgcn_mfma_f32_16x16x32_bf16(Bt[n][k], At[m][k], acc[ai][bj][m][n], 0, 0, 0); __builtin_amdgcn_s_setprio(0); } while (0)
; #define PG8_WAIT_V(n) asm volatile("s_waitcnt vmcnt(" #n ")" ::: "memory")
; #define PG8_WAIT_L(n) asm volatile("s_waitcnt lgkmcnt(" #n ")" ::: "memory")
; template <class Epi, class Sched, bool ALIGN_EPI = false, bool SP2 = false>
; __device__ __forceinline__ void gemm_phase(PG8_LAS unsigned char* lds, const Gemm g, const Sched& S, const Epi& E, const int tid_arg) {
;     ...
;             const bool last = (t == nt - 2);
;             const char* a1 = cA + (size_t)(t + 1) * kstep;
;             const char* a2 = last ? nA : cA + (size_t)(t + 2) * kstep; const char* b2 = last ? nB : cB + (size_t)(t + 2) * kstep;
;             const char* a3 = a2 + kstep; const char* b3 = b2 + kstep;
;             if (last && has_next) S.a_ready(nxt);
;             if constexpr (SP2) {
;             PG8_LDB(B0, 0, 0); PG8_LDB(B1, 0, 1); PG8_SCHED; PG8_LDA(At, 0, 0); PG8_STAGE(PG8_SA(1, 1), a1 + hstep, voffA);
;             PG8_WAIT_V(8); PG8_WAIT_L(0); PG8_BAR; PG8_MMA(0, 0, At, B0); PG8_MMA(0, 1, At, B1); PG8_BAR; PG8_SCHED;
;             PG8_LDA(At, 0, 1); PG8_STAGE(PG8_SB(0, 0), b2, voffB); PG8_STAGE(PG8_SB(0, 1), b2 + hstep, voffB); PG8_STAGE(PG8_SA(0, 0), a2, voffA);
;             PG8_WAIT_V(8); PG8_WAIT_L(0); PG8_BAR; PG8_MMA(1, 0, At, B0); PG8_MMA(1, 1, At, B1); PG8_BAR; PG8_SCHED;
.LBB0_871:
	s_add_u32 s22, s4, 0x100
	s_addc_u32 s23, s5, 0
	s_cmp_eq_u32 s57, 40
	s_cselect_b32 s25, s13, s23
	s_cselect_b32 s24, s12, s22
	s_cselect_b32 s1, s21, s56
	s_cselect_b32 s0, s20, s55
	s_mov_b32 m0, s48
	s_nop 0
	global_load_lds_dwordx4 v138, s[4:5]
	s_mov_b32 m0, s49
	s_nop 0
	global_load_lds_dwordx4 v136, s[4:5]
	ds_read_b128 v[144:147], v151
	ds_read_b128 v[168:171], v152
	ds_read_b128 v[172:175], v153
	ds_read_b128 v[176:179], v154
	ds_read_b128 v[180:183], v155
	ds_read_b128 v[184:187], v156
	ds_read_b128 v[188:191], v157
	ds_read_b128 v[192:195], v158
	ds_read_b128 v[196:199], v150
	ds_read_b128 v[200:203], v150 offset:1024
	ds_read_b128 v[204:207], v150 offset:2048
	ds_read_b128 v[208:211], v150 offset:3072
	ds_read_b128 v[212:215], v150 offset:4096
	ds_read_b128 v[216:219], v150 offset:5120
	ds_read_b128 v[220:223], v150 offset:6144
	ds_read_b128 v[224:227], v150 offset:7168
	s_waitcnt vmcnt(8)
	s_waitcnt lgkmcnt(0)
	s_setprio 1
	s_barrier
	v_mfma_f32_16x16x32_bf16 v[124:127], v[144:147], v[196:199], v[124:127]
	v_mfma_f32_16x16x32_bf16 v[120:123], v[172:175], v[196:199], v[120:123]
	v_mfma_f32_16x16x32_bf16 v[108:111], v[144:147], v[204:207], v[108:111]
	v_mfma_f32_16x16x32_bf16 v[104:107], v[172:175], v[204:207], v[104:107]
	v_mfma_f32_16x16x32_bf16 v[92:95], v[144:147], v[212:215], v[92:95]
	v_mfma_f32_16x16x32_bf16 v[88:91], v[172:175], v[212:215], v[88:91]
	v_mfma_f32_16x16x32_bf16 v[76:79], v[144:147], v[220:223], v[76:79]
	v_mfma_f32_16x16x32_bf16 v[72:75], v[172:175], v[220:223], v[72:75]
	v_mfma_f32_16x16x32_bf16 v[124:127], v[168:171], v[200:203], v[124:127]
	v_mfma_f32_16x16x32_bf16 v[120:123], v[176:179], v[200:203], v[120:123]
	v_mfma_f32_16x16x32_bf16 v[108:111], v[168:171], v[208:211], v[108:111]
	v_mfma_f32_16x16x32_bf16 v[104:107], v[176:179], v[208:211], v[104:107]
	v_mfma_f32_16x16x32_bf16 v[92:95], v[168:171], v[216:219], v[92:95]
	v_mfma_f32_16x16x32_bf16 v[88:91], v[176:179], v[216:219], v[88:91]
	v_mfma_f32_16x16x32_bf16 v[76:79], v[168:171], v[224:227], v[76:79]
	v_mfma_f32_16x16x32_bf16 v[72:75], v[176:179], v[224:227], v[72:75]
	s_setprio 0
	s_setprio 1
	v_mfma_f32_16x16x32_bf16 v[116:119], v[180:183], v[196:199], v[116:119]
	v_mfma_f32_16x16x32_bf16 v[112:115], v[188:191], v[196:199], v[112:115]
	v_mfma_f32_16x16x32_bf16 v[100:103], v[180:183], v[204:207], v[100:103]
	v_mfma_f32_16x16x32_bf16 v[96:99], v[188:191], v[204:207], v[96:99]
	v_mfma_f32_16x16x32_bf16 v[84:87], v[180:183], v[212:215], v[84:87]
	v_mfma_f32_16x16x32_bf16 v[80:83], v[188:191], v[212:215], v[80:83]
	v_mfma_f32_16x16x32_bf16 v[68:71], v[180:183], v[220:223], v[68:71]
	v_mfma_f32_16x16x32_bf16 v[64:67], v[188:191], v[220:223], v[64:67]
	v_mfma_f32_16x16x32_bf16 v[116:119], v[184:187], v[200:203], v[116:119]
	v_mfma_f32_16x16x32_bf16 v[112:115], v[192:195], v[200:203], v[112:115]
	v_mfma_f32_16x16x32_bf16 v[100:103], v[184:187], v[208:211], v[100:103]
	v_mfma_f32_16x16x32_bf16 v[96:99], v[192:195], v[208:211], v[96:99]
	v_mfma_f32_16x16x32_bf16 v[84:87], v[184:187], v[216:219], v[84:87]
	v_mfma_f32_16x16x32_bf16 v[80:83], v[192:195], v[216:219], v[80:83]
	v_mfma_f32_16x16x32_bf16 v[68:71], v[184:187], v[224:227], v[68:71]
	v_mfma_f32_16x16x32_bf16 v[64:67], v[192:195], v[224:227], v[64:67]
	s_barrier
	s_setprio 0
	s_mov_b32 m0, s29
	s_add_u32 s98, s0, s16
	s_addc_u32 s99, s1, s17
	s_add_u32 s4, s0, 0xb0000
	global_load_lds_dwordx4 v130, s[0:1]
	s_mov_b32 m0, s30
	s_addc_u32 s5, s1, 0
	global_load_lds_dwordx4 v134, s[0:1]
	s_mov_b32 m0, s31
	s_nop 0
	global_load_lds_dwordx4 v130, s[4:5]
	s_mov_b32 m0, s33
	s_nop 0
	global_load_lds_dwordx4 v134, s[4:5]
	s_add_u32 s100, s24, s16
	s_addc_u32 s101, s25, s17
	s_mov_b32 m0, s28
	s_nop 0
	global_load_lds_dwordx4 v128, s[24:25]
	s_mov_b32 m0, s34
	s_nop 0
	global_load_lds_dwordx4 v132, s[24:25]
	ds_read_b128 v[196:199], v150 offset:16384
	ds_read_b128 v[200:203], v150 offset:17408
	ds_read_b128 v[204:207], v150 offset:18432
	ds_read_b128 v[208:211], v150 offset:19456
	ds_read_b128 v[212:215], v150 offset:20480
	ds_read_b128 v[216:219], v150 offset:21504
	ds_read_b128 v[220:223], v150 offset:22528
	ds_read_b128 v[224:227], v150 offset:23552
	s_waitcnt vmcnt(8)
	s_waitcnt lgkmcnt(0)
	s_setprio 1
	s_barrier
	v_mfma_f32_16x16x32_bf16 v[60:63], v[144:147], v[196:199], v[60:63]
	v_mfma_f32_16x16x32_bf16 v[56:59], v[172:175], v[196:199], v[56:59]
	v_mfma_f32_16x16x32_bf16 v[44:47], v[144:147], v[204:207], v[44:47]
	v_mfma_f32_16x16x32_bf16 v[40:43], v[172:175], v[204:207], v[40:43]
	v_mfma_f32_16x16x32_bf16 v[28:31], v[144:147], v[212:215], v[28:31]
	v_mfma_f32_16x16x32_bf16 v[24:27], v[172:175], v[212:215], v[24:27]
	v_mfma_f32_16x16x32_bf16 v[12:15], v[144:147], v[220:223], v[12:15]
	v_mfma_f32_16x16x32_bf16 v[8:11], v[172:175], v[220:223], v[8:11]
	v_mfma_f32_16x16x32_bf16 v[60:63], v[168:171], v[200:203], v[60:63]
	v_mfma_f32_16x16x32_bf16 v[56:59], v[176:179], v[200:203], v[56:59]
	v_mfma_f32_16x16x32_bf16 v[44:47], v[168:171], v[208:211], v[44:47]
	v_mfma_f32_16x16x32_bf16 v[40:43], v[176:179], v[208:211], v[40:43]
	v_mfma_f32_16x16x32_bf16 v[28:31], v[168:171], v[216:219], v[28:31]
	v_mfma_f32_16x16x32_bf16 v[24:27], v[176:179], v[216:219], v[24:27]
	v_mfma_f32_16x16x32_bf16 v[12:15], v[168:171], v[224:227], v[12:15]
	v_mfma_f32_16x16x32_bf16 v[8:11], v[176:179], v[224:227], v[8:11]
	s_setprio 0
	s_setprio 1
	v_mfma_f32_16x16x32_bf16 v[52:55], v[180:183], v[196:199], v[52:55]
	v_mfma_f32_16x16x32_bf16 v[48:51], v[188:191], v[196:199], v[48:51]
	v_mfma_f32_16x16x32_bf16 v[36:39], v[180:183], v[204:207], v[36:39]
	v_mfma_f32_16x16x32_bf16 v[32:35], v[188:191], v[204:207], v[32:35]
	v_mfma_f32_16x16x32_bf16 v[20:23], v[180:183], v[212:215], v[20:23]
	v_mfma_f32_16x16x32_bf16 v[16:19], v[188:191], v[212:215], v[16:19]
	v_mfma_f32_16x16x32_bf16 v[4:7], v[180:183], v[220:223], v[4:7]
	v_mfma_f32_16x16x32_bf16 v[0:3], v[188:191], v[220:223], v[0:3]
	v_mfma_f32_16x16x32_bf16 v[52:55], v[184:187], v[200:203], v[52:55]
	v_mfma_f32_16x16x32_bf16 v[48:51], v[192:195], v[200:203], v[48:51]
	v_mfma_f32_16x16x32_bf16 v[36:39], v[184:187], v[208:211], v[36:39]
	v_mfma_f32_16x16x32_bf16 v[32:35], v[192:195], v[208:211], v[32:35]
	v_mfma_f32_16x16x32_bf16 v[20:23], v[184:187], v[216:219], v[20:23]
	v_mfma_f32_16x16x32_bf16 v[16:19], v[192:195], v[216:219], v[16:19]
	v_mfma_f32_16x16x32_bf16 v[4:7], v[184:187], v[224:227], v[4:7]
	v_mfma_f32_16x16x32_bf16 v[0:3], v[192:195], v[224:227], v[0:3]
	s_barrier
; #define PG8_STAGE(bufoff, gbase, voff) do { _Pragma("unroll") for (int _i = 0; _i < 2; ++_i) \
;         __builtin_amdgcn_global_load_lds((const unsigned*)((const char*)(gbase) + (voff)[_i]), (PG8_LAS unsigned*)(lds + (bufoff) + ldsw + _i * 8192), 16, 0, 0); } while (0)
; #define PG8_LDA(dst, b, h) do { _Pragma("unroll") for (int m = 0; m < 4; ++m) _Pragma("unroll") for (int k = 0; k < 2; ++k) dst[m][k] = *(const PG8_LAS bf16x8*)(lds + PG8_SA(b, h) + aoff + m * 2048 + k * 1024); } while (0)
; #define PG8_LDB(dst, b, h) do { _Pragma("unroll") for (int n = 0; n < 2; ++n) _Pragma("unroll") for (int k = 0; k < 2; ++k) dst[n][k] = *(const PG8_LAS bf16x8*)(lds + PG8_SB(b, h) + boff + n * 2048 + k * 1024); } while (0)
; #define PG8_MMA(ai, bj, At, Bt) do { __builtin_amdgcn_s_setprio(1); _Pragma("unroll") for (int m = 0; m < 4; ++m) _Pragma("unroll") for (int n = 0; n < 2; ++n) _Pragma("unroll") for (int k = 0; k < 2; ++k) \
;         acc[ai][bj][m][n] = __builtin_amdgcn_mfma_f32_16x16x32_bf16(Bt[n][k], At[m][k], acc[ai][bj][m][n], 0, 0, 0); __builtin_amdgcn_s_setprio(0); } while (0)
; #define PG8_WAIT_V(n) asm volatile("s_waitcnt vmcnt(" #n ")" ::: "memory")
; #define PG8_WAIT_L(n) asm volatile("s_waitcnt lgkmcnt(" #n ")" ::: "memory")
; #define PG8_BAR __builtin_amdgcn_s_barrier()
; #define PG8_SCHED __builtin_amdgcn_sched_barrier(0)
; template <class Epi, class Sched, bool ALIGN_EPI = false, bool SP2 = false>
; __device__ __forceinline__ void gemm_phase(PG8_LAS unsigned char* lds, const Gemm g, const Sched& S, const Epi& E, const int tid_arg) {
;     ...
;         for (int t = 0; t < nt; t += 2) {
;     ...
;             PG8_LDB(B0, 1, 0); PG8_LDB(B1, 1, 1); PG8_SCHED; PG8_LDA(At, 1, 0); PG8_STAGE(PG8_SA(0, 1), a2 + hstep, voffA);
;             PG8_WAIT_V(8); PG8_WAIT_L(0); PG8_BAR; PG8_MMA(0, 0, At, B0); PG8_MMA(0, 1, At, B1); PG8_BAR; PG8_SCHED;
;             PG8_LDA(At, 1, 1); PG8_STAGE(PG8_SB(1, 0), b3, voffB); PG8_STAGE(PG8_SB(1, 1), b3 + hstep, voffB); PG8_STAGE(PG8_SA(1, 0), a3, voffA);
;             PG8_WAIT_V(8); PG8_WAIT_L(0); PG8_BAR; PG8_MMA(1, 0, At, B0); PG8_MMA(1, 1, At, B1); PG8_BAR; PG8_SCHED;
	s_setprio 0
	s_add_u32 s4, s24, 0xb0000
	s_addc_u32 s5, s25, 0
	s_mov_b32 m0, s35
	s_nop 0
	global_load_lds_dwordx4 v128, s[4:5]
	s_mov_b32 m0, s36
	s_nop 0
	global_load_lds_dwordx4 v132, s[4:5]
	ds_read_b128 v[144:147], v159
	ds_read_b128 v[168:171], v160
	ds_read_b128 v[172:175], v161
	ds_read_b128 v[176:179], v162
	ds_read_b128 v[180:183], v163
	ds_read_b128 v[184:187], v164
	ds_read_b128 v[188:191], v165
	ds_read_b128 v[192:195], v166
	ds_read_b128 v[196:199], v150 offset:32768
	ds_read_b128 v[200:203], v150 offset:33792
	ds_read_b128 v[204:207], v150 offset:34816
	ds_read_b128 v[208:211], v150 offset:35840
	ds_read_b128 v[212:215], v150 offset:36864
	ds_read_b128 v[216:219], v150 offset:37888
	ds_read_b128 v[220:223], v150 offset:38912
	ds_read_b128 v[224:227], v150 offset:39936
	s_waitcnt vmcnt(8)
	s_waitcnt lgkmcnt(0)
	s_setprio 1
	s_barrier
	v_mfma_f32_16x16x32_bf16 v[124:127], v[144:147], v[196:199], v[124:127]
	v_mfma_f32_16x16x32_bf16 v[120:123], v[172:175], v[196:199], v[120:123]
	v_mfma_f32_16x16x32_bf16 v[108:111], v[144:147], v[204:207], v[108:111]
	v_mfma_f32_16x16x32_bf16 v[104:107], v[172:175], v[204:207], v[104:107]
	v_mfma_f32_16x16x32_bf16 v[92:95], v[144:147], v[212:215], v[92:95]
	v_mfma_f32_16x16x32_bf16 v[88:91], v[172:175], v[212:215], v[88:91]
	v_mfma_f32_16x16x32_bf16 v[76:79], v[144:147], v[220:223], v[76:79]
	v_mfma_f32_16x16x32_bf16 v[72:75], v[172:175], v[220:223], v[72:75]
	v_mfma_f32_16x16x32_bf16 v[124:127], v[168:171], v[200:203], v[124:127]
	v_mfma_f32_16x16x32_bf16 v[120:123], v[176:179], v[200:203], v[120:123]
	v_mfma_f32_16x16x32_bf16 v[108:111], v[168:171], v[208:211], v[108:111]
	v_mfma_f32_16x16x32_bf16 v[104:107], v[176:179], v[208:211], v[104:107]
	v_mfma_f32_16x16x32_bf16 v[92:95], v[168:171], v[216:219], v[92:95]
	v_mfma_f32_16x16x32_bf16 v[88:91], v[176:179], v[216:219], v[88:91]
	v_mfma_f32_16x16x32_bf16 v[76:79], v[168:171], v[224:227], v[76:79]
	v_mfma_f32_16x16x32_bf16 v[72:75], v[176:179], v[224:227], v[72:75]
	s_setprio 0
	s_setprio 1
	v_mfma_f32_16x16x32_bf16 v[116:119], v[180:183], v[196:199], v[116:119]
	v_mfma_f32_16x16x32_bf16 v[112:115], v[188:191], v[196:199], v[112:115]
	v_mfma_f32_16x16x32_bf16 v[100:103], v[180:183], v[204:207], v[100:103]
	v_mfma_f32_16x16x32_bf16 v[96:99], v[188:191], v[204:207], v[96:99]
	v_mfma_f32_16x16x32_bf16 v[84:87], v[180:183], v[212:215], v[84:87]
	v_mfma_f32_16x16x32_bf16 v[80:83], v[188:191], v[212:215], v[80:83]
	v_mfma_f32_16x16x32_bf16 v[68:71], v[180:183], v[220:223], v[68:71]
	v_mfma_f32_16x16x32_bf16 v[64:67], v[188:191], v[220:223], v[64:67]
	v_mfma_f32_16x16x32_bf16 v[116:119], v[184:187], v[200:203], v[116:119]
	v_mfma_f32_16x16x32_bf16 v[112:115], v[192:195], v[200:203], v[112:115]
	v_mfma_f32_16x16x32_bf16 v[100:103], v[184:187], v[208:211], v[100:103]
	v_mfma_f32_16x16x32_bf16 v[96:99], v[192:195], v[208:211], v[96:99]
	v_mfma_f32_16x16x32_bf16 v[84:87], v[184:187], v[216:219], v[84:87]
	v_mfma_f32_16x16x32_bf16 v[80:83], v[192:195], v[216:219], v[80:83]
	v_mfma_f32_16x16x32_bf16 v[68:71], v[184:187], v[224:227], v[68:71]
	v_mfma_f32_16x16x32_bf16 v[64:67], v[192:195], v[224:227], v[64:67]
	s_barrier
	s_setprio 0
	s_mov_b32 m0, s40
	s_add_u32 s0, s0, 0xb0080
	global_load_lds_dwordx4 v130, s[98:99]
	s_mov_b32 m0, s41
	s_addc_u32 s1, s1, 0
	global_load_lds_dwordx4 v134, s[98:99]
	s_mov_b32 m0, s44
	s_nop 0
	global_load_lds_dwordx4 v130, s[0:1]
	s_mov_b32 m0, s45
	s_nop 0
	global_load_lds_dwordx4 v134, s[0:1]
	s_mov_b32 m0, s42
	s_nop 0
	global_load_lds_dwordx4 v128, s[100:101]
	s_mov_b32 m0, s43
	s_nop 0
	global_load_lds_dwordx4 v132, s[100:101]
	ds_read_b128 v[196:199], v150 offset:49152
	ds_read_b128 v[200:203], v150 offset:50176
	ds_read_b128 v[204:207], v150 offset:51200
	ds_read_b128 v[208:211], v150 offset:52224
	ds_read_b128 v[212:215], v150 offset:53248
	ds_read_b128 v[216:219], v150 offset:54272
	ds_read_b128 v[220:223], v150 offset:55296
	ds_read_b128 v[224:227], v150 offset:56320
	s_waitcnt vmcnt(8)
	s_waitcnt lgkmcnt(0)
	s_setprio 1
	s_barrier
	v_mfma_f32_16x16x32_bf16 v[60:63], v[144:147], v[196:199], v[60:63]
	v_mfma_f32_16x16x32_bf16 v[56:59], v[172:175], v[196:199], v[56:59]
	v_mfma_f32_16x16x32_bf16 v[44:47], v[144:147], v[204:207], v[44:47]
	v_mfma_f32_16x16x32_bf16 v[40:43], v[172:175], v[204:207], v[40:43]
	v_mfma_f32_16x16x32_bf16 v[28:31], v[144:147], v[212:215], v[28:31]
	v_mfma_f32_16x16x32_bf16 v[24:27], v[172:175], v[212:215], v[24:27]
	v_mfma_f32_16x16x32_bf16 v[12:15], v[144:147], v[220:223], v[12:15]
	v_mfma_f32_16x16x32_bf16 v[8:11], v[172:175], v[220:223], v[8:11]
	v_mfma_f32_16x16x32_bf16 v[60:63], v[168:171], v[200:203], v[60:63]
	v_mfma_f32_16x16x32_bf16 v[56:59], v[176:179], v[200:203], v[56:59]
	v_mfma_f32_16x16x32_bf16 v[44:47], v[168:171], v[208:211], v[44:47]
	v_mfma_f32_16x16x32_bf16 v[40:43], v[176:179], v[208:211], v[40:43]
	v_mfma_f32_16x16x32_bf16 v[28:31], v[168:171], v[216:219], v[28:31]
	v_mfma_f32_16x16x32_bf16 v[24:27], v[176:179], v[216:219], v[24:27]
	v_mfma_f32_16x16x32_bf16 v[12:15], v[168:171], v[224:227], v[12:15]
	v_mfma_f32_16x16x32_bf16 v[8:11], v[176:179], v[224:227], v[8:11]
	s_setprio 0
	s_setprio 1
	v_mfma_f32_16x16x32_bf16 v[52:55], v[180:183], v[196:199], v[52:55]
	v_mfma_f32_16x16x32_bf16 v[48:51], v[188:191], v[196:199], v[48:51]
	v_mfma_f32_16x16x32_bf16 v[36:39], v[180:183], v[204:207], v[36:39]
	v_mfma_f32_16x16x32_bf16 v[32:35], v[188:191], v[204:207], v[32:35]
	v_mfma_f32_16x16x32_bf16 v[20:23], v[180:183], v[212:215], v[20:23]
	v_mfma_f32_16x16x32_bf16 v[16:19], v[188:191], v[212:215], v[16:19]
	v_mfma_f32_16x16x32_bf16 v[4:7], v[180:183], v[220:223], v[4:7]
	v_mfma_f32_16x16x32_bf16 v[0:3], v[188:191], v[220:223], v[0:3]
	v_mfma_f32_16x16x32_bf16 v[52:55], v[184:187], v[200:203], v[52:55]
	v_mfma_f32_16x16x32_bf16 v[48:51], v[192:195], v[200:203], v[48:51]
	v_mfma_f32_16x16x32_bf16 v[36:39], v[184:187], v[208:211], v[36:39]
	v_mfma_f32_16x16x32_bf16 v[32:35], v[192:195], v[208:211], v[32:35]
	v_mfma_f32_16x16x32_bf16 v[20:23], v[184:187], v[216:219], v[20:23]
	v_mfma_f32_16x16x32_bf16 v[16:19], v[192:195], v[216:219], v[16:19]
	v_mfma_f32_16x16x32_bf16 v[4:7], v[184:187], v[224:227], v[4:7]
	v_mfma_f32_16x16x32_bf16 v[0:3], v[192:195], v[224:227], v[0:3]
	s_barrier
	s_setprio 0
	s_add_i32 s57, s57, 2
	s_add_u32 s55, s55, 0x100
	s_addc_u32 s56, s56, 0
	s_cmp_gt_u32 s57, 41
	s_mov_b64 s[4:5], s[22:23]
	s_cbranch_scc0 .LBB0_871
	s_and_b64 vcc, exec, s[18:19]
	s_cbranch_vccz .LBB0_874
	s_barrier

; #define PG8_STAGE(bufoff, gbase, voff) do { _Pragma("unroll") for (int _i = 0; _i < 2; ++_i) \
;         __builtin_amdgcn_global_load_lds((const unsigned*)((const char*)(gbase) + (voff)[_i]), (PG8_LAS unsigned*)(lds + (bufoff) + ldsw + _i * 8192), 16, 0, 0); } while (0)
; #define PG8_LDA(dst, b, h) do { _Pragma("unroll") for (int m = 0; m < 4; ++m) _Pragma("unroll") for (int k = 0; k < 2; ++k) dst[m][k] = *(const PG8_LAS bf16x8*)(lds + PG8_SA(b, h) + aoff + m * 2048 + k * 1024); } while (0)
; #define PG8_LDB(dst, b, h) do { _Pragma("unroll") for (int n = 0; n < 2; ++n) _Pragma("unroll") for (int k = 0; k < 2; ++k) dst[n][k] = *(const PG8_LAS bf16x8*)(lds + PG8_SB(b, h) + boff + n * 2048 + k * 1024); } while (0)
; #define PG8_MMA(ai, bj, At, Bt) do { __builtin_amdgcn_s_setprio(1); _Pragma("unroll") for (int m = 0; m < 4; ++m) _Pragma("unroll") for (int n = 0; n < 2; ++n) _Pragma("unroll") for (int k = 0; k < 2; ++k) \
;         acc[ai][bj][m][n] = __builtin_amdgcn_mfma_f32_16x16x32_bf16(Bt[n][k], At[m][k], acc[ai][bj][m][n], 0, 0, 0); __builtin_amdgcn_s_setprio(0); } while (0)
; #define PG8_WAIT_V(n) asm volatile("s_waitcnt vmcnt(" #n ")" ::: "memory")
; #define PG8_WAIT_L(n) asm volatile("s_waitcnt lgkmcnt(" #n ")" ::: "memory")
; template <class Epi, class Sched, bool ALIGN_EPI = false, bool SP2 = false>
; __device__ __forceinline__ void gemm_phase(PG8_LAS unsigned char* lds, const Gemm g, const Sched& S, const Epi& E, const int tid_arg) {
;     ...
;             const bool last = (t == nt - 2);
;             const char* a1 = cA + (size_t)(t + 1) * kstep;
;             const char* a2 = last ? nA : cA + (size_t)(t + 2) * kstep; const char* b2 = last ? nB : cB + (size_t)(t + 2) * kstep;
;             const char* a3 = a2 + kstep; const char* b3 = b2 + kstep;
;             if (last && has_next) S.a_ready(nxt);
;             if constexpr (SP2) {
;             PG8_LDB(B0, 0, 0); PG8_LDB(B1, 0, 1); PG8_SCHED; PG8_LDA(At, 0, 0); PG8_STAGE(PG8_SA(1, 1), a1 + hstep, voffA);
;             PG8_WAIT_V(8); PG8_WAIT_L(0); PG8_BAR; PG8_MMA(0, 0, At, B0); PG8_MMA(0, 1, At, B1); PG8_BAR; PG8_SCHED;
;             PG8_LDA(At, 0, 1); PG8_STAGE(PG8_SB(0, 0), b2, voffB); PG8_STAGE(PG8_SB(0, 1), b2 + hstep, voffB); PG8_STAGE(PG8_SA(0, 0), a2, voffA);
;             PG8_WAIT_V(8); PG8_WAIT_L(0); PG8_BAR; PG8_MMA(1, 0, At, B0); PG8_MMA(1, 1, At, B1); PG8_BAR; PG8_SCHED;
.LBB0_965:
	s_add_u32 s0, s40, 0xfffc0080
	s_addc_u32 s1, s41, -1
	s_cmp_eq_u32 s72, 12
	s_cselect_b32 s43, s35, s1
	s_cselect_b32 s42, s68, s0
	s_cselect_b32 s1, s31, s71
	s_cselect_b32 s0, s69, s70
	s_mov_b32 m0, s60
	s_nop 0
	global_load_lds_dwordx4 v138, s[40:41]
	s_mov_b32 m0, s61
	s_nop 0
	global_load_lds_dwordx4 v136, s[40:41]
	ds_read_b128 v[170:173], v151
	ds_read_b128 v[174:177], v153
	ds_read_b128 v[178:181], v155
	ds_read_b128 v[182:185], v156
	ds_read_b128 v[186:189], v157
	ds_read_b128 v[190:193], v158
	ds_read_b128 v[194:197], v159
	ds_read_b128 v[198:201], v160
	ds_read_b128 v[202:205], v149
	ds_read_b128 v[206:209], v149 offset:1024
	ds_read_b128 v[210:213], v149 offset:2048
	ds_read_b128 v[214:217], v149 offset:3072
	ds_read_b128 v[218:221], v149 offset:4096
	ds_read_b128 v[222:225], v149 offset:5120
	ds_read_b128 v[226:229], v149 offset:6144
	ds_read_b128 v[230:233], v149 offset:7168
	s_waitcnt vmcnt(8)
	s_waitcnt lgkmcnt(0)
	s_setprio 1
	s_barrier
	v_mfma_f32_16x16x32_bf16 v[124:127], v[170:173], v[202:205], v[124:127]
	v_mfma_f32_16x16x32_bf16 v[120:123], v[178:181], v[202:205], v[120:123]
	v_mfma_f32_16x16x32_bf16 v[108:111], v[170:173], v[210:213], v[108:111]
	v_mfma_f32_16x16x32_bf16 v[104:107], v[178:181], v[210:213], v[104:107]
	v_mfma_f32_16x16x32_bf16 v[92:95], v[170:173], v[218:221], v[92:95]
	v_mfma_f32_16x16x32_bf16 v[88:91], v[178:181], v[218:221], v[88:91]
	v_mfma_f32_16x16x32_bf16 v[76:79], v[170:173], v[226:229], v[76:79]
	v_mfma_f32_16x16x32_bf16 v[72:75], v[178:181], v[226:229], v[72:75]
	v_mfma_f32_16x16x32_bf16 v[124:127], v[174:177], v[206:209], v[124:127]
	v_mfma_f32_16x16x32_bf16 v[120:123], v[182:185], v[206:209], v[120:123]
	v_mfma_f32_16x16x32_bf16 v[108:111], v[174:177], v[214:217], v[108:111]
	v_mfma_f32_16x16x32_bf16 v[104:107], v[182:185], v[214:217], v[104:107]
	v_mfma_f32_16x16x32_bf16 v[92:95], v[174:177], v[222:225], v[92:95]
	v_mfma_f32_16x16x32_bf16 v[88:91], v[182:185], v[222:225], v[88:91]
	v_mfma_f32_16x16x32_bf16 v[76:79], v[174:177], v[230:233], v[76:79]
	v_mfma_f32_16x16x32_bf16 v[72:75], v[182:185], v[230:233], v[72:75]
	s_setprio 0
	s_setprio 1
	v_mfma_f32_16x16x32_bf16 v[116:119], v[186:189], v[202:205], v[116:119]
	v_mfma_f32_16x16x32_bf16 v[112:115], v[194:197], v[202:205], v[112:115]
	v_mfma_f32_16x16x32_bf16 v[100:103], v[186:189], v[210:213], v[100:103]
	v_mfma_f32_16x16x32_bf16 v[96:99], v[194:197], v[210:213], v[96:99]
	v_mfma_f32_16x16x32_bf16 v[84:87], v[186:189], v[218:221], v[84:87]
	v_mfma_f32_16x16x32_bf16 v[80:83], v[194:197], v[218:221], v[80:83]
	v_mfma_f32_16x16x32_bf16 v[68:71], v[186:189], v[226:229], v[68:71]
	v_mfma_f32_16x16x32_bf16 v[64:67], v[194:197], v[226:229], v[64:67]
	v_mfma_f32_16x16x32_bf16 v[116:119], v[190:193], v[206:209], v[116:119]
	v_mfma_f32_16x16x32_bf16 v[112:115], v[198:201], v[206:209], v[112:115]
	v_mfma_f32_16x16x32_bf16 v[100:103], v[190:193], v[214:217], v[100:103]
	v_mfma_f32_16x16x32_bf16 v[96:99], v[198:201], v[214:217], v[96:99]
	v_mfma_f32_16x16x32_bf16 v[84:87], v[190:193], v[222:225], v[84:87]
	v_mfma_f32_16x16x32_bf16 v[80:83], v[198:201], v[222:225], v[80:83]
	v_mfma_f32_16x16x32_bf16 v[68:71], v[190:193], v[230:233], v[68:71]
	v_mfma_f32_16x16x32_bf16 v[64:67], v[198:201], v[230:233], v[64:67]
	s_barrier
	s_setprio 0
	s_mov_b32 m0, s5
	s_add_u32 s98, s0, s12
	s_addc_u32 s99, s1, s13
	s_add_u32 s74, s0, 0x40000
	global_load_lds_dwordx4 v130, s[0:1]
	s_mov_b32 m0, s47
	s_addc_u32 s75, s1, 0
	global_load_lds_dwordx4 v134, s[0:1]
	s_mov_b32 m0, s48
	s_nop 0
	global_load_lds_dwordx4 v130, s[74:75]
	s_mov_b32 m0, s49
	s_nop 0
	global_load_lds_dwordx4 v134, s[74:75]
	s_add_u32 s100, s42, s12
	s_addc_u32 s101, s43, s13
	s_mov_b32 m0, s46
	s_nop 0
	global_load_lds_dwordx4 v128, s[42:43]
	s_mov_b32 m0, s50
	s_nop 0
	global_load_lds_dwordx4 v132, s[42:43]
	ds_read_b128 v[202:205], v149 offset:16384
	ds_read_b128 v[206:209], v149 offset:17408
	ds_read_b128 v[210:213], v149 offset:18432
	ds_read_b128 v[214:217], v149 offset:19456
	ds_read_b128 v[218:221], v149 offset:20480
	ds_read_b128 v[222:225], v149 offset:21504
	ds_read_b128 v[226:229], v149 offset:22528
	ds_read_b128 v[230:233], v149 offset:23552
	s_waitcnt vmcnt(8)
	s_waitcnt lgkmcnt(0)
	s_setprio 1
	s_barrier
	v_mfma_f32_16x16x32_bf16 v[60:63], v[170:173], v[202:205], v[60:63]
	v_mfma_f32_16x16x32_bf16 v[56:59], v[178:181], v[202:205], v[56:59]
	v_mfma_f32_16x16x32_bf16 v[44:47], v[170:173], v[210:213], v[44:47]
	v_mfma_f32_16x16x32_bf16 v[40:43], v[178:181], v[210:213], v[40:43]
	v_mfma_f32_16x16x32_bf16 v[28:31], v[170:173], v[218:221], v[28:31]
	v_mfma_f32_16x16x32_bf16 v[24:27], v[178:181], v[218:221], v[24:27]
	v_mfma_f32_16x16x32_bf16 v[12:15], v[170:173], v[226:229], v[12:15]
	v_mfma_f32_16x16x32_bf16 v[8:11], v[178:181], v[226:229], v[8:11]
	v_mfma_f32_16x16x32_bf16 v[60:63], v[174:177], v[206:209], v[60:63]
	v_mfma_f32_16x16x32_bf16 v[56:59], v[182:185], v[206:209], v[56:59]
	v_mfma_f32_16x16x32_bf16 v[44:47], v[174:177], v[214:217], v[44:47]
	v_mfma_f32_16x16x32_bf16 v[40:43], v[182:185], v[214:217], v[40:43]
	v_mfma_f32_16x16x32_bf16 v[28:31], v[174:177], v[222:225], v[28:31]
	v_mfma_f32_16x16x32_bf16 v[24:27], v[182:185], v[222:225], v[24:27]
	v_mfma_f32_16x16x32_bf16 v[12:15], v[174:177], v[230:233], v[12:15]
	v_mfma_f32_16x16x32_bf16 v[8:11], v[182:185], v[230:233], v[8:11]
	s_setprio 0
	s_setprio 1
	v_mfma_f32_16x16x32_bf16 v[52:55], v[186:189], v[202:205], v[52:55]
	v_mfma_f32_16x16x32_bf16 v[48:51], v[194:197], v[202:205], v[48:51]
	v_mfma_f32_16x16x32_bf16 v[36:39], v[186:189], v[210:213], v[36:39]
	v_mfma_f32_16x16x32_bf16 v[32:35], v[194:197], v[210:213], v[32:35]
	v_mfma_f32_16x16x32_bf16 v[20:23], v[186:189], v[218:221], v[20:23]
	v_mfma_f32_16x16x32_bf16 v[16:19], v[194:197], v[218:221], v[16:19]
	v_mfma_f32_16x16x32_bf16 v[4:7], v[186:189], v[226:229], v[4:7]
	v_mfma_f32_16x16x32_bf16 v[0:3], v[194:197], v[226:229], v[0:3]
	v_mfma_f32_16x16x32_bf16 v[52:55], v[190:193], v[206:209], v[52:55]
	v_mfma_f32_16x16x32_bf16 v[48:51], v[198:201], v[206:209], v[48:51]
	v_mfma_f32_16x16x32_bf16 v[36:39], v[190:193], v[214:217], v[36:39]
	v_mfma_f32_16x16x32_bf16 v[32:35], v[198:201], v[214:217], v[32:35]
	v_mfma_f32_16x16x32_bf16 v[20:23], v[190:193], v[222:225], v[20:23]
	v_mfma_f32_16x16x32_bf16 v[16:19], v[198:201], v[222:225], v[16:19]
	v_mfma_f32_16x16x32_bf16 v[4:7], v[190:193], v[230:233], v[4:7]
	v_mfma_f32_16x16x32_bf16 v[0:3], v[198:201], v[230:233], v[0:3]
	s_barrier
; #define PG8_STAGE(bufoff, gbase, voff) do { _Pragma("unroll") for (int _i = 0; _i < 2; ++_i) \
;         __builtin_amdgcn_global_load_lds((const unsigned*)((const char*)(gbase) + (voff)[_i]), (PG8_LAS unsigned*)(lds + (bufoff) + ldsw + _i * 8192), 16, 0, 0); } while (0)
; #define PG8_LDA(dst, b, h) do { _Pragma("unroll") for (int m = 0; m < 4; ++m) _Pragma("unroll") for (int k = 0; k < 2; ++k) dst[m][k] = *(const PG8_LAS bf16x8*)(lds + PG8_SA(b, h) + aoff + m * 2048 + k * 1024); } while (0)
; #define PG8_LDB(dst, b, h) do { _Pragma("unroll") for (int n = 0; n < 2; ++n) _Pragma("unroll") for (int k = 0; k < 2; ++k) dst[n][k] = *(const PG8_LAS bf16x8*)(lds + PG8_SB(b, h) + boff + n * 2048 + k * 1024); } while (0)
; #define PG8_MMA(ai, bj, At, Bt) do { __builtin_amdgcn_s_setprio(1); _Pragma("unroll") for (int m = 0; m < 4; ++m) _Pragma("unroll") for (int n = 0; n < 2; ++n) _Pragma("unroll") for (int k = 0; k < 2; ++k) \
;         acc[ai][bj][m][n] = __builtin_amdgcn_mfma_f32_16x16x32_bf16(Bt[n][k], At[m][k], acc[ai][bj][m][n], 0, 0, 0); __builtin_amdgcn_s_setprio(0); } while (0)
; #define PG8_WAIT_V(n) asm volatile("s_waitcnt vmcnt(" #n ")" ::: "memory")
; #define PG8_WAIT_L(n) asm volatile("s_waitcnt lgkmcnt(" #n ")" ::: "memory")
; #define PG8_BAR __builtin_amdgcn_s_barrier()
; #define PG8_SCHED __builtin_amdgcn_sched_barrier(0)
; template <class Epi, class Sched, bool ALIGN_EPI = false, bool SP2 = false>
; __device__ __forceinline__ void gemm_phase(PG8_LAS unsigned char* lds, const Gemm g, const Sched& S, const Epi& E, const int tid_arg) {
;     ...
;         for (int t = 0; t < nt; t += 2) {
;     ...
;             PG8_LDB(B0, 1, 0); PG8_LDB(B1, 1, 1); PG8_SCHED; PG8_LDA(At, 1, 0); PG8_STAGE(PG8_SA(0, 1), a2 + hstep, voffA);
;             PG8_WAIT_V(8); PG8_WAIT_L(0); PG8_BAR; PG8_MMA(0, 0, At, B0); PG8_MMA(0, 1, At, B1); PG8_BAR; PG8_SCHED;
;             PG8_LDA(At, 1, 1); PG8_STAGE(PG8_SB(1, 0), b3, voffB); PG8_STAGE(PG8_SB(1, 1), b3 + hstep, voffB); PG8_STAGE(PG8_SA(1, 0), a3, voffA);
;             PG8_WAIT_V(8); PG8_WAIT_L(0); PG8_BAR; PG8_MMA(1, 0, At, B0); PG8_MMA(1, 1, At, B1); PG8_BAR; PG8_SCHED;
	s_setprio 0
	s_add_u32 s42, s42, 0x40000
	s_addc_u32 s43, s43, 0
	s_mov_b32 m0, s51
	s_nop 0
	global_load_lds_dwordx4 v128, s[42:43]
	s_mov_b32 m0, s52
	s_nop 0
	global_load_lds_dwordx4 v132, s[42:43]
	ds_read_b128 v[170:173], v161
	ds_read_b128 v[174:177], v162
	ds_read_b128 v[178:181], v163
	ds_read_b128 v[182:185], v164
	ds_read_b128 v[186:189], v165
	ds_read_b128 v[190:193], v166
	ds_read_b128 v[194:197], v167
	ds_read_b128 v[198:201], v168
	ds_read_b128 v[202:205], v149 offset:32768
	ds_read_b128 v[206:209], v149 offset:33792
	ds_read_b128 v[210:213], v149 offset:34816
	ds_read_b128 v[214:217], v149 offset:35840
	ds_read_b128 v[218:221], v149 offset:36864
	ds_read_b128 v[222:225], v149 offset:37888
	ds_read_b128 v[226:229], v149 offset:38912
	ds_read_b128 v[230:233], v149 offset:39936
	s_waitcnt vmcnt(8)
	s_waitcnt lgkmcnt(0)
	s_setprio 1
	s_barrier
	v_mfma_f32_16x16x32_bf16 v[124:127], v[170:173], v[202:205], v[124:127]
	v_mfma_f32_16x16x32_bf16 v[120:123], v[178:181], v[202:205], v[120:123]
	v_mfma_f32_16x16x32_bf16 v[108:111], v[170:173], v[210:213], v[108:111]
	v_mfma_f32_16x16x32_bf16 v[104:107], v[178:181], v[210:213], v[104:107]
	v_mfma_f32_16x16x32_bf16 v[92:95], v[170:173], v[218:221], v[92:95]
	v_mfma_f32_16x16x32_bf16 v[88:91], v[178:181], v[218:221], v[88:91]
	v_mfma_f32_16x16x32_bf16 v[76:79], v[170:173], v[226:229], v[76:79]
	v_mfma_f32_16x16x32_bf16 v[72:75], v[178:181], v[226:229], v[72:75]
	v_mfma_f32_16x16x32_bf16 v[124:127], v[174:177], v[206:209], v[124:127]
	v_mfma_f32_16x16x32_bf16 v[120:123], v[182:185], v[206:209], v[120:123]
	v_mfma_f32_16x16x32_bf16 v[108:111], v[174:177], v[214:217], v[108:111]
	v_mfma_f32_16x16x32_bf16 v[104:107], v[182:185], v[214:217], v[104:107]
	v_mfma_f32_16x16x32_bf16 v[92:95], v[174:177], v[222:225], v[92:95]
	v_mfma_f32_16x16x32_bf16 v[88:91], v[182:185], v[222:225], v[88:91]
	v_mfma_f32_16x16x32_bf16 v[76:79], v[174:177], v[230:233], v[76:79]
	v_mfma_f32_16x16x32_bf16 v[72:75], v[182:185], v[230:233], v[72:75]
	s_setprio 0
	s_setprio 1
	v_mfma_f32_16x16x32_bf16 v[116:119], v[186:189], v[202:205], v[116:119]
	v_mfma_f32_16x16x32_bf16 v[112:115], v[194:197], v[202:205], v[112:115]
	v_mfma_f32_16x16x32_bf16 v[100:103], v[186:189], v[210:213], v[100:103]
	v_mfma_f32_16x16x32_bf16 v[96:99], v[194:197], v[210:213], v[96:99]
	v_mfma_f32_16x16x32_bf16 v[84:87], v[186:189], v[218:221], v[84:87]
	v_mfma_f32_16x16x32_bf16 v[80:83], v[194:197], v[218:221], v[80:83]
	v_mfma_f32_16x16x32_bf16 v[68:71], v[186:189], v[226:229], v[68:71]
	v_mfma_f32_16x16x32_bf16 v[64:67], v[194:197], v[226:229], v[64:67]
	v_mfma_f32_16x16x32_bf16 v[116:119], v[190:193], v[206:209], v[116:119]
	v_mfma_f32_16x16x32_bf16 v[112:115], v[198:201], v[206:209], v[112:115]
	v_mfma_f32_16x16x32_bf16 v[100:103], v[190:193], v[214:217], v[100:103]
	v_mfma_f32_16x16x32_bf16 v[96:99], v[198:201], v[214:217], v[96:99]
	v_mfma_f32_16x16x32_bf16 v[84:87], v[190:193], v[222:225], v[84:87]
	v_mfma_f32_16x16x32_bf16 v[80:83], v[198:201], v[222:225], v[80:83]
	v_mfma_f32_16x16x32_bf16 v[68:71], v[190:193], v[230:233], v[68:71]
	v_mfma_f32_16x16x32_bf16 v[64:67], v[198:201], v[230:233], v[64:67]
	s_barrier
	s_setprio 0
	s_mov_b32 m0, s54
	s_add_u32 s0, s0, 0x40080
	global_load_lds_dwordx4 v130, s[98:99]
	s_mov_b32 m0, s55
	s_addc_u32 s1, s1, 0
	global_load_lds_dwordx4 v134, s[98:99]
	s_mov_b32 m0, s58
	s_nop 0
	global_load_lds_dwordx4 v130, s[0:1]
	s_mov_b32 m0, s59
	s_nop 0
	global_load_lds_dwordx4 v134, s[0:1]
	s_mov_b32 m0, s56
	s_nop 0
	global_load_lds_dwordx4 v128, s[100:101]
	s_mov_b32 m0, s57
	s_nop 0
	global_load_lds_dwordx4 v132, s[100:101]
	ds_read_b128 v[202:205], v149 offset:49152
	ds_read_b128 v[206:209], v149 offset:50176
	ds_read_b128 v[210:213], v149 offset:51200
	ds_read_b128 v[214:217], v149 offset:52224
	ds_read_b128 v[218:221], v149 offset:53248
	ds_read_b128 v[222:225], v149 offset:54272
	ds_read_b128 v[226:229], v149 offset:55296
	ds_read_b128 v[230:233], v149 offset:56320
	s_waitcnt vmcnt(8)
	s_waitcnt lgkmcnt(0)
	s_setprio 1
	s_barrier
	v_mfma_f32_16x16x32_bf16 v[60:63], v[170:173], v[202:205], v[60:63]
	v_mfma_f32_16x16x32_bf16 v[56:59], v[178:181], v[202:205], v[56:59]
	v_mfma_f32_16x16x32_bf16 v[44:47], v[170:173], v[210:213], v[44:47]
	v_mfma_f32_16x16x32_bf16 v[40:43], v[178:181], v[210:213], v[40:43]
	v_mfma_f32_16x16x32_bf16 v[28:31], v[170:173], v[218:221], v[28:31]
	v_mfma_f32_16x16x32_bf16 v[24:27], v[178:181], v[218:221], v[24:27]
	v_mfma_f32_16x16x32_bf16 v[12:15], v[170:173], v[226:229], v[12:15]
	v_mfma_f32_16x16x32_bf16 v[8:11], v[178:181], v[226:229], v[8:11]
	v_mfma_f32_16x16x32_bf16 v[60:63], v[174:177], v[206:209], v[60:63]
	v_mfma_f32_16x16x32_bf16 v[56:59], v[182:185], v[206:209], v[56:59]
	v_mfma_f32_16x16x32_bf16 v[44:47], v[174:177], v[214:217], v[44:47]
	v_mfma_f32_16x16x32_bf16 v[40:43], v[182:185], v[214:217], v[40:43]
	v_mfma_f32_16x16x32_bf16 v[28:31], v[174:177], v[222:225], v[28:31]
	v_mfma_f32_16x16x32_bf16 v[24:27], v[182:185], v[222:225], v[24:27]
	v_mfma_f32_16x16x32_bf16 v[12:15], v[174:177], v[230:233], v[12:15]
	v_mfma_f32_16x16x32_bf16 v[8:11], v[182:185], v[230:233], v[8:11]
	s_setprio 0
	s_setprio 1
	v_mfma_f32_16x16x32_bf16 v[52:55], v[186:189], v[202:205], v[52:55]
	v_mfma_f32_16x16x32_bf16 v[48:51], v[194:197], v[202:205], v[48:51]
	v_mfma_f32_16x16x32_bf16 v[36:39], v[186:189], v[210:213], v[36:39]
	v_mfma_f32_16x16x32_bf16 v[32:35], v[194:197], v[210:213], v[32:35]
	v_mfma_f32_16x16x32_bf16 v[20:23], v[186:189], v[218:221], v[20:23]
	v_mfma_f32_16x16x32_bf16 v[16:19], v[194:197], v[218:221], v[16:19]
	v_mfma_f32_16x16x32_bf16 v[4:7], v[186:189], v[226:229], v[4:7]
	v_mfma_f32_16x16x32_bf16 v[0:3], v[194:197], v[226:229], v[0:3]
	v_mfma_f32_16x16x32_bf16 v[52:55], v[190:193], v[206:209], v[52:55]
	v_mfma_f32_16x16x32_bf16 v[48:51], v[198:201], v[206:209], v[48:51]
	v_mfma_f32_16x16x32_bf16 v[36:39], v[190:193], v[214:217], v[36:39]
	v_mfma_f32_16x16x32_bf16 v[32:35], v[198:201], v[214:217], v[32:35]
	v_mfma_f32_16x16x32_bf16 v[20:23], v[190:193], v[222:225], v[20:23]
	v_mfma_f32_16x16x32_bf16 v[16:19], v[198:201], v[222:225], v[16:19]
	v_mfma_f32_16x16x32_bf16 v[4:7], v[190:193], v[230:233], v[4:7]
	v_mfma_f32_16x16x32_bf16 v[0:3], v[198:201], v[230:233], v[0:3]
	s_barrier
	s_setprio 0
	s_add_i32 s72, s72, 2
	s_add_u32 s70, s70, 0x100
	s_addc_u32 s71, s71, 0
	s_add_u32 s40, s40, 0x100
	s_addc_u32 s41, s41, 0
	s_cmp_gt_u32 s72, 13
	s_cbranch_scc0 .LBB0_965
	s_and_b64 vcc, exec, s[14:15]
	s_cbranch_vccz .LBB0_968
	s_barrier

; #define PG8_STAGE(bufoff, gbase, voff) do { _Pragma("unroll") for (int _i = 0; _i < 2; ++_i) \
;         __builtin_amdgcn_global_load_lds((const unsigned*)((const char*)(gbase) + (voff)[_i]), (PG8_LAS unsigned*)(lds + (bufoff) + ldsw + _i * 8192), 16, 0, 0); } while (0)
; #define PG8_LDA(dst, b, h) do { _Pragma("unroll") for (int m = 0; m < 4; ++m) _Pragma("unroll") for (int k = 0; k < 2; ++k) dst[m][k] = *(const PG8_LAS bf16x8*)(lds + PG8_SA(b, h) + aoff + m * 2048 + k * 1024); } while (0)
; #define PG8_LDB(dst, b, h) do { _Pragma("unroll") for (int n = 0; n < 2; ++n) _Pragma("unroll") for (int k = 0; k < 2; ++k) dst[n][k] = *(const PG8_LAS bf16x8*)(lds + PG8_SB(b, h) + boff + n * 2048 + k * 1024); } while (0)
; #define PG8_MMA(ai, bj, At, Bt) do { __builtin_amdgcn_s_setprio(1); _Pragma("unroll") for (int m = 0; m < 4; ++m) _Pragma("unroll") for (int n = 0; n < 2; ++n) _Pragma("unroll") for (int k = 0; k < 2; ++k) \
;         acc[ai][bj][m][n] = __builtin_amdgcn_mfma_f32_16x16x32_bf16(Bt[n][k], At[m][k], acc[ai][bj][m][n], 0, 0, 0); __builtin_amdgcn_s_setprio(0); } while (0)
; #define PG8_WAIT_V(n) asm volatile("s_waitcnt vmcnt(" #n ")" ::: "memory")
; #define PG8_BAR __builtin_amdgcn_s_barrier()
; template <class Epi, class Sched, bool ALIGN_EPI = false, bool SP2 = false>
; __device__ __forceinline__ void gemm_phase(PG8_LAS unsigned char* lds, const Gemm g, const Sched& S, const Epi& E, const int tid_arg) {
;     ...
;         for (int t = 0; t < nt; t += 2) {
;             const bool last = (t == nt - 2);
;             const char* a1 = cA + (size_t)(t + 1) * kstep;
;             const char* a2 = last ? nA : cA + (size_t)(t + 2) * kstep; const char* b2 = last ? nB : cB + (size_t)(t + 2) * kstep;
;             const char* a3 = a2 + kstep; const char* b3 = b2 + kstep;
;             if (last && has_next) S.a_ready(nxt);
;             if constexpr (SP2) {
;             PG8_LDB(B0, 0, 0); PG8_LDB(B1, 0, 1); PG8_SCHED; PG8_LDA(At, 0, 0); PG8_STAGE(PG8_SA(1, 1), a1 + hstep, voffA);
;             PG8_WAIT_V(8); PG8_WAIT_L(0); PG8_BAR; PG8_MMA(0, 0, At, B0); PG8_MMA(0, 1, At, B1); PG8_BAR; PG8_SCHED;
;             PG8_LDA(At, 0, 1); PG8_STAGE(PG8_SB(0, 0), b2, voffB); PG8_STAGE(PG8_SB(0, 1), b2 + hstep, voffB); PG8_STAGE(PG8_SA(0, 0), a2, voffA);
;             PG8_WAIT_V(8); PG8_WAIT_L(0); PG8_BAR; PG8_MMA(1, 0, At, B0); PG8_MMA(1, 1, At, B1); PG8_BAR; PG8_SCHED;
.LBB0_1046:
	s_add_i32 s30, s0, 2
	s_add_u32 s31, s4, 0x80
	s_addc_u32 s1, s5, 0
	s_cmp_eq_u32 s52, s0
	s_cselect_b32 s0, s14, s31
	s_cselect_b32 s1, s15, s1
	s_cselect_b32 s63, s29, s61
	s_cselect_b32 s62, s28, s60
	s_mov_b32 m0, s53
	s_nop 0
	global_load_lds_dwordx4 v138, s[4:5]
	s_mov_b32 m0, s54
	s_nop 0
	global_load_lds_dwordx4 v136, s[4:5]
	ds_read_b128 v[144:147], v151
	ds_read_b128 v[168:171], v152
	ds_read_b128 v[172:175], v153
	ds_read_b128 v[176:179], v154
	ds_read_b128 v[180:183], v155
	ds_read_b128 v[184:187], v156
	ds_read_b128 v[188:191], v157
	ds_read_b128 v[192:195], v158
	ds_read_b128 v[196:199], v150
	ds_read_b128 v[200:203], v150 offset:1024
	ds_read_b128 v[204:207], v150 offset:2048
	ds_read_b128 v[208:211], v150 offset:3072
	ds_read_b128 v[212:215], v150 offset:4096
	ds_read_b128 v[216:219], v150 offset:5120
	ds_read_b128 v[220:223], v150 offset:6144
	ds_read_b128 v[224:227], v150 offset:7168
	s_waitcnt vmcnt(8)
	s_waitcnt lgkmcnt(0)
	s_setprio 1
	s_barrier
	v_mfma_f32_16x16x32_bf16 v[124:127], v[144:147], v[196:199], v[124:127]
	v_mfma_f32_16x16x32_bf16 v[120:123], v[172:175], v[196:199], v[120:123]
	v_mfma_f32_16x16x32_bf16 v[108:111], v[144:147], v[204:207], v[108:111]
	v_mfma_f32_16x16x32_bf16 v[104:107], v[172:175], v[204:207], v[104:107]
	v_mfma_f32_16x16x32_bf16 v[92:95], v[144:147], v[212:215], v[92:95]
	v_mfma_f32_16x16x32_bf16 v[88:91], v[172:175], v[212:215], v[88:91]
	v_mfma_f32_16x16x32_bf16 v[76:79], v[144:147], v[220:223], v[76:79]
	v_mfma_f32_16x16x32_bf16 v[72:75], v[172:175], v[220:223], v[72:75]
	v_mfma_f32_16x16x32_bf16 v[124:127], v[168:171], v[200:203], v[124:127]
	v_mfma_f32_16x16x32_bf16 v[120:123], v[176:179], v[200:203], v[120:123]
	v_mfma_f32_16x16x32_bf16 v[108:111], v[168:171], v[208:211], v[108:111]
	v_mfma_f32_16x16x32_bf16 v[104:107], v[176:179], v[208:211], v[104:107]
	v_mfma_f32_16x16x32_bf16 v[92:95], v[168:171], v[216:219], v[92:95]
	v_mfma_f32_16x16x32_bf16 v[88:91], v[176:179], v[216:219], v[88:91]
	v_mfma_f32_16x16x32_bf16 v[76:79], v[168:171], v[224:227], v[76:79]
	v_mfma_f32_16x16x32_bf16 v[72:75], v[176:179], v[224:227], v[72:75]
	s_setprio 0
	s_setprio 1
	v_mfma_f32_16x16x32_bf16 v[116:119], v[180:183], v[196:199], v[116:119]
	v_mfma_f32_16x16x32_bf16 v[112:115], v[188:191], v[196:199], v[112:115]
	v_mfma_f32_16x16x32_bf16 v[100:103], v[180:183], v[204:207], v[100:103]
	v_mfma_f32_16x16x32_bf16 v[96:99], v[188:191], v[204:207], v[96:99]
	v_mfma_f32_16x16x32_bf16 v[84:87], v[180:183], v[212:215], v[84:87]
	v_mfma_f32_16x16x32_bf16 v[80:83], v[188:191], v[212:215], v[80:83]
	v_mfma_f32_16x16x32_bf16 v[68:71], v[180:183], v[220:223], v[68:71]
	v_mfma_f32_16x16x32_bf16 v[64:67], v[188:191], v[220:223], v[64:67]
	v_mfma_f32_16x16x32_bf16 v[116:119], v[184:187], v[200:203], v[116:119]
	v_mfma_f32_16x16x32_bf16 v[112:115], v[192:195], v[200:203], v[112:115]
	v_mfma_f32_16x16x32_bf16 v[100:103], v[184:187], v[208:211], v[100:103]
	v_mfma_f32_16x16x32_bf16 v[96:99], v[192:195], v[208:211], v[96:99]
	v_mfma_f32_16x16x32_bf16 v[84:87], v[184:187], v[216:219], v[84:87]
	v_mfma_f32_16x16x32_bf16 v[80:83], v[192:195], v[216:219], v[80:83]
	v_mfma_f32_16x16x32_bf16 v[68:71], v[184:187], v[224:227], v[68:71]
	v_mfma_f32_16x16x32_bf16 v[64:67], v[192:195], v[224:227], v[64:67]
	s_barrier
	s_setprio 0
	s_mov_b32 m0, s37
	s_add_u32 s98, s62, s22
	s_addc_u32 s99, s63, s23
	v_lshl_add_u64 v[228:229], s[62:63], 0, v[130:131]
	v_lshl_add_u64 v[230:231], s[62:63], 0, v[134:135]
	s_add_u32 s62, s62, s6
	global_load_lds_dwordx4 v[228:229], off
	s_mov_b32 m0, s38
	s_addc_u32 s63, s63, s7
	global_load_lds_dwordx4 v[230:231], off
	s_add_u32 s100, s62, s22
	s_addc_u32 s101, s63, s23
	s_mov_b32 m0, s39
	s_nop 0
	global_load_lds_dwordx4 v130, s[62:63]
	s_mov_b32 m0, s40
	v_lshl_add_u64 v[236:237], s[0:1], 0, v[128:129]
	global_load_lds_dwordx4 v134, s[62:63]
	s_mov_b32 m0, s36
	v_lshl_add_u64 v[238:239], s[0:1], 0, v[132:133]
	global_load_lds_dwordx4 v128, s[0:1]
	s_mov_b32 m0, s41
	s_nop 0
	global_load_lds_dwordx4 v132, s[0:1]
	ds_read_b128 v[196:199], v150 offset:16384
	ds_read_b128 v[200:203], v150 offset:17408
	ds_read_b128 v[204:207], v150 offset:18432
	ds_read_b128 v[208:211], v150 offset:19456
	ds_read_b128 v[212:215], v150 offset:20480
	ds_read_b128 v[216:219], v150 offset:21504
	ds_read_b128 v[220:223], v150 offset:22528
	ds_read_b128 v[224:227], v150 offset:23552
	s_waitcnt vmcnt(8)
	s_waitcnt lgkmcnt(0)
	s_setprio 1
	s_barrier
	v_mfma_f32_16x16x32_bf16 v[60:63], v[144:147], v[196:199], v[60:63]
	v_mfma_f32_16x16x32_bf16 v[56:59], v[172:175], v[196:199], v[56:59]
	v_mfma_f32_16x16x32_bf16 v[44:47], v[144:147], v[204:207], v[44:47]
	v_mfma_f32_16x16x32_bf16 v[40:43], v[172:175], v[204:207], v[40:43]
	v_mfma_f32_16x16x32_bf16 v[28:31], v[144:147], v[212:215], v[28:31]
	v_mfma_f32_16x16x32_bf16 v[24:27], v[172:175], v[212:215], v[24:27]
	v_mfma_f32_16x16x32_bf16 v[12:15], v[144:147], v[220:223], v[12:15]
	v_mfma_f32_16x16x32_bf16 v[8:11], v[172:175], v[220:223], v[8:11]
	v_mfma_f32_16x16x32_bf16 v[60:63], v[168:171], v[200:203], v[60:63]
	v_mfma_f32_16x16x32_bf16 v[56:59], v[176:179], v[200:203], v[56:59]
	v_mfma_f32_16x16x32_bf16 v[44:47], v[168:171], v[208:211], v[44:47]
	v_mfma_f32_16x16x32_bf16 v[40:43], v[176:179], v[208:211], v[40:43]
	v_mfma_f32_16x16x32_bf16 v[28:31], v[168:171], v[216:219], v[28:31]
	v_mfma_f32_16x16x32_bf16 v[24:27], v[176:179], v[216:219], v[24:27]
	v_mfma_f32_16x16x32_bf16 v[12:15], v[168:171], v[224:227], v[12:15]
	v_mfma_f32_16x16x32_bf16 v[8:11], v[176:179], v[224:227], v[8:11]
	s_setprio 0
	s_setprio 1
	v_mfma_f32_16x16x32_bf16 v[52:55], v[180:183], v[196:199], v[52:55]
	v_mfma_f32_16x16x32_bf16 v[48:51], v[188:191], v[196:199], v[48:51]
	v_mfma_f32_16x16x32_bf16 v[36:39], v[180:183], v[204:207], v[36:39]
	v_mfma_f32_16x16x32_bf16 v[32:35], v[188:191], v[204:207], v[32:35]
	v_mfma_f32_16x16x32_bf16 v[20:23], v[180:183], v[212:215], v[20:23]
	v_mfma_f32_16x16x32_bf16 v[16:19], v[188:191], v[212:215], v[16:19]
	v_mfma_f32_16x16x32_bf16 v[4:7], v[180:183], v[220:223], v[4:7]
	v_mfma_f32_16x16x32_bf16 v[0:3], v[188:191], v[220:223], v[0:3]
	v_mfma_f32_16x16x32_bf16 v[52:55], v[184:187], v[200:203], v[52:55]
	v_mfma_f32_16x16x32_bf16 v[48:51], v[192:195], v[200:203], v[48:51]
	v_mfma_f32_16x16x32_bf16 v[36:39], v[184:187], v[208:211], v[36:39]
	v_mfma_f32_16x16x32_bf16 v[32:35], v[192:195], v[208:211], v[32:35]
	v_mfma_f32_16x16x32_bf16 v[20:23], v[184:187], v[216:219], v[20:23]
	v_mfma_f32_16x16x32_bf16 v[16:19], v[192:195], v[216:219], v[16:19]
	v_mfma_f32_16x16x32_bf16 v[4:7], v[184:187], v[224:227], v[4:7]
	v_mfma_f32_16x16x32_bf16 v[0:3], v[192:195], v[224:227], v[0:3]
	s_barrier
; #define PG8_STAGE(bufoff, gbase, voff) do { _Pragma("unroll") for (int _i = 0; _i < 2; ++_i) \
;         __builtin_amdgcn_global_load_lds((const unsigned*)((const char*)(gbase) + (voff)[_i]), (PG8_LAS unsigned*)(lds + (bufoff) + ldsw + _i * 8192), 16, 0, 0); } while (0)
; #define PG8_LDA(dst, b, h) do { _Pragma("unroll") for (int m = 0; m < 4; ++m) _Pragma("unroll") for (int k = 0; k < 2; ++k) dst[m][k] = *(const PG8_LAS bf16x8*)(lds + PG8_SA(b, h) + aoff + m * 2048 + k * 1024); } while (0)
; #define PG8_LDB(dst, b, h) do { _Pragma("unroll") for (int n = 0; n < 2; ++n) _Pragma("unroll") for (int k = 0; k < 2; ++k) dst[n][k] = *(const PG8_LAS bf16x8*)(lds + PG8_SB(b, h) + boff + n * 2048 + k * 1024); } while (0)
; #define PG8_MMA(ai, bj, At, Bt) do { __builtin_amdgcn_s_setprio(1); _Pragma("unroll") for (int m = 0; m < 4; ++m) _Pragma("unroll") for (int n = 0; n < 2; ++n) _Pragma("unroll") for (int k = 0; k < 2; ++k) \
;         acc[ai][bj][m][n] = __builtin_amdgcn_mfma_f32_16x16x32_bf16(Bt[n][k], At[m][k], acc[ai][bj][m][n], 0, 0, 0); __builtin_amdgcn_s_setprio(0); } while (0)
; #define PG8_WAIT_V(n) asm volatile("s_waitcnt vmcnt(" #n ")" ::: "memory")
; #define PG8_WAIT_L(n) asm volatile("s_waitcnt lgkmcnt(" #n ")" ::: "memory")
; #define PG8_BAR __builtin_amdgcn_s_barrier()
; #define PG8_SCHED __builtin_amdgcn_sched_barrier(0)
; template <class Epi, class Sched, bool ALIGN_EPI = false, bool SP2 = false>
; __device__ __forceinline__ void gemm_phase(PG8_LAS unsigned char* lds, const Gemm g, const Sched& S, const Epi& E, const int tid_arg) {
;     ...
;         for (int t = 0; t < nt; t += 2) {
;     ...
;             PG8_LDB(B0, 1, 0); PG8_LDB(B1, 1, 1); PG8_SCHED; PG8_LDA(At, 1, 0); PG8_STAGE(PG8_SA(0, 1), a2 + hstep, voffA);
;             PG8_WAIT_V(8); PG8_WAIT_L(0); PG8_BAR; PG8_MMA(0, 0, At, B0); PG8_MMA(0, 1, At, B1); PG8_BAR; PG8_SCHED;
;             PG8_LDA(At, 1, 1); PG8_STAGE(PG8_SB(1, 0), b3, voffB); PG8_STAGE(PG8_SB(1, 1), b3 + hstep, voffB); PG8_STAGE(PG8_SA(1, 0), a3, voffA);
;             PG8_WAIT_V(8); PG8_WAIT_L(0); PG8_BAR; PG8_MMA(1, 0, At, B0); PG8_MMA(1, 1, At, B1); PG8_BAR; PG8_SCHED;
	s_setprio 0
	s_add_u32 s0, s0, s6
	s_addc_u32 s1, s1, s7
	s_mov_b32 m0, s42
	s_nop 0
	global_load_lds_dwordx4 v128, s[0:1]
	s_mov_b32 m0, s43
	s_nop 0
	global_load_lds_dwordx4 v132, s[0:1]
	ds_read_b128 v[144:147], v159
	ds_read_b128 v[168:171], v160
	ds_read_b128 v[172:175], v161
	ds_read_b128 v[176:179], v162
	ds_read_b128 v[180:183], v163
	ds_read_b128 v[184:187], v164
	ds_read_b128 v[188:191], v165
	ds_read_b128 v[192:195], v166
	ds_read_b128 v[196:199], v150 offset:32768
	ds_read_b128 v[200:203], v150 offset:33792
	ds_read_b128 v[204:207], v150 offset:34816
	ds_read_b128 v[208:211], v150 offset:35840
	ds_read_b128 v[212:215], v150 offset:36864
	ds_read_b128 v[216:219], v150 offset:37888
	ds_read_b128 v[220:223], v150 offset:38912
	ds_read_b128 v[224:227], v150 offset:39936
	s_waitcnt vmcnt(8)
	s_waitcnt lgkmcnt(0)
	s_setprio 1
	s_barrier
	v_mfma_f32_16x16x32_bf16 v[124:127], v[144:147], v[196:199], v[124:127]
	v_mfma_f32_16x16x32_bf16 v[120:123], v[172:175], v[196:199], v[120:123]
	v_mfma_f32_16x16x32_bf16 v[108:111], v[144:147], v[204:207], v[108:111]
	v_mfma_f32_16x16x32_bf16 v[104:107], v[172:175], v[204:207], v[104:107]
	v_mfma_f32_16x16x32_bf16 v[92:95], v[144:147], v[212:215], v[92:95]
	v_mfma_f32_16x16x32_bf16 v[88:91], v[172:175], v[212:215], v[88:91]
	v_mfma_f32_16x16x32_bf16 v[76:79], v[144:147], v[220:223], v[76:79]
	v_mfma_f32_16x16x32_bf16 v[72:75], v[172:175], v[220:223], v[72:75]
	v_mfma_f32_16x16x32_bf16 v[124:127], v[168:171], v[200:203], v[124:127]
	v_mfma_f32_16x16x32_bf16 v[120:123], v[176:179], v[200:203], v[120:123]
	v_mfma_f32_16x16x32_bf16 v[108:111], v[168:171], v[208:211], v[108:111]
	v_mfma_f32_16x16x32_bf16 v[104:107], v[176:179], v[208:211], v[104:107]
	v_mfma_f32_16x16x32_bf16 v[92:95], v[168:171], v[216:219], v[92:95]
	v_mfma_f32_16x16x32_bf16 v[88:91], v[176:179], v[216:219], v[88:91]
	v_mfma_f32_16x16x32_bf16 v[76:79], v[168:171], v[224:227], v[76:79]
	v_mfma_f32_16x16x32_bf16 v[72:75], v[176:179], v[224:227], v[72:75]
	s_setprio 0
	s_setprio 1
	v_mfma_f32_16x16x32_bf16 v[116:119], v[180:183], v[196:199], v[116:119]
	v_mfma_f32_16x16x32_bf16 v[112:115], v[188:191], v[196:199], v[112:115]
	v_mfma_f32_16x16x32_bf16 v[100:103], v[180:183], v[204:207], v[100:103]
	v_mfma_f32_16x16x32_bf16 v[96:99], v[188:191], v[204:207], v[96:99]
	v_mfma_f32_16x16x32_bf16 v[84:87], v[180:183], v[212:215], v[84:87]
	v_mfma_f32_16x16x32_bf16 v[80:83], v[188:191], v[212:215], v[80:83]
	v_mfma_f32_16x16x32_bf16 v[68:71], v[180:183], v[220:223], v[68:71]
	v_mfma_f32_16x16x32_bf16 v[64:67], v[188:191], v[220:223], v[64:67]
	v_mfma_f32_16x16x32_bf16 v[116:119], v[184:187], v[200:203], v[116:119]
	v_mfma_f32_16x16x32_bf16 v[112:115], v[192:195], v[200:203], v[112:115]
	v_mfma_f32_16x16x32_bf16 v[100:103], v[184:187], v[208:211], v[100:103]
	v_mfma_f32_16x16x32_bf16 v[96:99], v[192:195], v[208:211], v[96:99]
	v_mfma_f32_16x16x32_bf16 v[84:87], v[184:187], v[216:219], v[84:87]
	v_mfma_f32_16x16x32_bf16 v[80:83], v[192:195], v[216:219], v[80:83]
	v_mfma_f32_16x16x32_bf16 v[68:71], v[184:187], v[224:227], v[68:71]
	v_mfma_f32_16x16x32_bf16 v[64:67], v[192:195], v[224:227], v[64:67]
	s_barrier
	s_setprio 0
	s_mov_b32 m0, s44
	s_nop 0
	global_load_lds_dwordx4 v130, s[98:99]
	s_mov_b32 m0, s45
	s_nop 0
	global_load_lds_dwordx4 v134, s[98:99]
	s_mov_b32 m0, s48
	s_nop 0
	global_load_lds_dwordx4 v130, s[100:101]
	s_mov_b32 m0, s49
	s_nop 0
	global_load_lds_dwordx4 v134, s[100:101]
	v_lshl_add_u64 v[228:229], v[236:237], 0, s[22:23]
	s_mov_b32 m0, s46
	s_nop 0
	global_load_lds_dwordx4 v[228:229], off
	v_lshl_add_u64 v[228:229], v[238:239], 0, s[22:23]
	s_mov_b32 m0, s47
	s_nop 0
	global_load_lds_dwordx4 v[228:229], off
	ds_read_b128 v[196:199], v150 offset:49152
	ds_read_b128 v[200:203], v150 offset:50176
	ds_read_b128 v[204:207], v150 offset:51200
	ds_read_b128 v[208:211], v150 offset:52224
	ds_read_b128 v[212:215], v150 offset:53248
	ds_read_b128 v[216:219], v150 offset:54272
	ds_read_b128 v[220:223], v150 offset:55296
	ds_read_b128 v[224:227], v150 offset:56320
	s_waitcnt vmcnt(8)
	s_waitcnt lgkmcnt(0)
	s_setprio 1
	s_barrier
	v_mfma_f32_16x16x32_bf16 v[60:63], v[144:147], v[196:199], v[60:63]
	v_mfma_f32_16x16x32_bf16 v[56:59], v[172:175], v[196:199], v[56:59]
	v_mfma_f32_16x16x32_bf16 v[44:47], v[144:147], v[204:207], v[44:47]
	v_mfma_f32_16x16x32_bf16 v[40:43], v[172:175], v[204:207], v[40:43]
	v_mfma_f32_16x16x32_bf16 v[28:31], v[144:147], v[212:215], v[28:31]
	v_mfma_f32_16x16x32_bf16 v[24:27], v[172:175], v[212:215], v[24:27]
	v_mfma_f32_16x16x32_bf16 v[12:15], v[144:147], v[220:223], v[12:15]
	v_mfma_f32_16x16x32_bf16 v[8:11], v[172:175], v[220:223], v[8:11]
	v_mfma_f32_16x16x32_bf16 v[60:63], v[168:171], v[200:203], v[60:63]
	v_mfma_f32_16x16x32_bf16 v[56:59], v[176:179], v[200:203], v[56:59]
	v_mfma_f32_16x16x32_bf16 v[44:47], v[168:171], v[208:211], v[44:47]
	v_mfma_f32_16x16x32_bf16 v[40:43], v[176:179], v[208:211], v[40:43]
	v_mfma_f32_16x16x32_bf16 v[28:31], v[168:171], v[216:219], v[28:31]
	v_mfma_f32_16x16x32_bf16 v[24:27], v[176:179], v[216:219], v[24:27]
	v_mfma_f32_16x16x32_bf16 v[12:15], v[168:171], v[224:227], v[12:15]
	v_mfma_f32_16x16x32_bf16 v[8:11], v[176:179], v[224:227], v[8:11]
	s_setprio 0
	s_setprio 1
	v_mfma_f32_16x16x32_bf16 v[52:55], v[180:183], v[196:199], v[52:55]
	v_mfma_f32_16x16x32_bf16 v[48:51], v[188:191], v[196:199], v[48:51]
	v_mfma_f32_16x16x32_bf16 v[36:39], v[180:183], v[204:207], v[36:39]
	v_mfma_f32_16x16x32_bf16 v[32:35], v[188:191], v[204:207], v[32:35]
	v_mfma_f32_16x16x32_bf16 v[20:23], v[180:183], v[212:215], v[20:23]
	v_mfma_f32_16x16x32_bf16 v[16:19], v[188:191], v[212:215], v[16:19]
	v_mfma_f32_16x16x32_bf16 v[4:7], v[180:183], v[220:223], v[4:7]
	v_mfma_f32_16x16x32_bf16 v[0:3], v[188:191], v[220:223], v[0:3]
	v_mfma_f32_16x16x32_bf16 v[52:55], v[184:187], v[200:203], v[52:55]
	v_mfma_f32_16x16x32_bf16 v[48:51], v[192:195], v[200:203], v[48:51]
	v_mfma_f32_16x16x32_bf16 v[36:39], v[184:187], v[208:211], v[36:39]
	v_mfma_f32_16x16x32_bf16 v[32:35], v[192:195], v[208:211], v[32:35]
	v_mfma_f32_16x16x32_bf16 v[20:23], v[184:187], v[216:219], v[20:23]
	v_mfma_f32_16x16x32_bf16 v[16:19], v[192:195], v[216:219], v[16:19]
	v_mfma_f32_16x16x32_bf16 v[4:7], v[184:187], v[224:227], v[4:7]
	v_mfma_f32_16x16x32_bf16 v[0:3], v[192:195], v[224:227], v[0:3]
	s_barrier
	s_setprio 0
	s_add_u32 s60, s60, 0x100
	s_addc_u32 s61, s61, 0
	s_add_u32 s4, s4, 0x100
	s_addc_u32 s5, s5, 0
	s_cmp_ge_i32 s30, s50
	s_mov_b32 s0, s30
	s_cbranch_scc0 .LBB0_1046

; #define PG8_STAGE(bufoff, gbase, voff) do { _Pragma("unroll") for (int _i = 0; _i < 2; ++_i) \
;         __builtin_amdgcn_global_load_lds((const unsigned*)((const char*)(gbase) + (voff)[_i]), (PG8_LAS unsigned*)(lds + (bufoff) + ldsw + _i * 8192), 16, 0, 0); } while (0)
; #define PG8_LDA(dst, b, h) do { _Pragma("unroll") for (int m = 0; m < 4; ++m) _Pragma("unroll") for (int k = 0; k < 2; ++k) dst[m][k] = *(const PG8_LAS bf16x8*)(lds + PG8_SA(b, h) + aoff + m * 2048 + k * 1024); } while (0)
; #define PG8_LDB(dst, b, h) do { _Pragma("unroll") for (int n = 0; n < 2; ++n) _Pragma("unroll") for (int k = 0; k < 2; ++k) dst[n][k] = *(const PG8_LAS bf16x8*)(lds + PG8_SB(b, h) + boff + n * 2048 + k * 1024); } while (0)
; #define PG8_MMA(ai, bj, At, Bt) do { __builtin_amdgcn_s_setprio(1); _Pragma("unroll") for (int m = 0; m < 4; ++m) _Pragma("unroll") for (int n = 0; n < 2; ++n) _Pragma("unroll") for (int k = 0; k < 2; ++k) \
;         acc[ai][bj][m][n] = __builtin_amdgcn_mfma_f32_16x16x32_bf16(Bt[n][k], At[m][k], acc[ai][bj][m][n], 0, 0, 0); __builtin_amdgcn_s_setprio(0); } while (0)
; #define PG8_WAIT_V(n) asm volatile("s_waitcnt vmcnt(" #n ")" ::: "memory")
; #define PG8_WAIT_L(n) asm volatile("s_waitcnt lgkmcnt(" #n ")" ::: "memory")
; template <class Epi, class Sched, bool ALIGN_EPI = false, bool SP2 = false>
; __device__ __forceinline__ void gemm_phase(PG8_LAS unsigned char* lds, const Gemm g, const Sched& S, const Epi& E, const int tid_arg) {
;     ...
;             const bool last = (t == nt - 2);
;             const char* a1 = cA + (size_t)(t + 1) * kstep;
;             const char* a2 = last ? nA : cA + (size_t)(t + 2) * kstep; const char* b2 = last ? nB : cB + (size_t)(t + 2) * kstep;
;             const char* a3 = a2 + kstep; const char* b3 = b2 + kstep;
;             if (last && has_next) S.a_ready(nxt);
;             if constexpr (SP2) {
;             PG8_LDB(B0, 0, 0); PG8_LDB(B1, 0, 1); PG8_SCHED; PG8_LDA(At, 0, 0); PG8_STAGE(PG8_SA(1, 1), a1 + hstep, voffA);
;             PG8_WAIT_V(8); PG8_WAIT_L(0); PG8_BAR; PG8_MMA(0, 0, At, B0); PG8_MMA(0, 1, At, B1); PG8_BAR; PG8_SCHED;
;             PG8_LDA(At, 0, 1); PG8_STAGE(PG8_SB(0, 0), b2, voffB); PG8_STAGE(PG8_SB(0, 1), b2 + hstep, voffB); PG8_STAGE(PG8_SA(0, 0), a2, voffA);
;             PG8_WAIT_V(8); PG8_WAIT_L(0); PG8_BAR; PG8_MMA(1, 0, At, B0); PG8_MMA(1, 1, At, B1); PG8_BAR; PG8_SCHED;
.LBB0_1179:
	s_add_u32 s0, s4, 0xfffc0080
	s_addc_u32 s1, s5, -1
	s_cmp_eq_u32 s68, 12
	s_cselect_b32 s11, s25, s1
	s_cselect_b32 s10, s36, s0
	s_cselect_b32 s1, s23, s67
	s_cselect_b32 s0, s37, s66
	s_mov_b32 m0, s55
	s_nop 0
	global_load_lds_dwordx4 v138, s[4:5]
	s_mov_b32 m0, s56
	s_nop 0
	global_load_lds_dwordx4 v136, s[4:5]
	ds_read_b128 v[144:147], v166
	ds_read_b128 v[148:151], v167
	ds_read_b128 v[152:155], v168
	ds_read_b128 v[156:159], v169
	ds_read_b128 v[184:187], v170
	ds_read_b128 v[188:191], v171
	ds_read_b128 v[192:195], v172
	ds_read_b128 v[196:199], v173
	ds_read_b128 v[200:203], v165
	ds_read_b128 v[204:207], v165 offset:1024
	ds_read_b128 v[208:211], v165 offset:2048
	ds_read_b128 v[212:215], v165 offset:3072
	ds_read_b128 v[216:219], v165 offset:4096
	ds_read_b128 v[220:223], v165 offset:5120
	ds_read_b128 v[224:227], v165 offset:6144
	ds_read_b128 v[228:231], v165 offset:7168
	s_waitcnt vmcnt(8)
	s_waitcnt lgkmcnt(0)
	s_setprio 1
	s_barrier
	v_mfma_f32_16x16x32_bf16 v[124:127], v[144:147], v[200:203], v[124:127]
	v_mfma_f32_16x16x32_bf16 v[120:123], v[152:155], v[200:203], v[120:123]
	v_mfma_f32_16x16x32_bf16 v[108:111], v[144:147], v[208:211], v[108:111]
	v_mfma_f32_16x16x32_bf16 v[104:107], v[152:155], v[208:211], v[104:107]
	v_mfma_f32_16x16x32_bf16 v[92:95], v[144:147], v[216:219], v[92:95]
	v_mfma_f32_16x16x32_bf16 v[88:91], v[152:155], v[216:219], v[88:91]
	v_mfma_f32_16x16x32_bf16 v[76:79], v[144:147], v[224:227], v[76:79]
	v_mfma_f32_16x16x32_bf16 v[72:75], v[152:155], v[224:227], v[72:75]
	v_mfma_f32_16x16x32_bf16 v[124:127], v[148:151], v[204:207], v[124:127]
	v_mfma_f32_16x16x32_bf16 v[120:123], v[156:159], v[204:207], v[120:123]
	v_mfma_f32_16x16x32_bf16 v[108:111], v[148:151], v[212:215], v[108:111]
	v_mfma_f32_16x16x32_bf16 v[104:107], v[156:159], v[212:215], v[104:107]
	v_mfma_f32_16x16x32_bf16 v[92:95], v[148:151], v[220:223], v[92:95]
	v_mfma_f32_16x16x32_bf16 v[88:91], v[156:159], v[220:223], v[88:91]
	v_mfma_f32_16x16x32_bf16 v[76:79], v[148:151], v[228:231], v[76:79]
	v_mfma_f32_16x16x32_bf16 v[72:75], v[156:159], v[228:231], v[72:75]
	s_setprio 0
	s_setprio 1
	v_mfma_f32_16x16x32_bf16 v[116:119], v[184:187], v[200:203], v[116:119]
	v_mfma_f32_16x16x32_bf16 v[112:115], v[192:195], v[200:203], v[112:115]
	v_mfma_f32_16x16x32_bf16 v[100:103], v[184:187], v[208:211], v[100:103]
	v_mfma_f32_16x16x32_bf16 v[96:99], v[192:195], v[208:211], v[96:99]
	v_mfma_f32_16x16x32_bf16 v[84:87], v[184:187], v[216:219], v[84:87]
	v_mfma_f32_16x16x32_bf16 v[80:83], v[192:195], v[216:219], v[80:83]
	v_mfma_f32_16x16x32_bf16 v[68:71], v[184:187], v[224:227], v[68:71]
	v_mfma_f32_16x16x32_bf16 v[64:67], v[192:195], v[224:227], v[64:67]
	v_mfma_f32_16x16x32_bf16 v[116:119], v[188:191], v[204:207], v[116:119]
	v_mfma_f32_16x16x32_bf16 v[112:115], v[196:199], v[204:207], v[112:115]
	v_mfma_f32_16x16x32_bf16 v[100:103], v[188:191], v[212:215], v[100:103]
	v_mfma_f32_16x16x32_bf16 v[96:99], v[196:199], v[212:215], v[96:99]
	v_mfma_f32_16x16x32_bf16 v[84:87], v[188:191], v[220:223], v[84:87]
	v_mfma_f32_16x16x32_bf16 v[80:83], v[196:199], v[220:223], v[80:83]
	v_mfma_f32_16x16x32_bf16 v[68:71], v[188:191], v[228:231], v[68:71]
	v_mfma_f32_16x16x32_bf16 v[64:67], v[196:199], v[228:231], v[64:67]
	s_barrier
	s_setprio 0
	s_mov_b32 m0, s31
	s_add_u32 s98, s0, s16
	s_addc_u32 s99, s1, s17
	s_add_u32 s70, s0, 0x40000
	global_load_lds_dwordx4 v130, s[0:1]
	s_mov_b32 m0, s35
	s_addc_u32 s71, s1, 0
	global_load_lds_dwordx4 v134, s[0:1]
	s_mov_b32 m0, s40
	s_nop 0
	global_load_lds_dwordx4 v130, s[70:71]
	s_mov_b32 m0, s41
	s_nop 0
	global_load_lds_dwordx4 v134, s[70:71]
	s_add_u32 s100, s10, s16
	s_addc_u32 s101, s11, s17
	s_mov_b32 m0, s39
	s_nop 0
	global_load_lds_dwordx4 v128, s[10:11]
	s_mov_b32 m0, s42
	s_nop 0
	global_load_lds_dwordx4 v132, s[10:11]
	ds_read_b128 v[200:203], v165 offset:16384
	ds_read_b128 v[204:207], v165 offset:17408
	ds_read_b128 v[208:211], v165 offset:18432
	ds_read_b128 v[212:215], v165 offset:19456
	ds_read_b128 v[216:219], v165 offset:20480
	ds_read_b128 v[220:223], v165 offset:21504
	ds_read_b128 v[224:227], v165 offset:22528
	ds_read_b128 v[228:231], v165 offset:23552
	s_waitcnt vmcnt(8)
	s_waitcnt lgkmcnt(0)
	s_setprio 1
	s_barrier
	v_mfma_f32_16x16x32_bf16 v[60:63], v[144:147], v[200:203], v[60:63]
	v_mfma_f32_16x16x32_bf16 v[56:59], v[152:155], v[200:203], v[56:59]
	v_mfma_f32_16x16x32_bf16 v[44:47], v[144:147], v[208:211], v[44:47]
	v_mfma_f32_16x16x32_bf16 v[40:43], v[152:155], v[208:211], v[40:43]
	v_mfma_f32_16x16x32_bf16 v[28:31], v[144:147], v[216:219], v[28:31]
	v_mfma_f32_16x16x32_bf16 v[24:27], v[152:155], v[216:219], v[24:27]
	v_mfma_f32_16x16x32_bf16 v[12:15], v[144:147], v[224:227], v[12:15]
	v_mfma_f32_16x16x32_bf16 v[8:11], v[152:155], v[224:227], v[8:11]
	v_mfma_f32_16x16x32_bf16 v[60:63], v[148:151], v[204:207], v[60:63]
	v_mfma_f32_16x16x32_bf16 v[56:59], v[156:159], v[204:207], v[56:59]
	v_mfma_f32_16x16x32_bf16 v[44:47], v[148:151], v[212:215], v[44:47]
	v_mfma_f32_16x16x32_bf16 v[40:43], v[156:159], v[212:215], v[40:43]
	v_mfma_f32_16x16x32_bf16 v[28:31], v[148:151], v[220:223], v[28:31]
	v_mfma_f32_16x16x32_bf16 v[24:27], v[156:159], v[220:223], v[24:27]
	v_mfma_f32_16x16x32_bf16 v[12:15], v[148:151], v[228:231], v[12:15]
	v_mfma_f32_16x16x32_bf16 v[8:11], v[156:159], v[228:231], v[8:11]
	s_setprio 0
	s_setprio 1
	v_mfma_f32_16x16x32_bf16 v[52:55], v[184:187], v[200:203], v[52:55]
	v_mfma_f32_16x16x32_bf16 v[48:51], v[192:195], v[200:203], v[48:51]
	v_mfma_f32_16x16x32_bf16 v[36:39], v[184:187], v[208:211], v[36:39]
	v_mfma_f32_16x16x32_bf16 v[32:35], v[192:195], v[208:211], v[32:35]
	v_mfma_f32_16x16x32_bf16 v[20:23], v[184:187], v[216:219], v[20:23]
	v_mfma_f32_16x16x32_bf16 v[16:19], v[192:195], v[216:219], v[16:19]
	v_mfma_f32_16x16x32_bf16 v[4:7], v[184:187], v[224:227], v[4:7]
	v_mfma_f32_16x16x32_bf16 v[0:3], v[192:195], v[224:227], v[0:3]
	v_mfma_f32_16x16x32_bf16 v[52:55], v[188:191], v[204:207], v[52:55]
	v_mfma_f32_16x16x32_bf16 v[48:51], v[196:199], v[204:207], v[48:51]
	v_mfma_f32_16x16x32_bf16 v[36:39], v[188:191], v[212:215], v[36:39]
	v_mfma_f32_16x16x32_bf16 v[32:35], v[196:199], v[212:215], v[32:35]
	v_mfma_f32_16x16x32_bf16 v[20:23], v[188:191], v[220:223], v[20:23]
	v_mfma_f32_16x16x32_bf16 v[16:19], v[196:199], v[220:223], v[16:19]
	v_mfma_f32_16x16x32_bf16 v[4:7], v[188:191], v[228:231], v[4:7]
	v_mfma_f32_16x16x32_bf16 v[0:3], v[196:199], v[228:231], v[0:3]
	s_barrier
; #define PG8_STAGE(bufoff, gbase, voff) do { _Pragma("unroll") for (int _i = 0; _i < 2; ++_i) \
;         __builtin_amdgcn_global_load_lds((const unsigned*)((const char*)(gbase) + (voff)[_i]), (PG8_LAS unsigned*)(lds + (bufoff) + ldsw + _i * 8192), 16, 0, 0); } while (0)
; #define PG8_LDA(dst, b, h) do { _Pragma("unroll") for (int m = 0; m < 4; ++m) _Pragma("unroll") for (int k = 0; k < 2; ++k) dst[m][k] = *(const PG8_LAS bf16x8*)(lds + PG8_SA(b, h) + aoff + m * 2048 + k * 1024); } while (0)
; #define PG8_LDB(dst, b, h) do { _Pragma("unroll") for (int n = 0; n < 2; ++n) _Pragma("unroll") for (int k = 0; k < 2; ++k) dst[n][k] = *(const PG8_LAS bf16x8*)(lds + PG8_SB(b, h) + boff + n * 2048 + k * 1024); } while (0)
; #define PG8_MMA(ai, bj, At, Bt) do { __builtin_amdgcn_s_setprio(1); _Pragma("unroll") for (int m = 0; m < 4; ++m) _Pragma("unroll") for (int n = 0; n < 2; ++n) _Pragma("unroll") for (int k = 0; k < 2; ++k) \
;         acc[ai][bj][m][n] = __builtin_amdgcn_mfma_f32_16x16x32_bf16(Bt[n][k], At[m][k], acc[ai][bj][m][n], 0, 0, 0); __builtin_amdgcn_s_setprio(0); } while (0)
; #define PG8_WAIT_V(n) asm volatile("s_waitcnt vmcnt(" #n ")" ::: "memory")
; #define PG8_WAIT_L(n) asm volatile("s_waitcnt lgkmcnt(" #n ")" ::: "memory")
; #define PG8_BAR __builtin_amdgcn_s_barrier()
; #define PG8_SCHED __builtin_amdgcn_sched_barrier(0)
; template <class Epi, class Sched, bool ALIGN_EPI = false, bool SP2 = false>
; __device__ __forceinline__ void gemm_phase(PG8_LAS unsigned char* lds, const Gemm g, const Sched& S, const Epi& E, const int tid_arg) {
;     ...
;         for (int t = 0; t < nt; t += 2) {
;     ...
;             PG8_LDB(B0, 1, 0); PG8_LDB(B1, 1, 1); PG8_SCHED; PG8_LDA(At, 1, 0); PG8_STAGE(PG8_SA(0, 1), a2 + hstep, voffA);
;             PG8_WAIT_V(8); PG8_WAIT_L(0); PG8_BAR; PG8_MMA(0, 0, At, B0); PG8_MMA(0, 1, At, B1); PG8_BAR; PG8_SCHED;
;             PG8_LDA(At, 1, 1); PG8_STAGE(PG8_SB(1, 0), b3, voffB); PG8_STAGE(PG8_SB(1, 1), b3 + hstep, voffB); PG8_STAGE(PG8_SA(1, 0), a3, voffA);
;             PG8_WAIT_V(8); PG8_WAIT_L(0); PG8_BAR; PG8_MMA(1, 0, At, B0); PG8_MMA(1, 1, At, B1); PG8_BAR; PG8_SCHED;
	s_setprio 0
	s_add_u32 s10, s10, 0x40000
	s_addc_u32 s11, s11, 0
	s_mov_b32 m0, s43
	s_nop 0
	global_load_lds_dwordx4 v128, s[10:11]
	s_mov_b32 m0, s44
	s_nop 0
	global_load_lds_dwordx4 v132, s[10:11]
	ds_read_b128 v[144:147], v174
	ds_read_b128 v[148:151], v175
	ds_read_b128 v[152:155], v176
	ds_read_b128 v[156:159], v177
	ds_read_b128 v[184:187], v178
	ds_read_b128 v[188:191], v179
	ds_read_b128 v[192:195], v180
	ds_read_b128 v[196:199], v181
	ds_read_b128 v[200:203], v165 offset:32768
	ds_read_b128 v[204:207], v165 offset:33792
	ds_read_b128 v[208:211], v165 offset:34816
	ds_read_b128 v[212:215], v165 offset:35840
	ds_read_b128 v[216:219], v165 offset:36864
	ds_read_b128 v[220:223], v165 offset:37888
	ds_read_b128 v[224:227], v165 offset:38912
	ds_read_b128 v[228:231], v165 offset:39936
	s_waitcnt vmcnt(8)
	s_waitcnt lgkmcnt(0)
	s_setprio 1
	s_barrier
	v_mfma_f32_16x16x32_bf16 v[124:127], v[144:147], v[200:203], v[124:127]
	v_mfma_f32_16x16x32_bf16 v[120:123], v[152:155], v[200:203], v[120:123]
	v_mfma_f32_16x16x32_bf16 v[108:111], v[144:147], v[208:211], v[108:111]
	v_mfma_f32_16x16x32_bf16 v[104:107], v[152:155], v[208:211], v[104:107]
	v_mfma_f32_16x16x32_bf16 v[92:95], v[144:147], v[216:219], v[92:95]
	v_mfma_f32_16x16x32_bf16 v[88:91], v[152:155], v[216:219], v[88:91]
	v_mfma_f32_16x16x32_bf16 v[76:79], v[144:147], v[224:227], v[76:79]
	v_mfma_f32_16x16x32_bf16 v[72:75], v[152:155], v[224:227], v[72:75]
	v_mfma_f32_16x16x32_bf16 v[124:127], v[148:151], v[204:207], v[124:127]
	v_mfma_f32_16x16x32_bf16 v[120:123], v[156:159], v[204:207], v[120:123]
	v_mfma_f32_16x16x32_bf16 v[108:111], v[148:151], v[212:215], v[108:111]
	v_mfma_f32_16x16x32_bf16 v[104:107], v[156:159], v[212:215], v[104:107]
	v_mfma_f32_16x16x32_bf16 v[92:95], v[148:151], v[220:223], v[92:95]
	v_mfma_f32_16x16x32_bf16 v[88:91], v[156:159], v[220:223], v[88:91]
	v_mfma_f32_16x16x32_bf16 v[76:79], v[148:151], v[228:231], v[76:79]
	v_mfma_f32_16x16x32_bf16 v[72:75], v[156:159], v[228:231], v[72:75]
	s_setprio 0
	s_setprio 1
	v_mfma_f32_16x16x32_bf16 v[116:119], v[184:187], v[200:203], v[116:119]
	v_mfma_f32_16x16x32_bf16 v[112:115], v[192:195], v[200:203], v[112:115]
	v_mfma_f32_16x16x32_bf16 v[100:103], v[184:187], v[208:211], v[100:103]
	v_mfma_f32_16x16x32_bf16 v[96:99], v[192:195], v[208:211], v[96:99]
	v_mfma_f32_16x16x32_bf16 v[84:87], v[184:187], v[216:219], v[84:87]
	v_mfma_f32_16x16x32_bf16 v[80:83], v[192:195], v[216:219], v[80:83]
	v_mfma_f32_16x16x32_bf16 v[68:71], v[184:187], v[224:227], v[68:71]
	v_mfma_f32_16x16x32_bf16 v[64:67], v[192:195], v[224:227], v[64:67]
	v_mfma_f32_16x16x32_bf16 v[116:119], v[188:191], v[204:207], v[116:119]
	v_mfma_f32_16x16x32_bf16 v[112:115], v[196:199], v[204:207], v[112:115]
	v_mfma_f32_16x16x32_bf16 v[100:103], v[188:191], v[212:215], v[100:103]
	v_mfma_f32_16x16x32_bf16 v[96:99], v[196:199], v[212:215], v[96:99]
	v_mfma_f32_16x16x32_bf16 v[84:87], v[188:191], v[220:223], v[84:87]
	v_mfma_f32_16x16x32_bf16 v[80:83], v[196:199], v[220:223], v[80:83]
	v_mfma_f32_16x16x32_bf16 v[68:71], v[188:191], v[228:231], v[68:71]
	v_mfma_f32_16x16x32_bf16 v[64:67], v[196:199], v[228:231], v[64:67]
	s_barrier
	s_setprio 0
	s_mov_b32 m0, s47
	s_add_u32 s0, s0, 0x40080
	global_load_lds_dwordx4 v130, s[98:99]
	s_mov_b32 m0, s48
	s_addc_u32 s1, s1, 0
	global_load_lds_dwordx4 v134, s[98:99]
	s_mov_b32 m0, s51
	s_nop 0
	global_load_lds_dwordx4 v130, s[0:1]
	s_mov_b32 m0, s52
	s_nop 0
	global_load_lds_dwordx4 v134, s[0:1]
	s_mov_b32 m0, s49
	s_nop 0
	global_load_lds_dwordx4 v128, s[100:101]
	s_mov_b32 m0, s50
	s_nop 0
	global_load_lds_dwordx4 v132, s[100:101]
	ds_read_b128 v[200:203], v165 offset:49152
	ds_read_b128 v[204:207], v165 offset:50176
	ds_read_b128 v[208:211], v165 offset:51200
	ds_read_b128 v[212:215], v165 offset:52224
	ds_read_b128 v[216:219], v165 offset:53248
	ds_read_b128 v[220:223], v165 offset:54272
	ds_read_b128 v[224:227], v165 offset:55296
	ds_read_b128 v[228:231], v165 offset:56320
	s_waitcnt vmcnt(8)
	s_waitcnt lgkmcnt(0)
	s_setprio 1
	s_barrier
	v_mfma_f32_16x16x32_bf16 v[60:63], v[144:147], v[200:203], v[60:63]
	v_mfma_f32_16x16x32_bf16 v[56:59], v[152:155], v[200:203], v[56:59]
	v_mfma_f32_16x16x32_bf16 v[44:47], v[144:147], v[208:211], v[44:47]
	v_mfma_f32_16x16x32_bf16 v[40:43], v[152:155], v[208:211], v[40:43]
	v_mfma_f32_16x16x32_bf16 v[28:31], v[144:147], v[216:219], v[28:31]
	v_mfma_f32_16x16x32_bf16 v[24:27], v[152:155], v[216:219], v[24:27]
	v_mfma_f32_16x16x32_bf16 v[12:15], v[144:147], v[224:227], v[12:15]
	v_mfma_f32_16x16x32_bf16 v[8:11], v[152:155], v[224:227], v[8:11]
	v_mfma_f32_16x16x32_bf16 v[60:63], v[148:151], v[204:207], v[60:63]
	v_mfma_f32_16x16x32_bf16 v[56:59], v[156:159], v[204:207], v[56:59]
	v_mfma_f32_16x16x32_bf16 v[44:47], v[148:151], v[212:215], v[44:47]
	v_mfma_f32_16x16x32_bf16 v[40:43], v[156:159], v[212:215], v[40:43]
	v_mfma_f32_16x16x32_bf16 v[28:31], v[148:151], v[220:223], v[28:31]
	v_mfma_f32_16x16x32_bf16 v[24:27], v[156:159], v[220:223], v[24:27]
	v_mfma_f32_16x16x32_bf16 v[12:15], v[148:151], v[228:231], v[12:15]
	v_mfma_f32_16x16x32_bf16 v[8:11], v[156:159], v[228:231], v[8:11]
	s_setprio 0
	s_setprio 1
	v_mfma_f32_16x16x32_bf16 v[52:55], v[184:187], v[200:203], v[52:55]
	v_mfma_f32_16x16x32_bf16 v[48:51], v[192:195], v[200:203], v[48:51]
	v_mfma_f32_16x16x32_bf16 v[36:39], v[184:187], v[208:211], v[36:39]
	v_mfma_f32_16x16x32_bf16 v[32:35], v[192:195], v[208:211], v[32:35]
	v_mfma_f32_16x16x32_bf16 v[20:23], v[184:187], v[216:219], v[20:23]
	v_mfma_f32_16x16x32_bf16 v[16:19], v[192:195], v[216:219], v[16:19]
	v_mfma_f32_16x16x32_bf16 v[4:7], v[184:187], v[224:227], v[4:7]
	v_mfma_f32_16x16x32_bf16 v[0:3], v[192:195], v[224:227], v[0:3]
	v_mfma_f32_16x16x32_bf16 v[52:55], v[188:191], v[204:207], v[52:55]
	v_mfma_f32_16x16x32_bf16 v[48:51], v[196:199], v[204:207], v[48:51]
	v_mfma_f32_16x16x32_bf16 v[36:39], v[188:191], v[212:215], v[36:39]
	v_mfma_f32_16x16x32_bf16 v[32:35], v[196:199], v[212:215], v[32:35]
	v_mfma_f32_16x16x32_bf16 v[20:23], v[188:191], v[220:223], v[20:23]
	v_mfma_f32_16x16x32_bf16 v[16:19], v[196:199], v[220:223], v[16:19]
	v_mfma_f32_16x16x32_bf16 v[4:7], v[188:191], v[228:231], v[4:7]
	v_mfma_f32_16x16x32_bf16 v[0:3], v[196:199], v[228:231], v[0:3]
	s_barrier
	s_setprio 0
	s_add_i32 s68, s68, 2
	s_add_u32 s66, s66, 0x100
	s_addc_u32 s67, s67, 0
	s_add_u32 s4, s4, 0x100
	s_addc_u32 s5, s5, 0
	s_cmp_gt_u32 s68, 13
	s_cbranch_scc0 .LBB0_1179
	s_and_b64 vcc, exec, s[18:19]
	s_cbranch_vccz .LBB0_1182
	s_barrier

; #define PG8_STAGE(bufoff, gbase, voff) do { _Pragma("unroll") for (int _i = 0; _i < 2; ++_i) \
;         __builtin_amdgcn_global_load_lds((const unsigned*)((const char*)(gbase) + (voff)[_i]), (PG8_LAS unsigned*)(lds + (bufoff) + ldsw + _i * 8192), 16, 0, 0); } while (0)
; #define PG8_LDA(dst, b, h) do { _Pragma("unroll") for (int m = 0; m < 4; ++m) _Pragma("unroll") for (int k = 0; k < 2; ++k) dst[m][k] = *(const PG8_LAS bf16x8*)(lds + PG8_SA(b, h) + aoff + m * 2048 + k * 1024); } while (0)
; #define PG8_LDB(dst, b, h) do { _Pragma("unroll") for (int n = 0; n < 2; ++n) _Pragma("unroll") for (int k = 0; k < 2; ++k) dst[n][k] = *(const PG8_LAS bf16x8*)(lds + PG8_SB(b, h) + boff + n * 2048 + k * 1024); } while (0)
; #define PG8_MMA(ai, bj, At, Bt) do { __builtin_amdgcn_s_setprio(1); _Pragma("unroll") for (int m = 0; m < 4; ++m) _Pragma("unroll") for (int n = 0; n < 2; ++n) _Pragma("unroll") for (int k = 0; k < 2; ++k) \
;         acc[ai][bj][m][n] = __builtin_amdgcn_mfma_f32_16x16x32_bf16(Bt[n][k], At[m][k], acc[ai][bj][m][n], 0, 0, 0); __builtin_amdgcn_s_setprio(0); } while (0)
; #define PG8_WAIT_V(n) asm volatile("s_waitcnt vmcnt(" #n ")" ::: "memory")
; #define PG8_WAIT_L(n) asm volatile("s_waitcnt lgkmcnt(" #n ")" ::: "memory")
; template <class Epi, class Sched, bool ALIGN_EPI = false, bool SP2 = false>
; __device__ __forceinline__ void gemm_phase(PG8_LAS unsigned char* lds, const Gemm g, const Sched& S, const Epi& E, const int tid_arg) {
;     ...
;             const bool last = (t == nt - 2);
;             const char* a1 = cA + (size_t)(t + 1) * kstep;
;             const char* a2 = last ? nA : cA + (size_t)(t + 2) * kstep; const char* b2 = last ? nB : cB + (size_t)(t + 2) * kstep;
;             const char* a3 = a2 + kstep; const char* b3 = b2 + kstep;
;             if (last && has_next) S.a_ready(nxt);
;             if constexpr (SP2) {
;             PG8_LDB(B0, 0, 0); PG8_LDB(B1, 0, 1); PG8_SCHED; PG8_LDA(At, 0, 0); PG8_STAGE(PG8_SA(1, 1), a1 + hstep, voffA);
;             PG8_WAIT_V(8); PG8_WAIT_L(0); PG8_BAR; PG8_MMA(0, 0, At, B0); PG8_MMA(0, 1, At, B1); PG8_BAR; PG8_SCHED;
;             PG8_LDA(At, 0, 1); PG8_STAGE(PG8_SB(0, 0), b2, voffB); PG8_STAGE(PG8_SB(0, 1), b2 + hstep, voffB); PG8_STAGE(PG8_SA(0, 0), a2, voffA);
;             PG8_WAIT_V(8); PG8_WAIT_L(0); PG8_BAR; PG8_MMA(1, 0, At, B0); PG8_MMA(1, 1, At, B1); PG8_BAR; PG8_SCHED;
.LBB0_1459:
	s_add_u32 s0, s28, 0xfffc0080
	s_addc_u32 s1, s29, -1
	s_cmp_eq_u32 s59, 12
	s_cselect_b32 s31, s21, s1
	s_cselect_b32 s30, s27, s0
	s_cselect_b32 s1, s19, s58
	s_cselect_b32 s0, s56, s57
	s_mov_b32 m0, s53
	s_nop 0
	global_load_lds_dwordx4 v138, s[28:29]
	s_mov_b32 m0, s54
	s_nop 0
	global_load_lds_dwordx4 v136, s[28:29]
	ds_read_b128 v[144:147], v151
	ds_read_b128 v[168:171], v152
	ds_read_b128 v[172:175], v153
	ds_read_b128 v[176:179], v154
	ds_read_b128 v[180:183], v155
	ds_read_b128 v[184:187], v156
	ds_read_b128 v[188:191], v157
	ds_read_b128 v[192:195], v158
	ds_read_b128 v[196:199], v150
	ds_read_b128 v[200:203], v150 offset:1024
	ds_read_b128 v[204:207], v150 offset:2048
	ds_read_b128 v[208:211], v150 offset:3072
	ds_read_b128 v[212:215], v150 offset:4096
	ds_read_b128 v[216:219], v150 offset:5120
	ds_read_b128 v[220:223], v150 offset:6144
	ds_read_b128 v[224:227], v150 offset:7168
	s_waitcnt vmcnt(8)
	s_waitcnt lgkmcnt(0)
	s_setprio 1
	s_barrier
	v_mfma_f32_16x16x32_bf16 v[124:127], v[144:147], v[196:199], v[124:127]
	v_mfma_f32_16x16x32_bf16 v[120:123], v[172:175], v[196:199], v[120:123]
	v_mfma_f32_16x16x32_bf16 v[108:111], v[144:147], v[204:207], v[108:111]
	v_mfma_f32_16x16x32_bf16 v[104:107], v[172:175], v[204:207], v[104:107]
	v_mfma_f32_16x16x32_bf16 v[92:95], v[144:147], v[212:215], v[92:95]
	v_mfma_f32_16x16x32_bf16 v[88:91], v[172:175], v[212:215], v[88:91]
	v_mfma_f32_16x16x32_bf16 v[76:79], v[144:147], v[220:223], v[76:79]
	v_mfma_f32_16x16x32_bf16 v[72:75], v[172:175], v[220:223], v[72:75]
	v_mfma_f32_16x16x32_bf16 v[124:127], v[168:171], v[200:203], v[124:127]
	v_mfma_f32_16x16x32_bf16 v[120:123], v[176:179], v[200:203], v[120:123]
	v_mfma_f32_16x16x32_bf16 v[108:111], v[168:171], v[208:211], v[108:111]
	v_mfma_f32_16x16x32_bf16 v[104:107], v[176:179], v[208:211], v[104:107]
	v_mfma_f32_16x16x32_bf16 v[92:95], v[168:171], v[216:219], v[92:95]
	v_mfma_f32_16x16x32_bf16 v[88:91], v[176:179], v[216:219], v[88:91]
	v_mfma_f32_16x16x32_bf16 v[76:79], v[168:171], v[224:227], v[76:79]
	v_mfma_f32_16x16x32_bf16 v[72:75], v[176:179], v[224:227], v[72:75]
	s_setprio 0
	s_setprio 1
	v_mfma_f32_16x16x32_bf16 v[116:119], v[180:183], v[196:199], v[116:119]
	v_mfma_f32_16x16x32_bf16 v[112:115], v[188:191], v[196:199], v[112:115]
	v_mfma_f32_16x16x32_bf16 v[100:103], v[180:183], v[204:207], v[100:103]
	v_mfma_f32_16x16x32_bf16 v[96:99], v[188:191], v[204:207], v[96:99]
	v_mfma_f32_16x16x32_bf16 v[84:87], v[180:183], v[212:215], v[84:87]
	v_mfma_f32_16x16x32_bf16 v[80:83], v[188:191], v[212:215], v[80:83]
	v_mfma_f32_16x16x32_bf16 v[68:71], v[180:183], v[220:223], v[68:71]
	v_mfma_f32_16x16x32_bf16 v[64:67], v[188:191], v[220:223], v[64:67]
	v_mfma_f32_16x16x32_bf16 v[116:119], v[184:187], v[200:203], v[116:119]
	v_mfma_f32_16x16x32_bf16 v[112:115], v[192:195], v[200:203], v[112:115]
	v_mfma_f32_16x16x32_bf16 v[100:103], v[184:187], v[208:211], v[100:103]
	v_mfma_f32_16x16x32_bf16 v[96:99], v[192:195], v[208:211], v[96:99]
	v_mfma_f32_16x16x32_bf16 v[84:87], v[184:187], v[216:219], v[84:87]
	v_mfma_f32_16x16x32_bf16 v[80:83], v[192:195], v[216:219], v[80:83]
	v_mfma_f32_16x16x32_bf16 v[68:71], v[184:187], v[224:227], v[68:71]
	v_mfma_f32_16x16x32_bf16 v[64:67], v[192:195], v[224:227], v[64:67]
	s_barrier
	s_setprio 0
	s_mov_b32 m0, s5
	s_add_u32 s98, s0, s14
	s_addc_u32 s99, s1, s15
	s_add_u32 s60, s0, 0x40000
	global_load_lds_dwordx4 v130, s[0:1]
	s_mov_b32 m0, s36
	s_addc_u32 s61, s1, 0
	global_load_lds_dwordx4 v134, s[0:1]
	s_mov_b32 m0, s37
	s_nop 0
	global_load_lds_dwordx4 v130, s[60:61]
	s_mov_b32 m0, s38
	s_nop 0
	global_load_lds_dwordx4 v134, s[60:61]
	s_add_u32 s100, s30, s14
	s_addc_u32 s101, s31, s15
	s_mov_b32 m0, s35
	s_nop 0
	global_load_lds_dwordx4 v128, s[30:31]
	s_mov_b32 m0, s39
	s_nop 0
	global_load_lds_dwordx4 v132, s[30:31]
	ds_read_b128 v[196:199], v150 offset:16384
	ds_read_b128 v[200:203], v150 offset:17408
	ds_read_b128 v[204:207], v150 offset:18432
	ds_read_b128 v[208:211], v150 offset:19456
	ds_read_b128 v[212:215], v150 offset:20480
	ds_read_b128 v[216:219], v150 offset:21504
	ds_read_b128 v[220:223], v150 offset:22528
	ds_read_b128 v[224:227], v150 offset:23552
	s_waitcnt vmcnt(8)
	s_waitcnt lgkmcnt(0)
	s_setprio 1
	s_barrier
	v_mfma_f32_16x16x32_bf16 v[60:63], v[144:147], v[196:199], v[60:63]
	v_mfma_f32_16x16x32_bf16 v[56:59], v[172:175], v[196:199], v[56:59]
	v_mfma_f32_16x16x32_bf16 v[44:47], v[144:147], v[204:207], v[44:47]
	v_mfma_f32_16x16x32_bf16 v[40:43], v[172:175], v[204:207], v[40:43]
	v_mfma_f32_16x16x32_bf16 v[28:31], v[144:147], v[212:215], v[28:31]
	v_mfma_f32_16x16x32_bf16 v[24:27], v[172:175], v[212:215], v[24:27]
	v_mfma_f32_16x16x32_bf16 v[12:15], v[144:147], v[220:223], v[12:15]
	v_mfma_f32_16x16x32_bf16 v[8:11], v[172:175], v[220:223], v[8:11]
	v_mfma_f32_16x16x32_bf16 v[60:63], v[168:171], v[200:203], v[60:63]
	v_mfma_f32_16x16x32_bf16 v[56:59], v[176:179], v[200:203], v[56:59]
	v_mfma_f32_16x16x32_bf16 v[44:47], v[168:171], v[208:211], v[44:47]
	v_mfma_f32_16x16x32_bf16 v[40:43], v[176:179], v[208:211], v[40:43]
	v_mfma_f32_16x16x32_bf16 v[28:31], v[168:171], v[216:219], v[28:31]
	v_mfma_f32_16x16x32_bf16 v[24:27], v[176:179], v[216:219], v[24:27]
	v_mfma_f32_16x16x32_bf16 v[12:15], v[168:171], v[224:227], v[12:15]
	v_mfma_f32_16x16x32_bf16 v[8:11], v[176:179], v[224:227], v[8:11]
	s_setprio 0
	s_setprio 1
	v_mfma_f32_16x16x32_bf16 v[52:55], v[180:183], v[196:199], v[52:55]
	v_mfma_f32_16x16x32_bf16 v[48:51], v[188:191], v[196:199], v[48:51]
	v_mfma_f32_16x16x32_bf16 v[36:39], v[180:183], v[204:207], v[36:39]
	v_mfma_f32_16x16x32_bf16 v[32:35], v[188:191], v[204:207], v[32:35]
	v_mfma_f32_16x16x32_bf16 v[20:23], v[180:183], v[212:215], v[20:23]
	v_mfma_f32_16x16x32_bf16 v[16:19], v[188:191], v[212:215], v[16:19]
	v_mfma_f32_16x16x32_bf16 v[4:7], v[180:183], v[220:223], v[4:7]
	v_mfma_f32_16x16x32_bf16 v[0:3], v[188:191], v[220:223], v[0:3]
	v_mfma_f32_16x16x32_bf16 v[52:55], v[184:187], v[200:203], v[52:55]
	v_mfma_f32_16x16x32_bf16 v[48:51], v[192:195], v[200:203], v[48:51]
	v_mfma_f32_16x16x32_bf16 v[36:39], v[184:187], v[208:211], v[36:39]
	v_mfma_f32_16x16x32_bf16 v[32:35], v[192:195], v[208:211], v[32:35]
	v_mfma_f32_16x16x32_bf16 v[20:23], v[184:187], v[216:219], v[20:23]
	v_mfma_f32_16x16x32_bf16 v[16:19], v[192:195], v[216:219], v[16:19]
	v_mfma_f32_16x16x32_bf16 v[4:7], v[184:187], v[224:227], v[4:7]
	v_mfma_f32_16x16x32_bf16 v[0:3], v[192:195], v[224:227], v[0:3]
	s_barrier
; #define PG8_STAGE(bufoff, gbase, voff) do { _Pragma("unroll") for (int _i = 0; _i < 2; ++_i) \
;         __builtin_amdgcn_global_load_lds((const unsigned*)((const char*)(gbase) + (voff)[_i]), (PG8_LAS unsigned*)(lds + (bufoff) + ldsw + _i * 8192), 16, 0, 0); } while (0)
; #define PG8_LDA(dst, b, h) do { _Pragma("unroll") for (int m = 0; m < 4; ++m) _Pragma("unroll") for (int k = 0; k < 2; ++k) dst[m][k] = *(const PG8_LAS bf16x8*)(lds + PG8_SA(b, h) + aoff + m * 2048 + k * 1024); } while (0)
; #define PG8_LDB(dst, b, h) do { _Pragma("unroll") for (int n = 0; n < 2; ++n) _Pragma("unroll") for (int k = 0; k < 2; ++k) dst[n][k] = *(const PG8_LAS bf16x8*)(lds + PG8_SB(b, h) + boff + n * 2048 + k * 1024); } while (0)
; #define PG8_MMA(ai, bj, At, Bt) do { __builtin_amdgcn_s_setprio(1); _Pragma("unroll") for (int m = 0; m < 4; ++m) _Pragma("unroll") for (int n = 0; n < 2; ++n) _Pragma("unroll") for (int k = 0; k < 2; ++k) \
;         acc[ai][bj][m][n] = __builtin_amdgcn_mfma_f32_16x16x32_bf16(Bt[n][k], At[m][k], acc[ai][bj][m][n], 0, 0, 0); __builtin_amdgcn_s_setprio(0); } while (0)
; #define PG8_WAIT_V(n) asm volatile("s_waitcnt vmcnt(" #n ")" ::: "memory")
; #define PG8_WAIT_L(n) asm volatile("s_waitcnt lgkmcnt(" #n ")" ::: "memory")
; #define PG8_BAR __builtin_amdgcn_s_barrier()
; #define PG8_SCHED __builtin_amdgcn_sched_barrier(0)
; template <class Epi, class Sched, bool ALIGN_EPI = false, bool SP2 = false>
; __device__ __forceinline__ void gemm_phase(PG8_LAS unsigned char* lds, const Gemm g, const Sched& S, const Epi& E, const int tid_arg) {
;     ...
;             PG8_LDB(B0, 1, 0); PG8_LDB(B1, 1, 1); PG8_SCHED; PG8_LDA(At, 1, 0); PG8_STAGE(PG8_SA(0, 1), a2 + hstep, voffA);
;             PG8_WAIT_V(8); PG8_WAIT_L(0); PG8_BAR; PG8_MMA(0, 0, At, B0); PG8_MMA(0, 1, At, B1); PG8_BAR; PG8_SCHED;
;             PG8_LDA(At, 1, 1); PG8_STAGE(PG8_SB(1, 0), b3, voffB); PG8_STAGE(PG8_SB(1, 1), b3 + hstep, voffB); PG8_STAGE(PG8_SA(1, 0), a3, voffA);
;             PG8_WAIT_V(8); PG8_WAIT_L(0); PG8_BAR; PG8_MMA(1, 0, At, B0); PG8_MMA(1, 1, At, B1); PG8_BAR; PG8_SCHED;
	s_setprio 0
	s_add_u32 s30, s30, 0x40000
	s_addc_u32 s31, s31, 0
	s_mov_b32 m0, s40
	s_nop 0
	global_load_lds_dwordx4 v128, s[30:31]
	s_mov_b32 m0, s41
	s_nop 0
	global_load_lds_dwordx4 v132, s[30:31]
	ds_read_b128 v[144:147], v159
	ds_read_b128 v[168:171], v160
	ds_read_b128 v[172:175], v161
	ds_read_b128 v[176:179], v162
	ds_read_b128 v[180:183], v163
	ds_read_b128 v[184:187], v164
	ds_read_b128 v[188:191], v165
	ds_read_b128 v[192:195], v166
	ds_read_b128 v[196:199], v150 offset:32768
	ds_read_b128 v[200:203], v150 offset:33792
	ds_read_b128 v[204:207], v150 offset:34816
	ds_read_b128 v[208:211], v150 offset:35840
	ds_read_b128 v[212:215], v150 offset:36864
	ds_read_b128 v[216:219], v150 offset:37888
	ds_read_b128 v[220:223], v150 offset:38912
	ds_read_b128 v[224:227], v150 offset:39936
	s_waitcnt vmcnt(8)
	s_waitcnt lgkmcnt(0)
	s_setprio 1
	s_barrier
	v_mfma_f32_16x16x32_bf16 v[124:127], v[144:147], v[196:199], v[124:127]
	v_mfma_f32_16x16x32_bf16 v[120:123], v[172:175], v[196:199], v[120:123]
	v_mfma_f32_16x16x32_bf16 v[108:111], v[144:147], v[204:207], v[108:111]
	v_mfma_f32_16x16x32_bf16 v[104:107], v[172:175], v[204:207], v[104:107]
	v_mfma_f32_16x16x32_bf16 v[92:95], v[144:147], v[212:215], v[92:95]
	v_mfma_f32_16x16x32_bf16 v[88:91], v[172:175], v[212:215], v[88:91]
	v_mfma_f32_16x16x32_bf16 v[76:79], v[144:147], v[220:223], v[76:79]
	v_mfma_f32_16x16x32_bf16 v[72:75], v[172:175], v[220:223], v[72:75]
	v_mfma_f32_16x16x32_bf16 v[124:127], v[168:171], v[200:203], v[124:127]
	v_mfma_f32_16x16x32_bf16 v[120:123], v[176:179], v[200:203], v[120:123]
	v_mfma_f32_16x16x32_bf16 v[108:111], v[168:171], v[208:211], v[108:111]
	v_mfma_f32_16x16x32_bf16 v[104:107], v[176:179], v[208:211], v[104:107]
	v_mfma_f32_16x16x32_bf16 v[92:95], v[168:171], v[216:219], v[92:95]
	v_mfma_f32_16x16x32_bf16 v[88:91], v[176:179], v[216:219], v[88:91]
	v_mfma_f32_16x16x32_bf16 v[76:79], v[168:171], v[224:227], v[76:79]
	v_mfma_f32_16x16x32_bf16 v[72:75], v[176:179], v[224:227], v[72:75]
	s_setprio 0
	s_setprio 1
	v_mfma_f32_16x16x32_bf16 v[116:119], v[180:183], v[196:199], v[116:119]
	v_mfma_f32_16x16x32_bf16 v[112:115], v[188:191], v[196:199], v[112:115]
	v_mfma_f32_16x16x32_bf16 v[100:103], v[180:183], v[204:207], v[100:103]
	v_mfma_f32_16x16x32_bf16 v[96:99], v[188:191], v[204:207], v[96:99]
	v_mfma_f32_16x16x32_bf16 v[84:87], v[180:183], v[212:215], v[84:87]
	v_mfma_f32_16x16x32_bf16 v[80:83], v[188:191], v[212:215], v[80:83]
	v_mfma_f32_16x16x32_bf16 v[68:71], v[180:183], v[220:223], v[68:71]
	v_mfma_f32_16x16x32_bf16 v[64:67], v[188:191], v[220:223], v[64:67]
	v_mfma_f32_16x16x32_bf16 v[116:119], v[184:187], v[200:203], v[116:119]
	v_mfma_f32_16x16x32_bf16 v[112:115], v[192:195], v[200:203], v[112:115]
	v_mfma_f32_16x16x32_bf16 v[100:103], v[184:187], v[208:211], v[100:103]
	v_mfma_f32_16x16x32_bf16 v[96:99], v[192:195], v[208:211], v[96:99]
	v_mfma_f32_16x16x32_bf16 v[84:87], v[184:187], v[216:219], v[84:87]
	v_mfma_f32_16x16x32_bf16 v[80:83], v[192:195], v[216:219], v[80:83]
	v_mfma_f32_16x16x32_bf16 v[68:71], v[184:187], v[224:227], v[68:71]
	v_mfma_f32_16x16x32_bf16 v[64:67], v[192:195], v[224:227], v[64:67]
	s_barrier
	s_setprio 0
	s_mov_b32 m0, s45
	s_add_u32 s0, s0, 0x40080
	global_load_lds_dwordx4 v130, s[98:99]
	s_mov_b32 m0, s46
	s_addc_u32 s1, s1, 0
	global_load_lds_dwordx4 v134, s[98:99]
	s_mov_b32 m0, s49
	s_nop 0
	global_load_lds_dwordx4 v130, s[0:1]
	s_mov_b32 m0, s50
	s_nop 0
	global_load_lds_dwordx4 v134, s[0:1]
	s_mov_b32 m0, s47
	s_nop 0
	global_load_lds_dwordx4 v128, s[100:101]
	s_mov_b32 m0, s48
	s_nop 0
	global_load_lds_dwordx4 v132, s[100:101]
	ds_read_b128 v[196:199], v150 offset:49152
	ds_read_b128 v[200:203], v150 offset:50176
	ds_read_b128 v[204:207], v150 offset:51200
	ds_read_b128 v[208:211], v150 offset:52224
	ds_read_b128 v[212:215], v150 offset:53248
	ds_read_b128 v[216:219], v150 offset:54272
	ds_read_b128 v[220:223], v150 offset:55296
	ds_read_b128 v[224:227], v150 offset:56320
	s_waitcnt vmcnt(8)
	s_waitcnt lgkmcnt(0)
	s_setprio 1
	s_barrier
	v_mfma_f32_16x16x32_bf16 v[60:63], v[144:147], v[196:199], v[60:63]
	v_mfma_f32_16x16x32_bf16 v[56:59], v[172:175], v[196:199], v[56:59]
	v_mfma_f32_16x16x32_bf16 v[44:47], v[144:147], v[204:207], v[44:47]
	v_mfma_f32_16x16x32_bf16 v[40:43], v[172:175], v[204:207], v[40:43]
	v_mfma_f32_16x16x32_bf16 v[28:31], v[144:147], v[212:215], v[28:31]
	v_mfma_f32_16x16x32_bf16 v[24:27], v[172:175], v[212:215], v[24:27]
	v_mfma_f32_16x16x32_bf16 v[12:15], v[144:147], v[220:223], v[12:15]
	v_mfma_f32_16x16x32_bf16 v[8:11], v[172:175], v[220:223], v[8:11]
	v_mfma_f32_16x16x32_bf16 v[60:63], v[168:171], v[200:203], v[60:63]
	v_mfma_f32_16x16x32_bf16 v[56:59], v[176:179], v[200:203], v[56:59]
	v_mfma_f32_16x16x32_bf16 v[44:47], v[168:171], v[208:211], v[44:47]
	v_mfma_f32_16x16x32_bf16 v[40:43], v[176:179], v[208:211], v[40:43]
	v_mfma_f32_16x16x32_bf16 v[28:31], v[168:171], v[216:219], v[28:31]
	v_mfma_f32_16x16x32_bf16 v[24:27], v[176:179], v[216:219], v[24:27]
	v_mfma_f32_16x16x32_bf16 v[12:15], v[168:171], v[224:227], v[12:15]
	v_mfma_f32_16x16x32_bf16 v[8:11], v[176:179], v[224:227], v[8:11]
	s_setprio 0
	s_setprio 1
	v_mfma_f32_16x16x32_bf16 v[52:55], v[180:183], v[196:199], v[52:55]
	v_mfma_f32_16x16x32_bf16 v[48:51], v[188:191], v[196:199], v[48:51]
	v_mfma_f32_16x16x32_bf16 v[36:39], v[180:183], v[204:207], v[36:39]
	v_mfma_f32_16x16x32_bf16 v[32:35], v[188:191], v[204:207], v[32:35]
	v_mfma_f32_16x16x32_bf16 v[20:23], v[180:183], v[212:215], v[20:23]
	v_mfma_f32_16x16x32_bf16 v[16:19], v[188:191], v[212:215], v[16:19]
	v_mfma_f32_16x16x32_bf16 v[4:7], v[180:183], v[220:223], v[4:7]
	v_mfma_f32_16x16x32_bf16 v[0:3], v[188:191], v[220:223], v[0:3]
	v_mfma_f32_16x16x32_bf16 v[52:55], v[184:187], v[200:203], v[52:55]
	v_mfma_f32_16x16x32_bf16 v[48:51], v[192:195], v[200:203], v[48:51]
	v_mfma_f32_16x16x32_bf16 v[36:39], v[184:187], v[208:211], v[36:39]
	v_mfma_f32_16x16x32_bf16 v[32:35], v[192:195], v[208:211], v[32:35]
	v_mfma_f32_16x16x32_bf16 v[20:23], v[184:187], v[216:219], v[20:23]
	v_mfma_f32_16x16x32_bf16 v[16:19], v[192:195], v[216:219], v[16:19]
	v_mfma_f32_16x16x32_bf16 v[4:7], v[184:187], v[224:227], v[4:7]
	v_mfma_f32_16x16x32_bf16 v[0:3], v[192:195], v[224:227], v[0:3]
	s_barrier
	s_setprio 0
	s_add_i32 s59, s59, 2
	s_add_u32 s57, s57, 0x100
	s_addc_u32 s58, s58, 0
	s_add_u32 s28, s28, 0x100
	s_addc_u32 s29, s29, 0
	s_cmp_gt_u32 s59, 13
	s_cbranch_scc0 .LBB0_1459
	s_and_b64 vcc, exec, s[16:17]
	s_cbranch_vccz .LBB0_1462
	s_barrier

; #define PG8_STAGE(bufoff, gbase, voff) do { _Pragma("unroll") for (int _i = 0; _i < 2; ++_i) \
;         __builtin_amdgcn_global_load_lds((const unsigned*)((const char*)(gbase) + (voff)[_i]), (PG8_LAS unsigned*)(lds + (bufoff) + ldsw + _i * 8192), 16, 0, 0); } while (0)
; #define PG8_LDA(dst, b, h) do { _Pragma("unroll") for (int m = 0; m < 4; ++m) _Pragma("unroll") for (int k = 0; k < 2; ++k) dst[m][k] = *(const PG8_LAS bf16x8*)(lds + PG8_SA(b, h) + aoff + m * 2048 + k * 1024); } while (0)
; #define PG8_LDB(dst, b, h) do { _Pragma("unroll") for (int n = 0; n < 2; ++n) _Pragma("unroll") for (int k = 0; k < 2; ++k) dst[n][k] = *(const PG8_LAS bf16x8*)(lds + PG8_SB(b, h) + boff + n * 2048 + k * 1024); } while (0)
; #define PG8_MMA(ai, bj, At, Bt) do { __builtin_amdgcn_s_setprio(1); _Pragma("unroll") for (int m = 0; m < 4; ++m) _Pragma("unroll") for (int n = 0; n < 2; ++n) _Pragma("unroll") for (int k = 0; k < 2; ++k) \
;         acc[ai][bj][m][n] = __builtin_amdgcn_mfma_f32_16x16x32_bf16(Bt[n][k], At[m][k], acc[ai][bj][m][n], 0, 0, 0); __builtin_amdgcn_s_setprio(0); } while (0)
; #define PG8_WAIT_V(n) asm volatile("s_waitcnt vmcnt(" #n ")" ::: "memory")
; #define PG8_WAIT_L(n) asm volatile("s_waitcnt lgkmcnt(" #n ")" ::: "memory")
; #define PG8_BAR __builtin_amdgcn_s_barrier()
; template <class Epi, class Sched, bool ALIGN_EPI = false, bool SP2 = false>
; __device__ __forceinline__ void gemm_phase(PG8_LAS unsigned char* lds, const Gemm g, const Sched& S, const Epi& E, const int tid_arg) {
;     ...
;             const char* a1 = cA + (size_t)(t + 1) * kstep;
;             const char* a2 = last ? nA : cA + (size_t)(t + 2) * kstep; const char* b2 = last ? nB : cB + (size_t)(t + 2) * kstep;
;             const char* a3 = a2 + kstep; const char* b3 = b2 + kstep;
;             if (last && has_next) S.a_ready(nxt);
;             if constexpr (SP2) {
;             PG8_LDB(B0, 0, 0); PG8_LDB(B1, 0, 1); PG8_SCHED; PG8_LDA(At, 0, 0); PG8_STAGE(PG8_SA(1, 1), a1 + hstep, voffA);
;             PG8_WAIT_V(8); PG8_WAIT_L(0); PG8_BAR; PG8_MMA(0, 0, At, B0); PG8_MMA(0, 1, At, B1); PG8_BAR; PG8_SCHED;
;             PG8_LDA(At, 0, 1); PG8_STAGE(PG8_SB(0, 0), b2, voffB); PG8_STAGE(PG8_SB(0, 1), b2 + hstep, voffB); PG8_STAGE(PG8_SA(0, 0), a2, voffA);
;             PG8_WAIT_V(8); PG8_WAIT_L(0); PG8_BAR; PG8_MMA(1, 0, At, B0); PG8_MMA(1, 1, At, B1); PG8_BAR; PG8_SCHED;
.LBB0_1547:
	s_add_u32 s6, s4, 0x100
	s_addc_u32 s7, s5, 0
	s_cmp_eq_u32 s78, 12
	s_cselect_b32 s11, s13, s7
	s_cselect_b32 s10, s31, s6
	s_cselect_b32 s1, s29, s75
	s_cselect_b32 s0, s42, s43
	s_mov_b32 m0, s71
	s_nop 0
	global_load_lds_dwordx4 v196, s[4:5]
	s_mov_b32 m0, s72
	s_nop 0
	global_load_lds_dwordx4 v194, s[4:5]
	ds_read_b128 v[72:75], v207
	ds_read_b128 v[100:103], v208
	ds_read_b128 v[136:139], v209
	ds_read_b128 v[140:143], v210
	ds_read_b128 v[144:147], v211
	ds_read_b128 v[148:151], v212
	ds_read_b128 v[152:155], v213
	ds_read_b128 v[156:159], v214
	ds_read_b128 v[160:163], v206
	ds_read_b128 v[164:167], v206 offset:1024
	ds_read_b128 v[168:171], v206 offset:2048
	ds_read_b128 v[172:175], v206 offset:3072
	ds_read_b128 v[176:179], v206 offset:4096
	ds_read_b128 v[180:183], v206 offset:5120
	ds_read_b128 v[226:229], v206 offset:6144
	ds_read_b128 v[230:233], v206 offset:7168
	s_waitcnt vmcnt(8)
	s_waitcnt lgkmcnt(0)
	s_setprio 1
	s_barrier
	v_mfma_f32_16x16x32_bf16 v[132:135], v[72:75], v[160:163], v[132:135]
	v_mfma_f32_16x16x32_bf16 v[60:63], v[136:139], v[160:163], v[60:63]
	v_mfma_f32_16x16x32_bf16 v[124:127], v[72:75], v[168:171], v[124:127]
	v_mfma_f32_16x16x32_bf16 v[52:55], v[136:139], v[168:171], v[52:55]
	v_mfma_f32_16x16x32_bf16 v[116:119], v[72:75], v[176:179], v[116:119]
	v_mfma_f32_16x16x32_bf16 v[44:47], v[136:139], v[176:179], v[44:47]
	v_mfma_f32_16x16x32_bf16 v[108:111], v[72:75], v[226:229], v[108:111]
	v_mfma_f32_16x16x32_bf16 v[36:39], v[136:139], v[226:229], v[36:39]
	v_mfma_f32_16x16x32_bf16 v[132:135], v[100:103], v[164:167], v[132:135]
	v_mfma_f32_16x16x32_bf16 v[60:63], v[140:143], v[164:167], v[60:63]
	v_mfma_f32_16x16x32_bf16 v[124:127], v[100:103], v[172:175], v[124:127]
	v_mfma_f32_16x16x32_bf16 v[52:55], v[140:143], v[172:175], v[52:55]
	v_mfma_f32_16x16x32_bf16 v[116:119], v[100:103], v[180:183], v[116:119]
	v_mfma_f32_16x16x32_bf16 v[44:47], v[140:143], v[180:183], v[44:47]
	v_mfma_f32_16x16x32_bf16 v[108:111], v[100:103], v[230:233], v[108:111]
	v_mfma_f32_16x16x32_bf16 v[36:39], v[140:143], v[230:233], v[36:39]
	s_setprio 0
	s_setprio 1
	v_mfma_f32_16x16x32_bf16 v[128:131], v[144:147], v[160:163], v[128:131]
	v_mfma_f32_16x16x32_bf16 v[56:59], v[152:155], v[160:163], v[56:59]
	v_mfma_f32_16x16x32_bf16 v[120:123], v[144:147], v[168:171], v[120:123]
	v_mfma_f32_16x16x32_bf16 v[48:51], v[152:155], v[168:171], v[48:51]
	v_mfma_f32_16x16x32_bf16 v[112:115], v[144:147], v[176:179], v[112:115]
	v_mfma_f32_16x16x32_bf16 v[40:43], v[152:155], v[176:179], v[40:43]
	v_mfma_f32_16x16x32_bf16 v[104:107], v[144:147], v[226:229], v[104:107]
	v_mfma_f32_16x16x32_bf16 v[32:35], v[152:155], v[226:229], v[32:35]
	v_mfma_f32_16x16x32_bf16 v[128:131], v[148:151], v[164:167], v[128:131]
	v_mfma_f32_16x16x32_bf16 v[56:59], v[156:159], v[164:167], v[56:59]
	v_mfma_f32_16x16x32_bf16 v[120:123], v[148:151], v[172:175], v[120:123]
	v_mfma_f32_16x16x32_bf16 v[48:51], v[156:159], v[172:175], v[48:51]
	v_mfma_f32_16x16x32_bf16 v[112:115], v[148:151], v[180:183], v[112:115]
	v_mfma_f32_16x16x32_bf16 v[40:43], v[156:159], v[180:183], v[40:43]
	v_mfma_f32_16x16x32_bf16 v[104:107], v[148:151], v[230:233], v[104:107]
	v_mfma_f32_16x16x32_bf16 v[32:35], v[156:159], v[230:233], v[32:35]
	s_barrier
	s_setprio 0
	s_mov_b32 m0, s39
	s_add_u32 s98, s0, s20
	s_addc_u32 s99, s1, s21
	s_add_u32 s4, s0, 0x40000
	global_load_lds_dwordx4 v188, s[0:1]
	s_mov_b32 m0, s41
	s_addc_u32 s5, s1, 0
	global_load_lds_dwordx4 v192, s[0:1]
	s_mov_b32 m0, s47
	s_nop 0
	global_load_lds_dwordx4 v188, s[4:5]
	s_mov_b32 m0, s48
	s_nop 0
	global_load_lds_dwordx4 v192, s[4:5]
	s_add_u32 s100, s10, s20
	s_addc_u32 s101, s11, s21
	s_mov_b32 m0, s46
	s_nop 0
	global_load_lds_dwordx4 v186, s[10:11]
	s_mov_b32 m0, s49
	s_nop 0
	global_load_lds_dwordx4 v190, s[10:11]
	ds_read_b128 v[160:163], v206 offset:16384
	ds_read_b128 v[164:167], v206 offset:17408
	ds_read_b128 v[168:171], v206 offset:18432
	ds_read_b128 v[172:175], v206 offset:19456
	ds_read_b128 v[176:179], v206 offset:20480
	ds_read_b128 v[180:183], v206 offset:21504
	ds_read_b128 v[226:229], v206 offset:22528
	ds_read_b128 v[230:233], v206 offset:23552
	s_waitcnt vmcnt(8)
	s_waitcnt lgkmcnt(0)
	s_setprio 1
	s_barrier
	v_mfma_f32_16x16x32_bf16 v[96:99], v[72:75], v[160:163], v[96:99]
	v_mfma_f32_16x16x32_bf16 v[28:31], v[136:139], v[160:163], v[28:31]
	v_mfma_f32_16x16x32_bf16 v[88:91], v[72:75], v[168:171], v[88:91]
	v_mfma_f32_16x16x32_bf16 v[20:23], v[136:139], v[168:171], v[20:23]
	v_mfma_f32_16x16x32_bf16 v[80:83], v[72:75], v[176:179], v[80:83]
	v_mfma_f32_16x16x32_bf16 v[12:15], v[136:139], v[176:179], v[12:15]
	v_mfma_f32_16x16x32_bf16 v[68:71], v[72:75], v[226:229], v[68:71]
	v_mfma_f32_16x16x32_bf16 v[4:7], v[136:139], v[226:229], v[4:7]
	v_mfma_f32_16x16x32_bf16 v[96:99], v[100:103], v[164:167], v[96:99]
	v_mfma_f32_16x16x32_bf16 v[28:31], v[140:143], v[164:167], v[28:31]
	v_mfma_f32_16x16x32_bf16 v[88:91], v[100:103], v[172:175], v[88:91]
	v_mfma_f32_16x16x32_bf16 v[20:23], v[140:143], v[172:175], v[20:23]
	v_mfma_f32_16x16x32_bf16 v[80:83], v[100:103], v[180:183], v[80:83]
	v_mfma_f32_16x16x32_bf16 v[12:15], v[140:143], v[180:183], v[12:15]
	v_mfma_f32_16x16x32_bf16 v[68:71], v[100:103], v[230:233], v[68:71]
	v_mfma_f32_16x16x32_bf16 v[4:7], v[140:143], v[230:233], v[4:7]
	s_setprio 0
	s_setprio 1
	v_mfma_f32_16x16x32_bf16 v[24:27], v[152:155], v[160:163], v[24:27]
	v_mfma_f32_16x16x32_bf16 v[84:87], v[144:147], v[168:171], v[84:87]
	v_mfma_f32_16x16x32_bf16 v[16:19], v[152:155], v[168:171], v[16:19]
	v_mfma_f32_16x16x32_bf16 v[76:79], v[144:147], v[176:179], v[76:79]
	v_mfma_f32_16x16x32_bf16 v[8:11], v[152:155], v[176:179], v[8:11]
	v_mfma_f32_16x16x32_bf16 v[64:67], v[144:147], v[226:229], v[64:67]
	v_mfma_f32_16x16x32_bf16 v[0:3], v[152:155], v[226:229], v[0:3]
	v_mfma_f32_16x16x32_bf16 v[72:75], v[144:147], v[160:163], v[92:95]
	v_mfma_f32_16x16x32_bf16 v[24:27], v[156:159], v[164:167], v[24:27]
	v_mfma_f32_16x16x32_bf16 v[84:87], v[148:151], v[172:175], v[84:87]
	v_mfma_f32_16x16x32_bf16 v[16:19], v[156:159], v[172:175], v[16:19]
	v_mfma_f32_16x16x32_bf16 v[76:79], v[148:151], v[180:183], v[76:79]
	v_mfma_f32_16x16x32_bf16 v[8:11], v[156:159], v[180:183], v[8:11]
	v_mfma_f32_16x16x32_bf16 v[64:67], v[148:151], v[230:233], v[64:67]
	v_mfma_f32_16x16x32_bf16 v[0:3], v[156:159], v[230:233], v[0:3]
	v_mfma_f32_16x16x32_bf16 v[72:75], v[148:151], v[164:167], v[72:75]
	s_barrier
; #define PG8_STAGE(bufoff, gbase, voff) do { _Pragma("unroll") for (int _i = 0; _i < 2; ++_i) \
;         __builtin_amdgcn_global_load_lds((const unsigned*)((const char*)(gbase) + (voff)[_i]), (PG8_LAS unsigned*)(lds + (bufoff) + ldsw + _i * 8192), 16, 0, 0); } while (0)
; #define PG8_LDA(dst, b, h) do { _Pragma("unroll") for (int m = 0; m < 4; ++m) _Pragma("unroll") for (int k = 0; k < 2; ++k) dst[m][k] = *(const PG8_LAS bf16x8*)(lds + PG8_SA(b, h) + aoff + m * 2048 + k * 1024); } while (0)
; #define PG8_LDB(dst, b, h) do { _Pragma("unroll") for (int n = 0; n < 2; ++n) _Pragma("unroll") for (int k = 0; k < 2; ++k) dst[n][k] = *(const PG8_LAS bf16x8*)(lds + PG8_SB(b, h) + boff + n * 2048 + k * 1024); } while (0)
; #define PG8_MMA(ai, bj, At, Bt) do { __builtin_amdgcn_s_setprio(1); _Pragma("unroll") for (int m = 0; m < 4; ++m) _Pragma("unroll") for (int n = 0; n < 2; ++n) _Pragma("unroll") for (int k = 0; k < 2; ++k) \
;         acc[ai][bj][m][n] = __builtin_amdgcn_mfma_f32_16x16x32_bf16(Bt[n][k], At[m][k], acc[ai][bj][m][n], 0, 0, 0); __builtin_amdgcn_s_setprio(0); } while (0)
; #define PG8_WAIT_V(n) asm volatile("s_waitcnt vmcnt(" #n ")" ::: "memory")
; #define PG8_WAIT_L(n) asm volatile("s_waitcnt lgkmcnt(" #n ")" ::: "memory")
; #define PG8_BAR __builtin_amdgcn_s_barrier()
; #define PG8_SCHED __builtin_amdgcn_sched_barrier(0)
; template <class Epi, class Sched, bool ALIGN_EPI = false, bool SP2 = false>
; __device__ __forceinline__ void gemm_phase(PG8_LAS unsigned char* lds, const Gemm g, const Sched& S, const Epi& E, const int tid_arg) {
;     ...
;             PG8_LDB(B0, 1, 0); PG8_LDB(B1, 1, 1); PG8_SCHED; PG8_LDA(At, 1, 0); PG8_STAGE(PG8_SA(0, 1), a2 + hstep, voffA);
;             PG8_WAIT_V(8); PG8_WAIT_L(0); PG8_BAR; PG8_MMA(0, 0, At, B0); PG8_MMA(0, 1, At, B1); PG8_BAR; PG8_SCHED;
;             PG8_LDA(At, 1, 1); PG8_STAGE(PG8_SB(1, 0), b3, voffB); PG8_STAGE(PG8_SB(1, 1), b3 + hstep, voffB); PG8_STAGE(PG8_SA(1, 0), a3, voffA);
;             PG8_WAIT_V(8); PG8_WAIT_L(0); PG8_BAR; PG8_MMA(1, 0, At, B0); PG8_MMA(1, 1, At, B1); PG8_BAR; PG8_SCHED;
	s_setprio 0
	s_add_u32 s4, s10, 0x40000
	s_addc_u32 s5, s11, 0
	s_mov_b32 m0, s50
	s_nop 0
	global_load_lds_dwordx4 v186, s[4:5]
	s_mov_b32 m0, s51
	s_nop 0
	global_load_lds_dwordx4 v190, s[4:5]
	ds_read_b128 v[92:95], v215
	ds_read_b128 v[100:103], v216
	ds_read_b128 v[136:139], v217
	ds_read_b128 v[140:143], v218
	ds_read_b128 v[144:147], v219
	ds_read_b128 v[148:151], v220
	ds_read_b128 v[152:155], v221
	ds_read_b128 v[156:159], v222
	ds_read_b128 v[160:163], v206 offset:32768
	ds_read_b128 v[164:167], v206 offset:33792
	ds_read_b128 v[168:171], v206 offset:34816
	ds_read_b128 v[172:175], v206 offset:35840
	ds_read_b128 v[176:179], v206 offset:36864
	ds_read_b128 v[180:183], v206 offset:37888
	ds_read_b128 v[226:229], v206 offset:38912
	ds_read_b128 v[230:233], v206 offset:39936
	s_waitcnt vmcnt(8)
	s_waitcnt lgkmcnt(0)
	s_setprio 1
	s_barrier
	v_mfma_f32_16x16x32_bf16 v[132:135], v[92:95], v[160:163], v[132:135]
	v_mfma_f32_16x16x32_bf16 v[60:63], v[136:139], v[160:163], v[60:63]
	v_mfma_f32_16x16x32_bf16 v[124:127], v[92:95], v[168:171], v[124:127]
	v_mfma_f32_16x16x32_bf16 v[52:55], v[136:139], v[168:171], v[52:55]
	v_mfma_f32_16x16x32_bf16 v[116:119], v[92:95], v[176:179], v[116:119]
	v_mfma_f32_16x16x32_bf16 v[44:47], v[136:139], v[176:179], v[44:47]
	v_mfma_f32_16x16x32_bf16 v[108:111], v[92:95], v[226:229], v[108:111]
	v_mfma_f32_16x16x32_bf16 v[36:39], v[136:139], v[226:229], v[36:39]
	v_mfma_f32_16x16x32_bf16 v[132:135], v[100:103], v[164:167], v[132:135]
	v_mfma_f32_16x16x32_bf16 v[60:63], v[140:143], v[164:167], v[60:63]
	v_mfma_f32_16x16x32_bf16 v[124:127], v[100:103], v[172:175], v[124:127]
	v_mfma_f32_16x16x32_bf16 v[52:55], v[140:143], v[172:175], v[52:55]
	v_mfma_f32_16x16x32_bf16 v[116:119], v[100:103], v[180:183], v[116:119]
	v_mfma_f32_16x16x32_bf16 v[44:47], v[140:143], v[180:183], v[44:47]
	v_mfma_f32_16x16x32_bf16 v[108:111], v[100:103], v[230:233], v[108:111]
	v_mfma_f32_16x16x32_bf16 v[36:39], v[140:143], v[230:233], v[36:39]
	s_setprio 0
	s_setprio 1
	v_mfma_f32_16x16x32_bf16 v[128:131], v[144:147], v[160:163], v[128:131]
	v_mfma_f32_16x16x32_bf16 v[56:59], v[152:155], v[160:163], v[56:59]
	v_mfma_f32_16x16x32_bf16 v[120:123], v[144:147], v[168:171], v[120:123]
	v_mfma_f32_16x16x32_bf16 v[48:51], v[152:155], v[168:171], v[48:51]
	v_mfma_f32_16x16x32_bf16 v[112:115], v[144:147], v[176:179], v[112:115]
	v_mfma_f32_16x16x32_bf16 v[40:43], v[152:155], v[176:179], v[40:43]
	v_mfma_f32_16x16x32_bf16 v[104:107], v[144:147], v[226:229], v[104:107]
	v_mfma_f32_16x16x32_bf16 v[32:35], v[152:155], v[226:229], v[32:35]
	v_mfma_f32_16x16x32_bf16 v[128:131], v[148:151], v[164:167], v[128:131]
	v_mfma_f32_16x16x32_bf16 v[56:59], v[156:159], v[164:167], v[56:59]
	v_mfma_f32_16x16x32_bf16 v[120:123], v[148:151], v[172:175], v[120:123]
	v_mfma_f32_16x16x32_bf16 v[48:51], v[156:159], v[172:175], v[48:51]
	v_mfma_f32_16x16x32_bf16 v[112:115], v[148:151], v[180:183], v[112:115]
	v_mfma_f32_16x16x32_bf16 v[40:43], v[156:159], v[180:183], v[40:43]
	v_mfma_f32_16x16x32_bf16 v[104:107], v[148:151], v[230:233], v[104:107]
	v_mfma_f32_16x16x32_bf16 v[32:35], v[156:159], v[230:233], v[32:35]
	s_barrier
	s_setprio 0
	s_mov_b32 m0, s60
	s_add_u32 s0, s0, 0x40080
	global_load_lds_dwordx4 v188, s[98:99]
	s_mov_b32 m0, s61
	s_addc_u32 s1, s1, 0
	global_load_lds_dwordx4 v192, s[98:99]
	s_mov_b32 m0, s64
	s_nop 0
	global_load_lds_dwordx4 v188, s[0:1]
	s_mov_b32 m0, s65
	s_nop 0
	global_load_lds_dwordx4 v192, s[0:1]
	s_mov_b32 m0, s62
	s_nop 0
	global_load_lds_dwordx4 v186, s[100:101]
	s_mov_b32 m0, s63
	s_nop 0
	global_load_lds_dwordx4 v190, s[100:101]
	ds_read_b128 v[160:163], v206 offset:49152
	ds_read_b128 v[164:167], v206 offset:50176
	ds_read_b128 v[168:171], v206 offset:51200
	ds_read_b128 v[172:175], v206 offset:52224
	ds_read_b128 v[176:179], v206 offset:53248
	ds_read_b128 v[180:183], v206 offset:54272
	ds_read_b128 v[226:229], v206 offset:55296
	ds_read_b128 v[230:233], v206 offset:56320
	s_waitcnt vmcnt(8)
	s_waitcnt lgkmcnt(0)
	s_setprio 1
	s_barrier
	v_mfma_f32_16x16x32_bf16 v[96:99], v[92:95], v[160:163], v[96:99]
	v_mfma_f32_16x16x32_bf16 v[28:31], v[136:139], v[160:163], v[28:31]
	v_mfma_f32_16x16x32_bf16 v[88:91], v[92:95], v[168:171], v[88:91]
	v_mfma_f32_16x16x32_bf16 v[20:23], v[136:139], v[168:171], v[20:23]
	v_mfma_f32_16x16x32_bf16 v[80:83], v[92:95], v[176:179], v[80:83]
	v_mfma_f32_16x16x32_bf16 v[12:15], v[136:139], v[176:179], v[12:15]
	v_mfma_f32_16x16x32_bf16 v[68:71], v[92:95], v[226:229], v[68:71]
	v_mfma_f32_16x16x32_bf16 v[4:7], v[136:139], v[226:229], v[4:7]
	v_mfma_f32_16x16x32_bf16 v[96:99], v[100:103], v[164:167], v[96:99]
	v_mfma_f32_16x16x32_bf16 v[28:31], v[140:143], v[164:167], v[28:31]
	v_mfma_f32_16x16x32_bf16 v[88:91], v[100:103], v[172:175], v[88:91]
	v_mfma_f32_16x16x32_bf16 v[20:23], v[140:143], v[172:175], v[20:23]
	v_mfma_f32_16x16x32_bf16 v[80:83], v[100:103], v[180:183], v[80:83]
	v_mfma_f32_16x16x32_bf16 v[12:15], v[140:143], v[180:183], v[12:15]
	v_mfma_f32_16x16x32_bf16 v[68:71], v[100:103], v[230:233], v[68:71]
	v_mfma_f32_16x16x32_bf16 v[4:7], v[140:143], v[230:233], v[4:7]
	s_setprio 0
	s_setprio 1
	v_mfma_f32_16x16x32_bf16 v[72:75], v[144:147], v[160:163], v[72:75]
	v_mfma_f32_16x16x32_bf16 v[92:95], v[148:151], v[164:167], v[72:75]
	v_mfma_f32_16x16x32_bf16 v[72:75], v[144:147], v[168:171], v[84:87]
	v_mfma_f32_16x16x32_bf16 v[24:27], v[152:155], v[160:163], v[24:27]
	v_mfma_f32_16x16x32_bf16 v[84:87], v[148:151], v[172:175], v[72:75]
	v_mfma_f32_16x16x32_bf16 v[16:19], v[152:155], v[168:171], v[16:19]
	v_mfma_f32_16x16x32_bf16 v[72:75], v[144:147], v[176:179], v[76:79]
	v_mfma_f32_16x16x32_bf16 v[8:11], v[152:155], v[176:179], v[8:11]
	v_mfma_f32_16x16x32_bf16 v[64:67], v[144:147], v[226:229], v[64:67]
	v_mfma_f32_16x16x32_bf16 v[0:3], v[152:155], v[226:229], v[0:3]
	v_mfma_f32_16x16x32_bf16 v[24:27], v[156:159], v[164:167], v[24:27]
	v_mfma_f32_16x16x32_bf16 v[16:19], v[156:159], v[172:175], v[16:19]
	v_mfma_f32_16x16x32_bf16 v[76:79], v[148:151], v[180:183], v[72:75]
	v_mfma_f32_16x16x32_bf16 v[8:11], v[156:159], v[180:183], v[8:11]
	v_mfma_f32_16x16x32_bf16 v[64:67], v[148:151], v[230:233], v[64:67]
	v_mfma_f32_16x16x32_bf16 v[0:3], v[156:159], v[230:233], v[0:3]
	s_barrier
	s_setprio 0
	s_add_i32 s78, s78, 2
	s_add_u32 s43, s43, 0x100
	s_addc_u32 s75, s75, 0
	s_cmp_gt_u32 s78, 13
	s_mov_b64 s[4:5], s[6:7]
	s_cbranch_scc0 .LBB0_1547
	s_and_b64 vcc, exec, s[22:23]
	s_cbranch_vccz .LBB0_1550
	s_barrier

; #define PG8_STAGE(bufoff, gbase, voff) do { _Pragma("unroll") for (int _i = 0; _i < 2; ++_i) \
;         __builtin_amdgcn_global_load_lds((const unsigned*)((const char*)(gbase) + (voff)[_i]), (PG8_LAS unsigned*)(lds + (bufoff) + ldsw + _i * 8192), 16, 0, 0); } while (0)
; #define PG8_LDA(dst, b, h) do { _Pragma("unroll") for (int m = 0; m < 4; ++m) _Pragma("unroll") for (int k = 0; k < 2; ++k) dst[m][k] = *(const PG8_LAS bf16x8*)(lds + PG8_SA(b, h) + aoff + m * 2048 + k * 1024); } while (0)
; #define PG8_LDB(dst, b, h) do { _Pragma("unroll") for (int n = 0; n < 2; ++n) _Pragma("unroll") for (int k = 0; k < 2; ++k) dst[n][k] = *(const PG8_LAS bf16x8*)(lds + PG8_SB(b, h) + boff + n * 2048 + k * 1024); } while (0)
; #define PG8_MMA(ai, bj, At, Bt) do { __builtin_amdgcn_s_setprio(1); _Pragma("unroll") for (int m = 0; m < 4; ++m) _Pragma("unroll") for (int n = 0; n < 2; ++n) _Pragma("unroll") for (int k = 0; k < 2; ++k) \
;         acc[ai][bj][m][n] = __builtin_amdgcn_mfma_f32_16x16x32_bf16(Bt[n][k], At[m][k], acc[ai][bj][m][n], 0, 0, 0); __builtin_amdgcn_s_setprio(0); } while (0)
; #define PG8_WAIT_V(n) asm volatile("s_waitcnt vmcnt(" #n ")" ::: "memory")
; #define PG8_WAIT_L(n) asm volatile("s_waitcnt lgkmcnt(" #n ")" ::: "memory")
; #define PG8_BAR __builtin_amdgcn_s_barrier()
; template <class Epi, class Sched, bool ALIGN_EPI = false, bool SP2 = false>
; __device__ __forceinline__ void gemm_phase(PG8_LAS unsigned char* lds, const Gemm g, const Sched& S, const Epi& E, const int tid_arg) {
;     ...
;             const char* a1 = cA + (size_t)(t + 1) * kstep;
;             const char* a2 = last ? nA : cA + (size_t)(t + 2) * kstep; const char* b2 = last ? nB : cB + (size_t)(t + 2) * kstep;
;             const char* a3 = a2 + kstep; const char* b3 = b2 + kstep;
;             if (last && has_next) S.a_ready(nxt);
;             if constexpr (SP2) {
;             PG8_LDB(B0, 0, 0); PG8_LDB(B1, 0, 1); PG8_SCHED; PG8_LDA(At, 0, 0); PG8_STAGE(PG8_SA(1, 1), a1 + hstep, voffA);
;             PG8_WAIT_V(8); PG8_WAIT_L(0); PG8_BAR; PG8_MMA(0, 0, At, B0); PG8_MMA(0, 1, At, B1); PG8_BAR; PG8_SCHED;
;             PG8_LDA(At, 0, 1); PG8_STAGE(PG8_SB(0, 0), b2, voffB); PG8_STAGE(PG8_SB(0, 1), b2 + hstep, voffB); PG8_STAGE(PG8_SA(0, 0), a2, voffA);
;             PG8_WAIT_V(8); PG8_WAIT_L(0); PG8_BAR; PG8_MMA(1, 0, At, B0); PG8_MMA(1, 1, At, B1); PG8_BAR; PG8_SCHED;
.LBB0_1733:
	s_add_u32 s22, s4, 0x100
	s_addc_u32 s23, s5, 0
	s_cmp_eq_u32 s57, 40
	s_cselect_b32 s25, s9, s23
	s_cselect_b32 s24, s8, s22
	s_cselect_b32 s1, s21, s56
	s_cselect_b32 s0, s20, s55
	s_mov_b32 m0, s48
	s_nop 0
	global_load_lds_dwordx4 v138, s[4:5]
	s_mov_b32 m0, s49
	s_nop 0
	global_load_lds_dwordx4 v136, s[4:5]
	ds_read_b128 v[144:147], v151
	ds_read_b128 v[168:171], v152
	ds_read_b128 v[172:175], v153
	ds_read_b128 v[176:179], v154
	ds_read_b128 v[180:183], v155
	ds_read_b128 v[184:187], v156
	ds_read_b128 v[188:191], v157
	ds_read_b128 v[192:195], v158
	ds_read_b128 v[196:199], v150
	ds_read_b128 v[200:203], v150 offset:1024
	ds_read_b128 v[204:207], v150 offset:2048
	ds_read_b128 v[208:211], v150 offset:3072
	ds_read_b128 v[212:215], v150 offset:4096
	ds_read_b128 v[216:219], v150 offset:5120
	ds_read_b128 v[220:223], v150 offset:6144
	ds_read_b128 v[224:227], v150 offset:7168
	s_waitcnt vmcnt(8)
	s_waitcnt lgkmcnt(0)
	s_setprio 1
	s_barrier
	v_mfma_f32_16x16x32_bf16 v[124:127], v[144:147], v[196:199], v[124:127]
	v_mfma_f32_16x16x32_bf16 v[120:123], v[172:175], v[196:199], v[120:123]
	v_mfma_f32_16x16x32_bf16 v[108:111], v[144:147], v[204:207], v[108:111]
	v_mfma_f32_16x16x32_bf16 v[104:107], v[172:175], v[204:207], v[104:107]
	v_mfma_f32_16x16x32_bf16 v[92:95], v[144:147], v[212:215], v[92:95]
	v_mfma_f32_16x16x32_bf16 v[88:91], v[172:175], v[212:215], v[88:91]
	v_mfma_f32_16x16x32_bf16 v[76:79], v[144:147], v[220:223], v[76:79]
	v_mfma_f32_16x16x32_bf16 v[72:75], v[172:175], v[220:223], v[72:75]
	v_mfma_f32_16x16x32_bf16 v[124:127], v[168:171], v[200:203], v[124:127]
	v_mfma_f32_16x16x32_bf16 v[120:123], v[176:179], v[200:203], v[120:123]
	v_mfma_f32_16x16x32_bf16 v[108:111], v[168:171], v[208:211], v[108:111]
	v_mfma_f32_16x16x32_bf16 v[104:107], v[176:179], v[208:211], v[104:107]
	v_mfma_f32_16x16x32_bf16 v[92:95], v[168:171], v[216:219], v[92:95]
	v_mfma_f32_16x16x32_bf16 v[88:91], v[176:179], v[216:219], v[88:91]
	v_mfma_f32_16x16x32_bf16 v[76:79], v[168:171], v[224:227], v[76:79]
	v_mfma_f32_16x16x32_bf16 v[72:75], v[176:179], v[224:227], v[72:75]
	s_setprio 0
	s_setprio 1
	v_mfma_f32_16x16x32_bf16 v[116:119], v[180:183], v[196:199], v[116:119]
	v_mfma_f32_16x16x32_bf16 v[112:115], v[188:191], v[196:199], v[112:115]
	v_mfma_f32_16x16x32_bf16 v[100:103], v[180:183], v[204:207], v[100:103]
	v_mfma_f32_16x16x32_bf16 v[96:99], v[188:191], v[204:207], v[96:99]
	v_mfma_f32_16x16x32_bf16 v[84:87], v[180:183], v[212:215], v[84:87]
	v_mfma_f32_16x16x32_bf16 v[80:83], v[188:191], v[212:215], v[80:83]
	v_mfma_f32_16x16x32_bf16 v[68:71], v[180:183], v[220:223], v[68:71]
	v_mfma_f32_16x16x32_bf16 v[64:67], v[188:191], v[220:223], v[64:67]
	v_mfma_f32_16x16x32_bf16 v[116:119], v[184:187], v[200:203], v[116:119]
	v_mfma_f32_16x16x32_bf16 v[112:115], v[192:195], v[200:203], v[112:115]
	v_mfma_f32_16x16x32_bf16 v[100:103], v[184:187], v[208:211], v[100:103]
	v_mfma_f32_16x16x32_bf16 v[96:99], v[192:195], v[208:211], v[96:99]
	v_mfma_f32_16x16x32_bf16 v[84:87], v[184:187], v[216:219], v[84:87]
	v_mfma_f32_16x16x32_bf16 v[80:83], v[192:195], v[216:219], v[80:83]
	v_mfma_f32_16x16x32_bf16 v[68:71], v[184:187], v[224:227], v[68:71]
	v_mfma_f32_16x16x32_bf16 v[64:67], v[192:195], v[224:227], v[64:67]
	s_barrier
	s_setprio 0
	s_mov_b32 m0, s29
	s_add_u32 s98, s0, s16
	s_addc_u32 s99, s1, s17
	s_add_u32 s4, s0, 0xb0000
	global_load_lds_dwordx4 v130, s[0:1]
	s_mov_b32 m0, s30
	s_addc_u32 s5, s1, 0
	global_load_lds_dwordx4 v134, s[0:1]
	s_mov_b32 m0, s31
	s_nop 0
	global_load_lds_dwordx4 v130, s[4:5]
	s_mov_b32 m0, s33
	s_nop 0
	global_load_lds_dwordx4 v134, s[4:5]
	s_add_u32 s100, s24, s16
	s_addc_u32 s101, s25, s17
	s_mov_b32 m0, s28
	s_nop 0
	global_load_lds_dwordx4 v128, s[24:25]
	s_mov_b32 m0, s34
	s_nop 0
	global_load_lds_dwordx4 v132, s[24:25]
	ds_read_b128 v[196:199], v150 offset:16384
	ds_read_b128 v[200:203], v150 offset:17408
	ds_read_b128 v[204:207], v150 offset:18432
	ds_read_b128 v[208:211], v150 offset:19456
	ds_read_b128 v[212:215], v150 offset:20480
	ds_read_b128 v[216:219], v150 offset:21504
	ds_read_b128 v[220:223], v150 offset:22528
	ds_read_b128 v[224:227], v150 offset:23552
	s_waitcnt vmcnt(8)
	s_waitcnt lgkmcnt(0)
	s_setprio 1
	s_barrier
	v_mfma_f32_16x16x32_bf16 v[60:63], v[144:147], v[196:199], v[60:63]
	v_mfma_f32_16x16x32_bf16 v[56:59], v[172:175], v[196:199], v[56:59]
	v_mfma_f32_16x16x32_bf16 v[44:47], v[144:147], v[204:207], v[44:47]
	v_mfma_f32_16x16x32_bf16 v[40:43], v[172:175], v[204:207], v[40:43]
	v_mfma_f32_16x16x32_bf16 v[28:31], v[144:147], v[212:215], v[28:31]
	v_mfma_f32_16x16x32_bf16 v[24:27], v[172:175], v[212:215], v[24:27]
	v_mfma_f32_16x16x32_bf16 v[12:15], v[144:147], v[220:223], v[12:15]
	v_mfma_f32_16x16x32_bf16 v[8:11], v[172:175], v[220:223], v[8:11]
	v_mfma_f32_16x16x32_bf16 v[60:63], v[168:171], v[200:203], v[60:63]
	v_mfma_f32_16x16x32_bf16 v[56:59], v[176:179], v[200:203], v[56:59]
	v_mfma_f32_16x16x32_bf16 v[44:47], v[168:171], v[208:211], v[44:47]
	v_mfma_f32_16x16x32_bf16 v[40:43], v[176:179], v[208:211], v[40:43]
	v_mfma_f32_16x16x32_bf16 v[28:31], v[168:171], v[216:219], v[28:31]
	v_mfma_f32_16x16x32_bf16 v[24:27], v[176:179], v[216:219], v[24:27]
	v_mfma_f32_16x16x32_bf16 v[12:15], v[168:171], v[224:227], v[12:15]
	v_mfma_f32_16x16x32_bf16 v[8:11], v[176:179], v[224:227], v[8:11]
	s_setprio 0
	s_setprio 1
	v_mfma_f32_16x16x32_bf16 v[52:55], v[180:183], v[196:199], v[52:55]
	v_mfma_f32_16x16x32_bf16 v[48:51], v[188:191], v[196:199], v[48:51]
	v_mfma_f32_16x16x32_bf16 v[36:39], v[180:183], v[204:207], v[36:39]
	v_mfma_f32_16x16x32_bf16 v[32:35], v[188:191], v[204:207], v[32:35]
	v_mfma_f32_16x16x32_bf16 v[20:23], v[180:183], v[212:215], v[20:23]
	v_mfma_f32_16x16x32_bf16 v[16:19], v[188:191], v[212:215], v[16:19]
	v_mfma_f32_16x16x32_bf16 v[4:7], v[180:183], v[220:223], v[4:7]
	v_mfma_f32_16x16x32_bf16 v[0:3], v[188:191], v[220:223], v[0:3]
	v_mfma_f32_16x16x32_bf16 v[52:55], v[184:187], v[200:203], v[52:55]
	v_mfma_f32_16x16x32_bf16 v[48:51], v[192:195], v[200:203], v[48:51]
	v_mfma_f32_16x16x32_bf16 v[36:39], v[184:187], v[208:211], v[36:39]
	v_mfma_f32_16x16x32_bf16 v[32:35], v[192:195], v[208:211], v[32:35]
	v_mfma_f32_16x16x32_bf16 v[20:23], v[184:187], v[216:219], v[20:23]
	v_mfma_f32_16x16x32_bf16 v[16:19], v[192:195], v[216:219], v[16:19]
	v_mfma_f32_16x16x32_bf16 v[4:7], v[184:187], v[224:227], v[4:7]
	v_mfma_f32_16x16x32_bf16 v[0:3], v[192:195], v[224:227], v[0:3]
	s_barrier
; #define PG8_STAGE(bufoff, gbase, voff) do { _Pragma("unroll") for (int _i = 0; _i < 2; ++_i) \
;         __builtin_amdgcn_global_load_lds((const unsigned*)((const char*)(gbase) + (voff)[_i]), (PG8_LAS unsigned*)(lds + (bufoff) + ldsw + _i * 8192), 16, 0, 0); } while (0)
; #define PG8_LDA(dst, b, h) do { _Pragma("unroll") for (int m = 0; m < 4; ++m) _Pragma("unroll") for (int k = 0; k < 2; ++k) dst[m][k] = *(const PG8_LAS bf16x8*)(lds + PG8_SA(b, h) + aoff + m * 2048 + k * 1024); } while (0)
; #define PG8_LDB(dst, b, h) do { _Pragma("unroll") for (int n = 0; n < 2; ++n) _Pragma("unroll") for (int k = 0; k < 2; ++k) dst[n][k] = *(const PG8_LAS bf16x8*)(lds + PG8_SB(b, h) + boff + n * 2048 + k * 1024); } while (0)
; #define PG8_MMA(ai, bj, At, Bt) do { __builtin_amdgcn_s_setprio(1); _Pragma("unroll") for (int m = 0; m < 4; ++m) _Pragma("unroll") for (int n = 0; n < 2; ++n) _Pragma("unroll") for (int k = 0; k < 2; ++k) \
;         acc[ai][bj][m][n] = __builtin_amdgcn_mfma_f32_16x16x32_bf16(Bt[n][k], At[m][k], acc[ai][bj][m][n], 0, 0, 0); __builtin_amdgcn_s_setprio(0); } while (0)
; #define PG8_WAIT_V(n) asm volatile("s_waitcnt vmcnt(" #n ")" ::: "memory")
; #define PG8_WAIT_L(n) asm volatile("s_waitcnt lgkmcnt(" #n ")" ::: "memory")
; #define PG8_BAR __builtin_amdgcn_s_barrier()
; #define PG8_SCHED __builtin_amdgcn_sched_barrier(0)
; template <class Epi, class Sched, bool ALIGN_EPI = false, bool SP2 = false>
; __device__ __forceinline__ void gemm_phase(PG8_LAS unsigned char* lds, const Gemm g, const Sched& S, const Epi& E, const int tid_arg) {
;     ...
;             PG8_LDB(B0, 1, 0); PG8_LDB(B1, 1, 1); PG8_SCHED; PG8_LDA(At, 1, 0); PG8_STAGE(PG8_SA(0, 1), a2 + hstep, voffA);
;             PG8_WAIT_V(8); PG8_WAIT_L(0); PG8_BAR; PG8_MMA(0, 0, At, B0); PG8_MMA(0, 1, At, B1); PG8_BAR; PG8_SCHED;
;             PG8_LDA(At, 1, 1); PG8_STAGE(PG8_SB(1, 0), b3, voffB); PG8_STAGE(PG8_SB(1, 1), b3 + hstep, voffB); PG8_STAGE(PG8_SA(1, 0), a3, voffA);
;             PG8_WAIT_V(8); PG8_WAIT_L(0); PG8_BAR; PG8_MMA(1, 0, At, B0); PG8_MMA(1, 1, At, B1); PG8_BAR; PG8_SCHED;
	s_setprio 0
	s_add_u32 s4, s24, 0xb0000
	s_addc_u32 s5, s25, 0
	s_mov_b32 m0, s35
	s_nop 0
	global_load_lds_dwordx4 v128, s[4:5]
	s_mov_b32 m0, s36
	s_nop 0
	global_load_lds_dwordx4 v132, s[4:5]
	ds_read_b128 v[144:147], v159
	ds_read_b128 v[168:171], v160
	ds_read_b128 v[172:175], v161
	ds_read_b128 v[176:179], v162
	ds_read_b128 v[180:183], v163
	ds_read_b128 v[184:187], v164
	ds_read_b128 v[188:191], v165
	ds_read_b128 v[192:195], v166
	ds_read_b128 v[196:199], v150 offset:32768
	ds_read_b128 v[200:203], v150 offset:33792
	ds_read_b128 v[204:207], v150 offset:34816
	ds_read_b128 v[208:211], v150 offset:35840
	ds_read_b128 v[212:215], v150 offset:36864
	ds_read_b128 v[216:219], v150 offset:37888
	ds_read_b128 v[220:223], v150 offset:38912
	ds_read_b128 v[224:227], v150 offset:39936
	s_waitcnt vmcnt(8)
	s_waitcnt lgkmcnt(0)
	s_setprio 1
	s_barrier
	v_mfma_f32_16x16x32_bf16 v[124:127], v[144:147], v[196:199], v[124:127]
	v_mfma_f32_16x16x32_bf16 v[120:123], v[172:175], v[196:199], v[120:123]
	v_mfma_f32_16x16x32_bf16 v[108:111], v[144:147], v[204:207], v[108:111]
	v_mfma_f32_16x16x32_bf16 v[104:107], v[172:175], v[204:207], v[104:107]
	v_mfma_f32_16x16x32_bf16 v[92:95], v[144:147], v[212:215], v[92:95]
	v_mfma_f32_16x16x32_bf16 v[88:91], v[172:175], v[212:215], v[88:91]
	v_mfma_f32_16x16x32_bf16 v[76:79], v[144:147], v[220:223], v[76:79]
	v_mfma_f32_16x16x32_bf16 v[72:75], v[172:175], v[220:223], v[72:75]
	v_mfma_f32_16x16x32_bf16 v[124:127], v[168:171], v[200:203], v[124:127]
	v_mfma_f32_16x16x32_bf16 v[120:123], v[176:179], v[200:203], v[120:123]
	v_mfma_f32_16x16x32_bf16 v[108:111], v[168:171], v[208:211], v[108:111]
	v_mfma_f32_16x16x32_bf16 v[104:107], v[176:179], v[208:211], v[104:107]
	v_mfma_f32_16x16x32_bf16 v[92:95], v[168:171], v[216:219], v[92:95]
	v_mfma_f32_16x16x32_bf16 v[88:91], v[176:179], v[216:219], v[88:91]
	v_mfma_f32_16x16x32_bf16 v[76:79], v[168:171], v[224:227], v[76:79]
	v_mfma_f32_16x16x32_bf16 v[72:75], v[176:179], v[224:227], v[72:75]
	s_setprio 0
	s_setprio 1
	v_mfma_f32_16x16x32_bf16 v[116:119], v[180:183], v[196:199], v[116:119]
	v_mfma_f32_16x16x32_bf16 v[112:115], v[188:191], v[196:199], v[112:115]
	v_mfma_f32_16x16x32_bf16 v[100:103], v[180:183], v[204:207], v[100:103]
	v_mfma_f32_16x16x32_bf16 v[96:99], v[188:191], v[204:207], v[96:99]
	v_mfma_f32_16x16x32_bf16 v[84:87], v[180:183], v[212:215], v[84:87]
	v_mfma_f32_16x16x32_bf16 v[80:83], v[188:191], v[212:215], v[80:83]
	v_mfma_f32_16x16x32_bf16 v[68:71], v[180:183], v[220:223], v[68:71]
	v_mfma_f32_16x16x32_bf16 v[64:67], v[188:191], v[220:223], v[64:67]
	v_mfma_f32_16x16x32_bf16 v[116:119], v[184:187], v[200:203], v[116:119]
	v_mfma_f32_16x16x32_bf16 v[112:115], v[192:195], v[200:203], v[112:115]
	v_mfma_f32_16x16x32_bf16 v[100:103], v[184:187], v[208:211], v[100:103]
	v_mfma_f32_16x16x32_bf16 v[96:99], v[192:195], v[208:211], v[96:99]
	v_mfma_f32_16x16x32_bf16 v[84:87], v[184:187], v[216:219], v[84:87]
	v_mfma_f32_16x16x32_bf16 v[80:83], v[192:195], v[216:219], v[80:83]
	v_mfma_f32_16x16x32_bf16 v[68:71], v[184:187], v[224:227], v[68:71]
	v_mfma_f32_16x16x32_bf16 v[64:67], v[192:195], v[224:227], v[64:67]
	s_barrier
	s_setprio 0
	s_mov_b32 m0, s40
	s_add_u32 s0, s0, 0xb0080
	global_load_lds_dwordx4 v130, s[98:99]
	s_mov_b32 m0, s41
	s_addc_u32 s1, s1, 0
	global_load_lds_dwordx4 v134, s[98:99]
	s_mov_b32 m0, s44
	s_nop 0
	global_load_lds_dwordx4 v130, s[0:1]
	s_mov_b32 m0, s45
	s_nop 0
	global_load_lds_dwordx4 v134, s[0:1]
	s_mov_b32 m0, s42
	s_nop 0
	global_load_lds_dwordx4 v128, s[100:101]
	s_mov_b32 m0, s43
	s_nop 0
	global_load_lds_dwordx4 v132, s[100:101]
	ds_read_b128 v[196:199], v150 offset:49152
	ds_read_b128 v[200:203], v150 offset:50176
	ds_read_b128 v[204:207], v150 offset:51200
	ds_read_b128 v[208:211], v150 offset:52224
	ds_read_b128 v[212:215], v150 offset:53248
	ds_read_b128 v[216:219], v150 offset:54272
	ds_read_b128 v[220:223], v150 offset:55296
	ds_read_b128 v[224:227], v150 offset:56320
	s_waitcnt vmcnt(8)
	s_waitcnt lgkmcnt(0)
	s_setprio 1
	s_barrier
	v_mfma_f32_16x16x32_bf16 v[60:63], v[144:147], v[196:199], v[60:63]
	v_mfma_f32_16x16x32_bf16 v[56:59], v[172:175], v[196:199], v[56:59]
	v_mfma_f32_16x16x32_bf16 v[44:47], v[144:147], v[204:207], v[44:47]
	v_mfma_f32_16x16x32_bf16 v[40:43], v[172:175], v[204:207], v[40:43]
	v_mfma_f32_16x16x32_bf16 v[28:31], v[144:147], v[212:215], v[28:31]
	v_mfma_f32_16x16x32_bf16 v[24:27], v[172:175], v[212:215], v[24:27]
	v_mfma_f32_16x16x32_bf16 v[12:15], v[144:147], v[220:223], v[12:15]
	v_mfma_f32_16x16x32_bf16 v[8:11], v[172:175], v[220:223], v[8:11]
	v_mfma_f32_16x16x32_bf16 v[60:63], v[168:171], v[200:203], v[60:63]
	v_mfma_f32_16x16x32_bf16 v[56:59], v[176:179], v[200:203], v[56:59]
	v_mfma_f32_16x16x32_bf16 v[44:47], v[168:171], v[208:211], v[44:47]
	v_mfma_f32_16x16x32_bf16 v[40:43], v[176:179], v[208:211], v[40:43]
	v_mfma_f32_16x16x32_bf16 v[28:31], v[168:171], v[216:219], v[28:31]
	v_mfma_f32_16x16x32_bf16 v[24:27], v[176:179], v[216:219], v[24:27]
	v_mfma_f32_16x16x32_bf16 v[12:15], v[168:171], v[224:227], v[12:15]
	v_mfma_f32_16x16x32_bf16 v[8:11], v[176:179], v[224:227], v[8:11]
	s_setprio 0
	s_setprio 1
	v_mfma_f32_16x16x32_bf16 v[52:55], v[180:183], v[196:199], v[52:55]
	v_mfma_f32_16x16x32_bf16 v[48:51], v[188:191], v[196:199], v[48:51]
	v_mfma_f32_16x16x32_bf16 v[36:39], v[180:183], v[204:207], v[36:39]
	v_mfma_f32_16x16x32_bf16 v[32:35], v[188:191], v[204:207], v[32:35]
	v_mfma_f32_16x16x32_bf16 v[20:23], v[180:183], v[212:215], v[20:23]
	v_mfma_f32_16x16x32_bf16 v[16:19], v[188:191], v[212:215], v[16:19]
	v_mfma_f32_16x16x32_bf16 v[4:7], v[180:183], v[220:223], v[4:7]
	v_mfma_f32_16x16x32_bf16 v[0:3], v[188:191], v[220:223], v[0:3]
	v_mfma_f32_16x16x32_bf16 v[52:55], v[184:187], v[200:203], v[52:55]
	v_mfma_f32_16x16x32_bf16 v[48:51], v[192:195], v[200:203], v[48:51]
	v_mfma_f32_16x16x32_bf16 v[36:39], v[184:187], v[208:211], v[36:39]
	v_mfma_f32_16x16x32_bf16 v[32:35], v[192:195], v[208:211], v[32:35]
	v_mfma_f32_16x16x32_bf16 v[20:23], v[184:187], v[216:219], v[20:23]
	v_mfma_f32_16x16x32_bf16 v[16:19], v[192:195], v[216:219], v[16:19]
	v_mfma_f32_16x16x32_bf16 v[4:7], v[184:187], v[224:227], v[4:7]
	v_mfma_f32_16x16x32_bf16 v[0:3], v[192:195], v[224:227], v[0:3]
	s_barrier
	s_setprio 0
	s_add_i32 s57, s57, 2
	s_add_u32 s55, s55, 0x100
	s_addc_u32 s56, s56, 0
	s_cmp_gt_u32 s57, 41
	s_mov_b64 s[4:5], s[22:23]
	s_cbranch_scc0 .LBB0_1733
	s_and_b64 vcc, exec, s[18:19]
	s_cbranch_vccz .LBB0_1736
	s_barrier

; #define PG8_STAGE(bufoff, gbase, voff) do { _Pragma("unroll") for (int _i = 0; _i < 2; ++_i) \
;         __builtin_amdgcn_global_load_lds((const unsigned*)((const char*)(gbase) + (voff)[_i]), (PG8_LAS unsigned*)(lds + (bufoff) + ldsw + _i * 8192), 16, 0, 0); } while (0)
; #define PG8_LDA(dst, b, h) do { _Pragma("unroll") for (int m = 0; m < 4; ++m) _Pragma("unroll") for (int k = 0; k < 2; ++k) dst[m][k] = *(const PG8_LAS bf16x8*)(lds + PG8_SA(b, h) + aoff + m * 2048 + k * 1024); } while (0)
; #define PG8_LDB(dst, b, h) do { _Pragma("unroll") for (int n = 0; n < 2; ++n) _Pragma("unroll") for (int k = 0; k < 2; ++k) dst[n][k] = *(const PG8_LAS bf16x8*)(lds + PG8_SB(b, h) + boff + n * 2048 + k * 1024); } while (0)
; #define PG8_MMA(ai, bj, At, Bt) do { __builtin_amdgcn_s_setprio(1); _Pragma("unroll") for (int m = 0; m < 4; ++m) _Pragma("unroll") for (int n = 0; n < 2; ++n) _Pragma("unroll") for (int k = 0; k < 2; ++k) \
;         acc[ai][bj][m][n] = __builtin_amdgcn_mfma_f32_16x16x32_bf16(Bt[n][k], At[m][k], acc[ai][bj][m][n], 0, 0, 0); __builtin_amdgcn_s_setprio(0); } while (0)
; #define PG8_WAIT_V(n) asm volatile("s_waitcnt vmcnt(" #n ")" ::: "memory")
; #define PG8_WAIT_L(n) asm volatile("s_waitcnt lgkmcnt(" #n ")" ::: "memory")
; #define PG8_BAR __builtin_amdgcn_s_barrier()
; template <class Epi, class Sched, bool ALIGN_EPI = false, bool SP2 = false>
; __device__ __forceinline__ void gemm_phase(PG8_LAS unsigned char* lds, const Gemm g, const Sched& S, const Epi& E, const int tid_arg) {
;     ...
;             const char* a1 = cA + (size_t)(t + 1) * kstep;
;             const char* a2 = last ? nA : cA + (size_t)(t + 2) * kstep; const char* b2 = last ? nB : cB + (size_t)(t + 2) * kstep;
;             const char* a3 = a2 + kstep; const char* b3 = b2 + kstep;
;             if (last && has_next) S.a_ready(nxt);
;             if constexpr (SP2) {
;             PG8_LDB(B0, 0, 0); PG8_LDB(B1, 0, 1); PG8_SCHED; PG8_LDA(At, 0, 0); PG8_STAGE(PG8_SA(1, 1), a1 + hstep, voffA);
;             PG8_WAIT_V(8); PG8_WAIT_L(0); PG8_BAR; PG8_MMA(0, 0, At, B0); PG8_MMA(0, 1, At, B1); PG8_BAR; PG8_SCHED;
;             PG8_LDA(At, 0, 1); PG8_STAGE(PG8_SB(0, 0), b2, voffB); PG8_STAGE(PG8_SB(0, 1), b2 + hstep, voffB); PG8_STAGE(PG8_SA(0, 0), a2, voffA);
;             PG8_WAIT_V(8); PG8_WAIT_L(0); PG8_BAR; PG8_MMA(1, 0, At, B0); PG8_MMA(1, 1, At, B1); PG8_BAR; PG8_SCHED;
.LBB0_1827:
	s_add_u32 s0, s44, 0xfffc0080
	s_addc_u32 s1, s45, -1
	s_cmp_eq_u32 s81, 12
	s_cselect_b32 s47, s39, s1
	s_cselect_b32 s46, s75, s0
	s_cselect_b32 s1, s37, s80
	s_cselect_b32 s0, s78, s79
	s_mov_b32 m0, s67
	s_nop 0
	global_load_lds_dwordx4 v138, s[44:45]
	s_mov_b32 m0, s68
	s_nop 0
	global_load_lds_dwordx4 v136, s[44:45]
	ds_read_b128 v[170:173], v151
	ds_read_b128 v[174:177], v153
	ds_read_b128 v[178:181], v155
	ds_read_b128 v[182:185], v156
	ds_read_b128 v[186:189], v157
	ds_read_b128 v[190:193], v158
	ds_read_b128 v[194:197], v159
	ds_read_b128 v[198:201], v160
	ds_read_b128 v[202:205], v149
	ds_read_b128 v[206:209], v149 offset:1024
	ds_read_b128 v[210:213], v149 offset:2048
	ds_read_b128 v[214:217], v149 offset:3072
	ds_read_b128 v[218:221], v149 offset:4096
	ds_read_b128 v[222:225], v149 offset:5120
	ds_read_b128 v[226:229], v149 offset:6144
	ds_read_b128 v[230:233], v149 offset:7168
	s_waitcnt vmcnt(8)
	s_waitcnt lgkmcnt(0)
	s_setprio 1
	s_barrier
	v_mfma_f32_16x16x32_bf16 v[124:127], v[170:173], v[202:205], v[124:127]
	v_mfma_f32_16x16x32_bf16 v[120:123], v[178:181], v[202:205], v[120:123]
	v_mfma_f32_16x16x32_bf16 v[108:111], v[170:173], v[210:213], v[108:111]
	v_mfma_f32_16x16x32_bf16 v[104:107], v[178:181], v[210:213], v[104:107]
	v_mfma_f32_16x16x32_bf16 v[92:95], v[170:173], v[218:221], v[92:95]
	v_mfma_f32_16x16x32_bf16 v[88:91], v[178:181], v[218:221], v[88:91]
	v_mfma_f32_16x16x32_bf16 v[76:79], v[170:173], v[226:229], v[76:79]
	v_mfma_f32_16x16x32_bf16 v[72:75], v[178:181], v[226:229], v[72:75]
	v_mfma_f32_16x16x32_bf16 v[124:127], v[174:177], v[206:209], v[124:127]
	v_mfma_f32_16x16x32_bf16 v[120:123], v[182:185], v[206:209], v[120:123]
	v_mfma_f32_16x16x32_bf16 v[108:111], v[174:177], v[214:217], v[108:111]
	v_mfma_f32_16x16x32_bf16 v[104:107], v[182:185], v[214:217], v[104:107]
	v_mfma_f32_16x16x32_bf16 v[92:95], v[174:177], v[222:225], v[92:95]
	v_mfma_f32_16x16x32_bf16 v[88:91], v[182:185], v[222:225], v[88:91]
	v_mfma_f32_16x16x32_bf16 v[76:79], v[174:177], v[230:233], v[76:79]
	v_mfma_f32_16x16x32_bf16 v[72:75], v[182:185], v[230:233], v[72:75]
	s_setprio 0
	s_setprio 1
	v_mfma_f32_16x16x32_bf16 v[116:119], v[186:189], v[202:205], v[116:119]
	v_mfma_f32_16x16x32_bf16 v[112:115], v[194:197], v[202:205], v[112:115]
	v_mfma_f32_16x16x32_bf16 v[100:103], v[186:189], v[210:213], v[100:103]
	v_mfma_f32_16x16x32_bf16 v[96:99], v[194:197], v[210:213], v[96:99]
	v_mfma_f32_16x16x32_bf16 v[84:87], v[186:189], v[218:221], v[84:87]
	v_mfma_f32_16x16x32_bf16 v[80:83], v[194:197], v[218:221], v[80:83]
	v_mfma_f32_16x16x32_bf16 v[68:71], v[186:189], v[226:229], v[68:71]
	v_mfma_f32_16x16x32_bf16 v[64:67], v[194:197], v[226:229], v[64:67]
	v_mfma_f32_16x16x32_bf16 v[116:119], v[190:193], v[206:209], v[116:119]
	v_mfma_f32_16x16x32_bf16 v[112:115], v[198:201], v[206:209], v[112:115]
	v_mfma_f32_16x16x32_bf16 v[100:103], v[190:193], v[214:217], v[100:103]
	v_mfma_f32_16x16x32_bf16 v[96:99], v[198:201], v[214:217], v[96:99]
	v_mfma_f32_16x16x32_bf16 v[84:87], v[190:193], v[222:225], v[84:87]
	v_mfma_f32_16x16x32_bf16 v[80:83], v[198:201], v[222:225], v[80:83]
	v_mfma_f32_16x16x32_bf16 v[68:71], v[190:193], v[230:233], v[68:71]
	v_mfma_f32_16x16x32_bf16 v[64:67], v[198:201], v[230:233], v[64:67]
	s_barrier
	s_setprio 0
	s_mov_b32 m0, s5
	s_add_u32 s98, s0, s16
	s_addc_u32 s99, s1, s17
	s_add_u32 s82, s0, 0x40000
	global_load_lds_dwordx4 v130, s[0:1]
	s_mov_b32 m0, s51
	s_addc_u32 s83, s1, 0
	global_load_lds_dwordx4 v134, s[0:1]
	s_mov_b32 m0, s52
	s_nop 0
	global_load_lds_dwordx4 v130, s[82:83]
	s_mov_b32 m0, s53
	s_nop 0
	global_load_lds_dwordx4 v134, s[82:83]
	s_add_u32 s100, s46, s16
	s_addc_u32 s101, s47, s17
	s_mov_b32 m0, s50
	s_nop 0
	global_load_lds_dwordx4 v128, s[46:47]
	s_mov_b32 m0, s54
	s_nop 0
	global_load_lds_dwordx4 v132, s[46:47]
	ds_read_b128 v[202:205], v149 offset:16384
	ds_read_b128 v[206:209], v149 offset:17408
	ds_read_b128 v[210:213], v149 offset:18432
	ds_read_b128 v[214:217], v149 offset:19456
	ds_read_b128 v[218:221], v149 offset:20480
	ds_read_b128 v[222:225], v149 offset:21504
	ds_read_b128 v[226:229], v149 offset:22528
	ds_read_b128 v[230:233], v149 offset:23552
	s_waitcnt vmcnt(8)
	s_waitcnt lgkmcnt(0)
	s_setprio 1
	s_barrier
	v_mfma_f32_16x16x32_bf16 v[60:63], v[170:173], v[202:205], v[60:63]
	v_mfma_f32_16x16x32_bf16 v[56:59], v[178:181], v[202:205], v[56:59]
	v_mfma_f32_16x16x32_bf16 v[44:47], v[170:173], v[210:213], v[44:47]
	v_mfma_f32_16x16x32_bf16 v[40:43], v[178:181], v[210:213], v[40:43]
	v_mfma_f32_16x16x32_bf16 v[28:31], v[170:173], v[218:221], v[28:31]
	v_mfma_f32_16x16x32_bf16 v[24:27], v[178:181], v[218:221], v[24:27]
	v_mfma_f32_16x16x32_bf16 v[12:15], v[170:173], v[226:229], v[12:15]
	v_mfma_f32_16x16x32_bf16 v[8:11], v[178:181], v[226:229], v[8:11]
	v_mfma_f32_16x16x32_bf16 v[60:63], v[174:177], v[206:209], v[60:63]
	v_mfma_f32_16x16x32_bf16 v[56:59], v[182:185], v[206:209], v[56:59]
	v_mfma_f32_16x16x32_bf16 v[44:47], v[174:177], v[214:217], v[44:47]
	v_mfma_f32_16x16x32_bf16 v[40:43], v[182:185], v[214:217], v[40:43]
	v_mfma_f32_16x16x32_bf16 v[28:31], v[174:177], v[222:225], v[28:31]
	v_mfma_f32_16x16x32_bf16 v[24:27], v[182:185], v[222:225], v[24:27]
	v_mfma_f32_16x16x32_bf16 v[12:15], v[174:177], v[230:233], v[12:15]
	v_mfma_f32_16x16x32_bf16 v[8:11], v[182:185], v[230:233], v[8:11]
	s_setprio 0
	s_setprio 1
	v_mfma_f32_16x16x32_bf16 v[52:55], v[186:189], v[202:205], v[52:55]
	v_mfma_f32_16x16x32_bf16 v[48:51], v[194:197], v[202:205], v[48:51]
	v_mfma_f32_16x16x32_bf16 v[36:39], v[186:189], v[210:213], v[36:39]
	v_mfma_f32_16x16x32_bf16 v[32:35], v[194:197], v[210:213], v[32:35]
	v_mfma_f32_16x16x32_bf16 v[20:23], v[186:189], v[218:221], v[20:23]
	v_mfma_f32_16x16x32_bf16 v[16:19], v[194:197], v[218:221], v[16:19]
	v_mfma_f32_16x16x32_bf16 v[4:7], v[186:189], v[226:229], v[4:7]
	v_mfma_f32_16x16x32_bf16 v[0:3], v[194:197], v[226:229], v[0:3]
	v_mfma_f32_16x16x32_bf16 v[52:55], v[190:193], v[206:209], v[52:55]
	v_mfma_f32_16x16x32_bf16 v[48:51], v[198:201], v[206:209], v[48:51]
	v_mfma_f32_16x16x32_bf16 v[36:39], v[190:193], v[214:217], v[36:39]
	v_mfma_f32_16x16x32_bf16 v[32:35], v[198:201], v[214:217], v[32:35]
	v_mfma_f32_16x16x32_bf16 v[20:23], v[190:193], v[222:225], v[20:23]
	v_mfma_f32_16x16x32_bf16 v[16:19], v[198:201], v[222:225], v[16:19]
	v_mfma_f32_16x16x32_bf16 v[4:7], v[190:193], v[230:233], v[4:7]
	v_mfma_f32_16x16x32_bf16 v[0:3], v[198:201], v[230:233], v[0:3]
	s_barrier
; #define PG8_STAGE(bufoff, gbase, voff) do { _Pragma("unroll") for (int _i = 0; _i < 2; ++_i) \
;         __builtin_amdgcn_global_load_lds((const unsigned*)((const char*)(gbase) + (voff)[_i]), (PG8_LAS unsigned*)(lds + (bufoff) + ldsw + _i * 8192), 16, 0, 0); } while (0)
; #define PG8_LDA(dst, b, h) do { _Pragma("unroll") for (int m = 0; m < 4; ++m) _Pragma("unroll") for (int k = 0; k < 2; ++k) dst[m][k] = *(const PG8_LAS bf16x8*)(lds + PG8_SA(b, h) + aoff + m * 2048 + k * 1024); } while (0)
; #define PG8_LDB(dst, b, h) do { _Pragma("unroll") for (int n = 0; n < 2; ++n) _Pragma("unroll") for (int k = 0; k < 2; ++k) dst[n][k] = *(const PG8_LAS bf16x8*)(lds + PG8_SB(b, h) + boff + n * 2048 + k * 1024); } while (0)
; #define PG8_MMA(ai, bj, At, Bt) do { __builtin_amdgcn_s_setprio(1); _Pragma("unroll") for (int m = 0; m < 4; ++m) _Pragma("unroll") for (int n = 0; n < 2; ++n) _Pragma("unroll") for (int k = 0; k < 2; ++k) \
;         acc[ai][bj][m][n] = __builtin_amdgcn_mfma_f32_16x16x32_bf16(Bt[n][k], At[m][k], acc[ai][bj][m][n], 0, 0, 0); __builtin_amdgcn_s_setprio(0); } while (0)
; #define PG8_WAIT_V(n) asm volatile("s_waitcnt vmcnt(" #n ")" ::: "memory")
; #define PG8_WAIT_L(n) asm volatile("s_waitcnt lgkmcnt(" #n ")" ::: "memory")
; #define PG8_BAR __builtin_amdgcn_s_barrier()
; #define PG8_SCHED __builtin_amdgcn_sched_barrier(0)
; template <class Epi, class Sched, bool ALIGN_EPI = false, bool SP2 = false>
; __device__ __forceinline__ void gemm_phase(PG8_LAS unsigned char* lds, const Gemm g, const Sched& S, const Epi& E, const int tid_arg) {
;     ...
;             PG8_LDB(B0, 1, 0); PG8_LDB(B1, 1, 1); PG8_SCHED; PG8_LDA(At, 1, 0); PG8_STAGE(PG8_SA(0, 1), a2 + hstep, voffA);
;             PG8_WAIT_V(8); PG8_WAIT_L(0); PG8_BAR; PG8_MMA(0, 0, At, B0); PG8_MMA(0, 1, At, B1); PG8_BAR; PG8_SCHED;
;             PG8_LDA(At, 1, 1); PG8_STAGE(PG8_SB(1, 0), b3, voffB); PG8_STAGE(PG8_SB(1, 1), b3 + hstep, voffB); PG8_STAGE(PG8_SA(1, 0), a3, voffA);
;             PG8_WAIT_V(8); PG8_WAIT_L(0); PG8_BAR; PG8_MMA(1, 0, At, B0); PG8_MMA(1, 1, At, B1); PG8_BAR; PG8_SCHED;
	s_setprio 0
	s_add_u32 s46, s46, 0x40000
	s_addc_u32 s47, s47, 0
	s_mov_b32 m0, s55
	s_nop 0
	global_load_lds_dwordx4 v128, s[46:47]
	s_mov_b32 m0, s56
	s_nop 0
	global_load_lds_dwordx4 v132, s[46:47]
	ds_read_b128 v[170:173], v161
	ds_read_b128 v[174:177], v162
	ds_read_b128 v[178:181], v163
	ds_read_b128 v[182:185], v164
	ds_read_b128 v[186:189], v165
	ds_read_b128 v[190:193], v166
	ds_read_b128 v[194:197], v167
	ds_read_b128 v[198:201], v168
	ds_read_b128 v[202:205], v149 offset:32768
	ds_read_b128 v[206:209], v149 offset:33792
	ds_read_b128 v[210:213], v149 offset:34816
	ds_read_b128 v[214:217], v149 offset:35840
	ds_read_b128 v[218:221], v149 offset:36864
	ds_read_b128 v[222:225], v149 offset:37888
	ds_read_b128 v[226:229], v149 offset:38912
	ds_read_b128 v[230:233], v149 offset:39936
	s_waitcnt vmcnt(8)
	s_waitcnt lgkmcnt(0)
	s_setprio 1
	s_barrier
	v_mfma_f32_16x16x32_bf16 v[124:127], v[170:173], v[202:205], v[124:127]
	v_mfma_f32_16x16x32_bf16 v[120:123], v[178:181], v[202:205], v[120:123]
	v_mfma_f32_16x16x32_bf16 v[108:111], v[170:173], v[210:213], v[108:111]
	v_mfma_f32_16x16x32_bf16 v[104:107], v[178:181], v[210:213], v[104:107]
	v_mfma_f32_16x16x32_bf16 v[92:95], v[170:173], v[218:221], v[92:95]
	v_mfma_f32_16x16x32_bf16 v[88:91], v[178:181], v[218:221], v[88:91]
	v_mfma_f32_16x16x32_bf16 v[76:79], v[170:173], v[226:229], v[76:79]
	v_mfma_f32_16x16x32_bf16 v[72:75], v[178:181], v[226:229], v[72:75]
	v_mfma_f32_16x16x32_bf16 v[124:127], v[174:177], v[206:209], v[124:127]
	v_mfma_f32_16x16x32_bf16 v[120:123], v[182:185], v[206:209], v[120:123]
	v_mfma_f32_16x16x32_bf16 v[108:111], v[174:177], v[214:217], v[108:111]
	v_mfma_f32_16x16x32_bf16 v[104:107], v[182:185], v[214:217], v[104:107]
	v_mfma_f32_16x16x32_bf16 v[92:95], v[174:177], v[222:225], v[92:95]
	v_mfma_f32_16x16x32_bf16 v[88:91], v[182:185], v[222:225], v[88:91]
	v_mfma_f32_16x16x32_bf16 v[76:79], v[174:177], v[230:233], v[76:79]
	v_mfma_f32_16x16x32_bf16 v[72:75], v[182:185], v[230:233], v[72:75]
	s_setprio 0
	s_setprio 1
	v_mfma_f32_16x16x32_bf16 v[116:119], v[186:189], v[202:205], v[116:119]
	v_mfma_f32_16x16x32_bf16 v[112:115], v[194:197], v[202:205], v[112:115]
	v_mfma_f32_16x16x32_bf16 v[100:103], v[186:189], v[210:213], v[100:103]
	v_mfma_f32_16x16x32_bf16 v[96:99], v[194:197], v[210:213], v[96:99]
	v_mfma_f32_16x16x32_bf16 v[84:87], v[186:189], v[218:221], v[84:87]
	v_mfma_f32_16x16x32_bf16 v[80:83], v[194:197], v[218:221], v[80:83]
	v_mfma_f32_16x16x32_bf16 v[68:71], v[186:189], v[226:229], v[68:71]
	v_mfma_f32_16x16x32_bf16 v[64:67], v[194:197], v[226:229], v[64:67]
	v_mfma_f32_16x16x32_bf16 v[116:119], v[190:193], v[206:209], v[116:119]
	v_mfma_f32_16x16x32_bf16 v[112:115], v[198:201], v[206:209], v[112:115]
	v_mfma_f32_16x16x32_bf16 v[100:103], v[190:193], v[214:217], v[100:103]
	v_mfma_f32_16x16x32_bf16 v[96:99], v[198:201], v[214:217], v[96:99]
	v_mfma_f32_16x16x32_bf16 v[84:87], v[190:193], v[222:225], v[84:87]
	v_mfma_f32_16x16x32_bf16 v[80:83], v[198:201], v[222:225], v[80:83]
	v_mfma_f32_16x16x32_bf16 v[68:71], v[190:193], v[230:233], v[68:71]
	v_mfma_f32_16x16x32_bf16 v[64:67], v[198:201], v[230:233], v[64:67]
	s_barrier
	s_setprio 0
	s_mov_b32 m0, s59
	s_add_u32 s0, s0, 0x40080
	global_load_lds_dwordx4 v130, s[98:99]
	s_mov_b32 m0, s60
	s_addc_u32 s1, s1, 0
	global_load_lds_dwordx4 v134, s[98:99]
	s_mov_b32 m0, s63
	s_nop 0
	global_load_lds_dwordx4 v130, s[0:1]
	s_mov_b32 m0, s64
	s_nop 0
	global_load_lds_dwordx4 v134, s[0:1]
	s_mov_b32 m0, s61
	s_nop 0
	global_load_lds_dwordx4 v128, s[100:101]
	s_mov_b32 m0, s62
	s_nop 0
	global_load_lds_dwordx4 v132, s[100:101]
	ds_read_b128 v[202:205], v149 offset:49152
	ds_read_b128 v[206:209], v149 offset:50176
	ds_read_b128 v[210:213], v149 offset:51200
	ds_read_b128 v[214:217], v149 offset:52224
	ds_read_b128 v[218:221], v149 offset:53248
	ds_read_b128 v[222:225], v149 offset:54272
	ds_read_b128 v[226:229], v149 offset:55296
	ds_read_b128 v[230:233], v149 offset:56320
	s_waitcnt vmcnt(8)
	s_waitcnt lgkmcnt(0)
	s_setprio 1
	s_barrier
	v_mfma_f32_16x16x32_bf16 v[60:63], v[170:173], v[202:205], v[60:63]
	v_mfma_f32_16x16x32_bf16 v[56:59], v[178:181], v[202:205], v[56:59]
	v_mfma_f32_16x16x32_bf16 v[44:47], v[170:173], v[210:213], v[44:47]
	v_mfma_f32_16x16x32_bf16 v[40:43], v[178:181], v[210:213], v[40:43]
	v_mfma_f32_16x16x32_bf16 v[28:31], v[170:173], v[218:221], v[28:31]
	v_mfma_f32_16x16x32_bf16 v[24:27], v[178:181], v[218:221], v[24:27]
	v_mfma_f32_16x16x32_bf16 v[12:15], v[170:173], v[226:229], v[12:15]
	v_mfma_f32_16x16x32_bf16 v[8:11], v[178:181], v[226:229], v[8:11]
	v_mfma_f32_16x16x32_bf16 v[60:63], v[174:177], v[206:209], v[60:63]
	v_mfma_f32_16x16x32_bf16 v[56:59], v[182:185], v[206:209], v[56:59]
	v_mfma_f32_16x16x32_bf16 v[44:47], v[174:177], v[214:217], v[44:47]
	v_mfma_f32_16x16x32_bf16 v[40:43], v[182:185], v[214:217], v[40:43]
	v_mfma_f32_16x16x32_bf16 v[28:31], v[174:177], v[222:225], v[28:31]
	v_mfma_f32_16x16x32_bf16 v[24:27], v[182:185], v[222:225], v[24:27]
	v_mfma_f32_16x16x32_bf16 v[12:15], v[174:177], v[230:233], v[12:15]
	v_mfma_f32_16x16x32_bf16 v[8:11], v[182:185], v[230:233], v[8:11]
	s_setprio 0
	s_setprio 1
	v_mfma_f32_16x16x32_bf16 v[52:55], v[186:189], v[202:205], v[52:55]
	v_mfma_f32_16x16x32_bf16 v[48:51], v[194:197], v[202:205], v[48:51]
	v_mfma_f32_16x16x32_bf16 v[36:39], v[186:189], v[210:213], v[36:39]
	v_mfma_f32_16x16x32_bf16 v[32:35], v[194:197], v[210:213], v[32:35]
	v_mfma_f32_16x16x32_bf16 v[20:23], v[186:189], v[218:221], v[20:23]
	v_mfma_f32_16x16x32_bf16 v[16:19], v[194:197], v[218:221], v[16:19]
	v_mfma_f32_16x16x32_bf16 v[4:7], v[186:189], v[226:229], v[4:7]
	v_mfma_f32_16x16x32_bf16 v[0:3], v[194:197], v[226:229], v[0:3]
	v_mfma_f32_16x16x32_bf16 v[52:55], v[190:193], v[206:209], v[52:55]
	v_mfma_f32_16x16x32_bf16 v[48:51], v[198:201], v[206:209], v[48:51]
	v_mfma_f32_16x16x32_bf16 v[36:39], v[190:193], v[214:217], v[36:39]
	v_mfma_f32_16x16x32_bf16 v[32:35], v[198:201], v[214:217], v[32:35]
	v_mfma_f32_16x16x32_bf16 v[20:23], v[190:193], v[222:225], v[20:23]
	v_mfma_f32_16x16x32_bf16 v[16:19], v[198:201], v[222:225], v[16:19]
	v_mfma_f32_16x16x32_bf16 v[4:7], v[190:193], v[230:233], v[4:7]
	v_mfma_f32_16x16x32_bf16 v[0:3], v[198:201], v[230:233], v[0:3]
	s_barrier
	s_setprio 0
	s_add_i32 s81, s81, 2
	s_add_u32 s79, s79, 0x100
	s_addc_u32 s80, s80, 0
	s_add_u32 s44, s44, 0x100
	s_addc_u32 s45, s45, 0
	s_cmp_gt_u32 s81, 13
	s_cbranch_scc0 .LBB0_1827
	s_and_b64 vcc, exec, s[18:19]
	s_cbranch_vccz .LBB0_1830
	s_barrier

; #define PG8_STAGE(bufoff, gbase, voff) do { _Pragma("unroll") for (int _i = 0; _i < 2; ++_i) \
;         __builtin_amdgcn_global_load_lds((const unsigned*)((const char*)(gbase) + (voff)[_i]), (PG8_LAS unsigned*)(lds + (bufoff) + ldsw + _i * 8192), 16, 0, 0); } while (0)
; #define PG8_LDA(dst, b, h) do { _Pragma("unroll") for (int m = 0; m < 4; ++m) _Pragma("unroll") for (int k = 0; k < 2; ++k) dst[m][k] = *(const PG8_LAS bf16x8*)(lds + PG8_SA(b, h) + aoff + m * 2048 + k * 1024); } while (0)
; #define PG8_LDB(dst, b, h) do { _Pragma("unroll") for (int n = 0; n < 2; ++n) _Pragma("unroll") for (int k = 0; k < 2; ++k) dst[n][k] = *(const PG8_LAS bf16x8*)(lds + PG8_SB(b, h) + boff + n * 2048 + k * 1024); } while (0)
; #define PG8_MMA(ai, bj, At, Bt) do { __builtin_amdgcn_s_setprio(1); _Pragma("unroll") for (int m = 0; m < 4; ++m) _Pragma("unroll") for (int n = 0; n < 2; ++n) _Pragma("unroll") for (int k = 0; k < 2; ++k) \
;         acc[ai][bj][m][n] = __builtin_amdgcn_mfma_f32_16x16x32_bf16(Bt[n][k], At[m][k], acc[ai][bj][m][n], 0, 0, 0); __builtin_amdgcn_s_setprio(0); } while (0)
; #define PG8_WAIT_V(n) asm volatile("s_waitcnt vmcnt(" #n ")" ::: "memory")
; #define PG8_WAIT_L(n) asm volatile("s_waitcnt lgkmcnt(" #n ")" ::: "memory")
; #define PG8_BAR __builtin_amdgcn_s_barrier()
; template <class Epi, class Sched, bool ALIGN_EPI = false, bool SP2 = false>
; __device__ __forceinline__ void gemm_phase(PG8_LAS unsigned char* lds, const Gemm g, const Sched& S, const Epi& E, const int tid_arg) {
;     ...
;             const char* a1 = cA + (size_t)(t + 1) * kstep;
;             const char* a2 = last ? nA : cA + (size_t)(t + 2) * kstep; const char* b2 = last ? nB : cB + (size_t)(t + 2) * kstep;
;             const char* a3 = a2 + kstep; const char* b3 = b2 + kstep;
;             if (last && has_next) S.a_ready(nxt);
;             if constexpr (SP2) {
;             PG8_LDB(B0, 0, 0); PG8_LDB(B1, 0, 1); PG8_SCHED; PG8_LDA(At, 0, 0); PG8_STAGE(PG8_SA(1, 1), a1 + hstep, voffA);
;             PG8_WAIT_V(8); PG8_WAIT_L(0); PG8_BAR; PG8_MMA(0, 0, At, B0); PG8_MMA(0, 1, At, B1); PG8_BAR; PG8_SCHED;
;             PG8_LDA(At, 0, 1); PG8_STAGE(PG8_SB(0, 0), b2, voffB); PG8_STAGE(PG8_SB(0, 1), b2 + hstep, voffB); PG8_STAGE(PG8_SA(0, 0), a2, voffA);
;             PG8_WAIT_V(8); PG8_WAIT_L(0); PG8_BAR; PG8_MMA(1, 0, At, B0); PG8_MMA(1, 1, At, B1); PG8_BAR; PG8_SCHED;
.LBB0_1911:
	s_add_i32 s36, s34, 2
	s_add_u32 s37, s6, 0x80
	s_addc_u32 s35, s7, 0
	s_cmp_eq_u32 s57, s34
	s_cselect_b32 s34, s28, s37
	s_cselect_b32 s35, s29, s35
	s_cselect_b32 s67, s31, s64
	s_cselect_b32 s66, s30, s63
	s_mov_b32 m0, s58
	s_nop 0
	global_load_lds_dwordx4 v138, s[6:7]
	s_mov_b32 m0, s59
	s_nop 0
	global_load_lds_dwordx4 v136, s[6:7]
	ds_read_b128 v[144:147], v157
	ds_read_b128 v[148:151], v158
	ds_read_b128 v[174:177], v159
	ds_read_b128 v[178:181], v160
	ds_read_b128 v[182:185], v161
	ds_read_b128 v[186:189], v162
	ds_read_b128 v[190:193], v163
	ds_read_b128 v[194:197], v164
	ds_read_b128 v[198:201], v156
	ds_read_b128 v[202:205], v156 offset:1024
	ds_read_b128 v[206:209], v156 offset:2048
	ds_read_b128 v[210:213], v156 offset:3072
	ds_read_b128 v[214:217], v156 offset:4096
	ds_read_b128 v[218:221], v156 offset:5120
	ds_read_b128 v[222:225], v156 offset:6144
	ds_read_b128 v[226:229], v156 offset:7168
	s_waitcnt vmcnt(8)
	s_waitcnt lgkmcnt(0)
	s_setprio 1
	s_barrier
	v_mfma_f32_16x16x32_bf16 v[124:127], v[144:147], v[198:201], v[124:127]
	v_mfma_f32_16x16x32_bf16 v[120:123], v[174:177], v[198:201], v[120:123]
	v_mfma_f32_16x16x32_bf16 v[108:111], v[144:147], v[206:209], v[108:111]
	v_mfma_f32_16x16x32_bf16 v[104:107], v[174:177], v[206:209], v[104:107]
	v_mfma_f32_16x16x32_bf16 v[92:95], v[144:147], v[214:217], v[92:95]
	v_mfma_f32_16x16x32_bf16 v[88:91], v[174:177], v[214:217], v[88:91]
	v_mfma_f32_16x16x32_bf16 v[76:79], v[144:147], v[222:225], v[76:79]
	v_mfma_f32_16x16x32_bf16 v[72:75], v[174:177], v[222:225], v[72:75]
	v_mfma_f32_16x16x32_bf16 v[124:127], v[148:151], v[202:205], v[124:127]
	v_mfma_f32_16x16x32_bf16 v[120:123], v[178:181], v[202:205], v[120:123]
	v_mfma_f32_16x16x32_bf16 v[108:111], v[148:151], v[210:213], v[108:111]
	v_mfma_f32_16x16x32_bf16 v[104:107], v[178:181], v[210:213], v[104:107]
	v_mfma_f32_16x16x32_bf16 v[92:95], v[148:151], v[218:221], v[92:95]
	v_mfma_f32_16x16x32_bf16 v[88:91], v[178:181], v[218:221], v[88:91]
	v_mfma_f32_16x16x32_bf16 v[76:79], v[148:151], v[226:229], v[76:79]
	v_mfma_f32_16x16x32_bf16 v[72:75], v[178:181], v[226:229], v[72:75]
	s_setprio 0
	s_setprio 1
	v_mfma_f32_16x16x32_bf16 v[116:119], v[182:185], v[198:201], v[116:119]
	v_mfma_f32_16x16x32_bf16 v[112:115], v[190:193], v[198:201], v[112:115]
	v_mfma_f32_16x16x32_bf16 v[100:103], v[182:185], v[206:209], v[100:103]
	v_mfma_f32_16x16x32_bf16 v[96:99], v[190:193], v[206:209], v[96:99]
	v_mfma_f32_16x16x32_bf16 v[84:87], v[182:185], v[214:217], v[84:87]
	v_mfma_f32_16x16x32_bf16 v[80:83], v[190:193], v[214:217], v[80:83]
	v_mfma_f32_16x16x32_bf16 v[68:71], v[182:185], v[222:225], v[68:71]
	v_mfma_f32_16x16x32_bf16 v[64:67], v[190:193], v[222:225], v[64:67]
	v_mfma_f32_16x16x32_bf16 v[116:119], v[186:189], v[202:205], v[116:119]
	v_mfma_f32_16x16x32_bf16 v[112:115], v[194:197], v[202:205], v[112:115]
	v_mfma_f32_16x16x32_bf16 v[100:103], v[186:189], v[210:213], v[100:103]
	v_mfma_f32_16x16x32_bf16 v[96:99], v[194:197], v[210:213], v[96:99]
	v_mfma_f32_16x16x32_bf16 v[84:87], v[186:189], v[218:221], v[84:87]
	v_mfma_f32_16x16x32_bf16 v[80:83], v[194:197], v[218:221], v[80:83]
	v_mfma_f32_16x16x32_bf16 v[68:71], v[186:189], v[226:229], v[68:71]
	v_mfma_f32_16x16x32_bf16 v[64:67], v[194:197], v[226:229], v[64:67]
	s_barrier
	s_setprio 0
	s_mov_b32 m0, s42
	s_add_u32 s98, s66, s20
	s_addc_u32 s99, s67, s21
	v_lshl_add_u64 v[152:153], s[66:67], 0, v[130:131]
	v_lshl_add_u64 v[230:231], s[66:67], 0, v[134:135]
	s_add_u32 s66, s66, s12
	global_load_lds_dwordx4 v[152:153], off
	s_mov_b32 m0, s43
	s_addc_u32 s67, s67, s13
	global_load_lds_dwordx4 v[230:231], off
	s_add_u32 s100, s66, s20
	s_addc_u32 s101, s67, s21
	s_mov_b32 m0, s44
	s_nop 0
	global_load_lds_dwordx4 v130, s[66:67]
	s_mov_b32 m0, s45
	v_lshl_add_u64 v[236:237], s[34:35], 0, v[128:129]
	global_load_lds_dwordx4 v134, s[66:67]
	s_mov_b32 m0, s41
	v_lshl_add_u64 v[238:239], s[34:35], 0, v[132:133]
	global_load_lds_dwordx4 v128, s[34:35]
	s_mov_b32 m0, s46
	s_nop 0
	global_load_lds_dwordx4 v132, s[34:35]
	ds_read_b128 v[198:201], v156 offset:16384
	ds_read_b128 v[202:205], v156 offset:17408
	ds_read_b128 v[206:209], v156 offset:18432
	ds_read_b128 v[210:213], v156 offset:19456
	ds_read_b128 v[214:217], v156 offset:20480
	ds_read_b128 v[218:221], v156 offset:21504
	ds_read_b128 v[222:225], v156 offset:22528
	ds_read_b128 v[226:229], v156 offset:23552
	s_waitcnt vmcnt(8)
	s_waitcnt lgkmcnt(0)
	s_setprio 1
	s_barrier
	v_mfma_f32_16x16x32_bf16 v[60:63], v[144:147], v[198:201], v[60:63]
	v_mfma_f32_16x16x32_bf16 v[56:59], v[174:177], v[198:201], v[56:59]
	v_mfma_f32_16x16x32_bf16 v[44:47], v[144:147], v[206:209], v[44:47]
	v_mfma_f32_16x16x32_bf16 v[40:43], v[174:177], v[206:209], v[40:43]
	v_mfma_f32_16x16x32_bf16 v[28:31], v[144:147], v[214:217], v[28:31]
	v_mfma_f32_16x16x32_bf16 v[24:27], v[174:177], v[214:217], v[24:27]
	v_mfma_f32_16x16x32_bf16 v[12:15], v[144:147], v[222:225], v[12:15]
	v_mfma_f32_16x16x32_bf16 v[8:11], v[174:177], v[222:225], v[8:11]
	v_mfma_f32_16x16x32_bf16 v[60:63], v[148:151], v[202:205], v[60:63]
	v_mfma_f32_16x16x32_bf16 v[56:59], v[178:181], v[202:205], v[56:59]
	v_mfma_f32_16x16x32_bf16 v[44:47], v[148:151], v[210:213], v[44:47]
	v_mfma_f32_16x16x32_bf16 v[40:43], v[178:181], v[210:213], v[40:43]
	v_mfma_f32_16x16x32_bf16 v[28:31], v[148:151], v[218:221], v[28:31]
	v_mfma_f32_16x16x32_bf16 v[24:27], v[178:181], v[218:221], v[24:27]
	v_mfma_f32_16x16x32_bf16 v[12:15], v[148:151], v[226:229], v[12:15]
	v_mfma_f32_16x16x32_bf16 v[8:11], v[178:181], v[226:229], v[8:11]
	s_setprio 0
	s_setprio 1
	v_mfma_f32_16x16x32_bf16 v[52:55], v[182:185], v[198:201], v[52:55]
	v_mfma_f32_16x16x32_bf16 v[48:51], v[190:193], v[198:201], v[48:51]
	v_mfma_f32_16x16x32_bf16 v[36:39], v[182:185], v[206:209], v[36:39]
	v_mfma_f32_16x16x32_bf16 v[32:35], v[190:193], v[206:209], v[32:35]
	v_mfma_f32_16x16x32_bf16 v[20:23], v[182:185], v[214:217], v[20:23]
	v_mfma_f32_16x16x32_bf16 v[16:19], v[190:193], v[214:217], v[16:19]
	v_mfma_f32_16x16x32_bf16 v[4:7], v[182:185], v[222:225], v[4:7]
	v_mfma_f32_16x16x32_bf16 v[0:3], v[190:193], v[222:225], v[0:3]
	v_mfma_f32_16x16x32_bf16 v[52:55], v[186:189], v[202:205], v[52:55]
	v_mfma_f32_16x16x32_bf16 v[48:51], v[194:197], v[202:205], v[48:51]
	v_mfma_f32_16x16x32_bf16 v[36:39], v[186:189], v[210:213], v[36:39]
	v_mfma_f32_16x16x32_bf16 v[32:35], v[194:197], v[210:213], v[32:35]
	v_mfma_f32_16x16x32_bf16 v[20:23], v[186:189], v[218:221], v[20:23]
	v_mfma_f32_16x16x32_bf16 v[16:19], v[194:197], v[218:221], v[16:19]
	v_mfma_f32_16x16x32_bf16 v[4:7], v[186:189], v[226:229], v[4:7]
	v_mfma_f32_16x16x32_bf16 v[0:3], v[194:197], v[226:229], v[0:3]
	s_barrier
; #define PG8_STAGE(bufoff, gbase, voff) do { _Pragma("unroll") for (int _i = 0; _i < 2; ++_i) \
;         __builtin_amdgcn_global_load_lds((const unsigned*)((const char*)(gbase) + (voff)[_i]), (PG8_LAS unsigned*)(lds + (bufoff) + ldsw + _i * 8192), 16, 0, 0); } while (0)
; #define PG8_LDA(dst, b, h) do { _Pragma("unroll") for (int m = 0; m < 4; ++m) _Pragma("unroll") for (int k = 0; k < 2; ++k) dst[m][k] = *(const PG8_LAS bf16x8*)(lds + PG8_SA(b, h) + aoff + m * 2048 + k * 1024); } while (0)
; #define PG8_LDB(dst, b, h) do { _Pragma("unroll") for (int n = 0; n < 2; ++n) _Pragma("unroll") for (int k = 0; k < 2; ++k) dst[n][k] = *(const PG8_LAS bf16x8*)(lds + PG8_SB(b, h) + boff + n * 2048 + k * 1024); } while (0)
; #define PG8_MMA(ai, bj, At, Bt) do { __builtin_amdgcn_s_setprio(1); _Pragma("unroll") for (int m = 0; m < 4; ++m) _Pragma("unroll") for (int n = 0; n < 2; ++n) _Pragma("unroll") for (int k = 0; k < 2; ++k) \
;         acc[ai][bj][m][n] = __builtin_amdgcn_mfma_f32_16x16x32_bf16(Bt[n][k], At[m][k], acc[ai][bj][m][n], 0, 0, 0); __builtin_amdgcn_s_setprio(0); } while (0)
; #define PG8_WAIT_V(n) asm volatile("s_waitcnt vmcnt(" #n ")" ::: "memory")
; #define PG8_WAIT_L(n) asm volatile("s_waitcnt lgkmcnt(" #n ")" ::: "memory")
; #define PG8_BAR __builtin_amdgcn_s_barrier()
; #define PG8_SCHED __builtin_amdgcn_sched_barrier(0)
; template <class Epi, class Sched, bool ALIGN_EPI = false, bool SP2 = false>
; __device__ __forceinline__ void gemm_phase(PG8_LAS unsigned char* lds, const Gemm g, const Sched& S, const Epi& E, const int tid_arg) {
;     ...
;             PG8_LDB(B0, 1, 0); PG8_LDB(B1, 1, 1); PG8_SCHED; PG8_LDA(At, 1, 0); PG8_STAGE(PG8_SA(0, 1), a2 + hstep, voffA);
;             PG8_WAIT_V(8); PG8_WAIT_L(0); PG8_BAR; PG8_MMA(0, 0, At, B0); PG8_MMA(0, 1, At, B1); PG8_BAR; PG8_SCHED;
;             PG8_LDA(At, 1, 1); PG8_STAGE(PG8_SB(1, 0), b3, voffB); PG8_STAGE(PG8_SB(1, 1), b3 + hstep, voffB); PG8_STAGE(PG8_SA(1, 0), a3, voffA);
;             PG8_WAIT_V(8); PG8_WAIT_L(0); PG8_BAR; PG8_MMA(1, 0, At, B0); PG8_MMA(1, 1, At, B1); PG8_BAR; PG8_SCHED;
	s_setprio 0
	s_add_u32 s34, s34, s12
	s_addc_u32 s35, s35, s13
	s_mov_b32 m0, s47
	s_nop 0
	global_load_lds_dwordx4 v128, s[34:35]
	s_mov_b32 m0, s48
	s_nop 0
	global_load_lds_dwordx4 v132, s[34:35]
	ds_read_b128 v[144:147], v165
	ds_read_b128 v[148:151], v166
	ds_read_b128 v[174:177], v167
	ds_read_b128 v[178:181], v168
	ds_read_b128 v[182:185], v169
	ds_read_b128 v[186:189], v170
	ds_read_b128 v[190:193], v171
	ds_read_b128 v[194:197], v172
	ds_read_b128 v[198:201], v156 offset:32768
	ds_read_b128 v[202:205], v156 offset:33792
	ds_read_b128 v[206:209], v156 offset:34816
	ds_read_b128 v[210:213], v156 offset:35840
	ds_read_b128 v[214:217], v156 offset:36864
	ds_read_b128 v[218:221], v156 offset:37888
	ds_read_b128 v[222:225], v156 offset:38912
	ds_read_b128 v[226:229], v156 offset:39936
	s_waitcnt vmcnt(8)
	s_waitcnt lgkmcnt(0)
	s_setprio 1
	s_barrier
	v_mfma_f32_16x16x32_bf16 v[124:127], v[144:147], v[198:201], v[124:127]
	v_mfma_f32_16x16x32_bf16 v[120:123], v[174:177], v[198:201], v[120:123]
	v_mfma_f32_16x16x32_bf16 v[108:111], v[144:147], v[206:209], v[108:111]
	v_mfma_f32_16x16x32_bf16 v[104:107], v[174:177], v[206:209], v[104:107]
	v_mfma_f32_16x16x32_bf16 v[92:95], v[144:147], v[214:217], v[92:95]
	v_mfma_f32_16x16x32_bf16 v[88:91], v[174:177], v[214:217], v[88:91]
	v_mfma_f32_16x16x32_bf16 v[76:79], v[144:147], v[222:225], v[76:79]
	v_mfma_f32_16x16x32_bf16 v[72:75], v[174:177], v[222:225], v[72:75]
	v_mfma_f32_16x16x32_bf16 v[124:127], v[148:151], v[202:205], v[124:127]
	v_mfma_f32_16x16x32_bf16 v[120:123], v[178:181], v[202:205], v[120:123]
	v_mfma_f32_16x16x32_bf16 v[108:111], v[148:151], v[210:213], v[108:111]
	v_mfma_f32_16x16x32_bf16 v[104:107], v[178:181], v[210:213], v[104:107]
	v_mfma_f32_16x16x32_bf16 v[92:95], v[148:151], v[218:221], v[92:95]
	v_mfma_f32_16x16x32_bf16 v[88:91], v[178:181], v[218:221], v[88:91]
	v_mfma_f32_16x16x32_bf16 v[76:79], v[148:151], v[226:229], v[76:79]
	v_mfma_f32_16x16x32_bf16 v[72:75], v[178:181], v[226:229], v[72:75]
	s_setprio 0
	s_setprio 1
	v_mfma_f32_16x16x32_bf16 v[116:119], v[182:185], v[198:201], v[116:119]
	v_mfma_f32_16x16x32_bf16 v[112:115], v[190:193], v[198:201], v[112:115]
	v_mfma_f32_16x16x32_bf16 v[100:103], v[182:185], v[206:209], v[100:103]
	v_mfma_f32_16x16x32_bf16 v[96:99], v[190:193], v[206:209], v[96:99]
	v_mfma_f32_16x16x32_bf16 v[84:87], v[182:185], v[214:217], v[84:87]
	v_mfma_f32_16x16x32_bf16 v[80:83], v[190:193], v[214:217], v[80:83]
	v_mfma_f32_16x16x32_bf16 v[68:71], v[182:185], v[222:225], v[68:71]
	v_mfma_f32_16x16x32_bf16 v[64:67], v[190:193], v[222:225], v[64:67]
	v_mfma_f32_16x16x32_bf16 v[116:119], v[186:189], v[202:205], v[116:119]
	v_mfma_f32_16x16x32_bf16 v[112:115], v[194:197], v[202:205], v[112:115]
	v_mfma_f32_16x16x32_bf16 v[100:103], v[186:189], v[210:213], v[100:103]
	v_mfma_f32_16x16x32_bf16 v[96:99], v[194:197], v[210:213], v[96:99]
	v_mfma_f32_16x16x32_bf16 v[84:87], v[186:189], v[218:221], v[84:87]
	v_mfma_f32_16x16x32_bf16 v[80:83], v[194:197], v[218:221], v[80:83]
	v_mfma_f32_16x16x32_bf16 v[68:71], v[186:189], v[226:229], v[68:71]
	v_mfma_f32_16x16x32_bf16 v[64:67], v[194:197], v[226:229], v[64:67]
	s_barrier
	s_setprio 0
	s_mov_b32 m0, s49
	s_nop 0
	global_load_lds_dwordx4 v130, s[98:99]
	s_mov_b32 m0, s50
	s_nop 0
	global_load_lds_dwordx4 v134, s[98:99]
	s_mov_b32 m0, s53
	s_nop 0
	global_load_lds_dwordx4 v130, s[100:101]
	s_mov_b32 m0, s54
	s_nop 0
	global_load_lds_dwordx4 v134, s[100:101]
	v_lshl_add_u64 v[152:153], v[236:237], 0, s[20:21]
	s_mov_b32 m0, s51
	s_nop 0
	global_load_lds_dwordx4 v[152:153], off
	v_lshl_add_u64 v[152:153], v[238:239], 0, s[20:21]
	s_mov_b32 m0, s52
	s_nop 0
	global_load_lds_dwordx4 v[152:153], off
	ds_read_b128 v[198:201], v156 offset:49152
	ds_read_b128 v[202:205], v156 offset:50176
	ds_read_b128 v[206:209], v156 offset:51200
	ds_read_b128 v[210:213], v156 offset:52224
	ds_read_b128 v[214:217], v156 offset:53248
	ds_read_b128 v[218:221], v156 offset:54272
	ds_read_b128 v[222:225], v156 offset:55296
	ds_read_b128 v[226:229], v156 offset:56320
	s_waitcnt vmcnt(8)
	s_waitcnt lgkmcnt(0)
	s_setprio 1
	s_barrier
	v_mfma_f32_16x16x32_bf16 v[60:63], v[144:147], v[198:201], v[60:63]
	v_mfma_f32_16x16x32_bf16 v[56:59], v[174:177], v[198:201], v[56:59]
	v_mfma_f32_16x16x32_bf16 v[44:47], v[144:147], v[206:209], v[44:47]
	v_mfma_f32_16x16x32_bf16 v[40:43], v[174:177], v[206:209], v[40:43]
	v_mfma_f32_16x16x32_bf16 v[28:31], v[144:147], v[214:217], v[28:31]
	v_mfma_f32_16x16x32_bf16 v[24:27], v[174:177], v[214:217], v[24:27]
	v_mfma_f32_16x16x32_bf16 v[12:15], v[144:147], v[222:225], v[12:15]
	v_mfma_f32_16x16x32_bf16 v[8:11], v[174:177], v[222:225], v[8:11]
	v_mfma_f32_16x16x32_bf16 v[60:63], v[148:151], v[202:205], v[60:63]
	v_mfma_f32_16x16x32_bf16 v[56:59], v[178:181], v[202:205], v[56:59]
	v_mfma_f32_16x16x32_bf16 v[44:47], v[148:151], v[210:213], v[44:47]
	v_mfma_f32_16x16x32_bf16 v[40:43], v[178:181], v[210:213], v[40:43]
	v_mfma_f32_16x16x32_bf16 v[28:31], v[148:151], v[218:221], v[28:31]
	v_mfma_f32_16x16x32_bf16 v[24:27], v[178:181], v[218:221], v[24:27]
	v_mfma_f32_16x16x32_bf16 v[12:15], v[148:151], v[226:229], v[12:15]
	v_mfma_f32_16x16x32_bf16 v[8:11], v[178:181], v[226:229], v[8:11]
	s_setprio 0
	s_setprio 1
	v_mfma_f32_16x16x32_bf16 v[52:55], v[182:185], v[198:201], v[52:55]
	v_mfma_f32_16x16x32_bf16 v[48:51], v[190:193], v[198:201], v[48:51]
	v_mfma_f32_16x16x32_bf16 v[36:39], v[182:185], v[206:209], v[36:39]
	v_mfma_f32_16x16x32_bf16 v[32:35], v[190:193], v[206:209], v[32:35]
	v_mfma_f32_16x16x32_bf16 v[20:23], v[182:185], v[214:217], v[20:23]
	v_mfma_f32_16x16x32_bf16 v[16:19], v[190:193], v[214:217], v[16:19]
	v_mfma_f32_16x16x32_bf16 v[4:7], v[182:185], v[222:225], v[4:7]
	v_mfma_f32_16x16x32_bf16 v[0:3], v[190:193], v[222:225], v[0:3]
	v_mfma_f32_16x16x32_bf16 v[52:55], v[186:189], v[202:205], v[52:55]
	v_mfma_f32_16x16x32_bf16 v[48:51], v[194:197], v[202:205], v[48:51]
	v_mfma_f32_16x16x32_bf16 v[36:39], v[186:189], v[210:213], v[36:39]
	v_mfma_f32_16x16x32_bf16 v[32:35], v[194:197], v[210:213], v[32:35]
	v_mfma_f32_16x16x32_bf16 v[20:23], v[186:189], v[218:221], v[20:23]
	v_mfma_f32_16x16x32_bf16 v[16:19], v[194:197], v[218:221], v[16:19]
	v_mfma_f32_16x16x32_bf16 v[4:7], v[186:189], v[226:229], v[4:7]
	v_mfma_f32_16x16x32_bf16 v[0:3], v[194:197], v[226:229], v[0:3]
	s_barrier
	s_setprio 0
	s_add_u32 s63, s63, 0x100
	s_addc_u32 s64, s64, 0
	s_add_u32 s6, s6, 0x100
	s_addc_u32 s7, s7, 0
	s_cmp_ge_i32 s36, s55
	s_mov_b32 s34, s36
	s_cbranch_scc0 .LBB0_1911
